# all LayerNorm and row-sum cross-lane hops via DPP and permlane swaps, no LDS round trips
# speedup vs baseline: 1.0020x; 1.0020x over previous
; #define LAS __attribute__((address_space(3)))
; __device__ __forceinline__ void conv_phase(LAS unsigned char* lds, const bf16_t* U, bf16_t* C, const float* wdw, const float* bdw, const float* lng, const float* lnb,
;                                            int first, int stride, int end, int tid, int wave, int lane) {
;     ...
;         for (int p = 0; p < 2; ++p) {
; #pragma unroll
;             for (int j = 0; j < 4; ++j)
; #pragma unroll
;                 for (int c = 0; c < 4; ++c) acc[p][j][c] = (f32x2){0.f, 0.f};
;             f32x4 wt[8][2];
;             typedef const __attribute__((address_space(1))) f32x4 gf32x4;
;             const gf32x4* wq = (const gf32x4*)(wdw + p * 512 + lane * 8);
; #pragma unroll
;             for (int t = 0; t < 4; ++t) { wt[t][0] = wq[0]; wt[t][1] = wq[1]; wq += D / 4; asm volatile("" : "+v"(wq)); }
; #pragma unroll
;             for (int r = 0; r < TT / NWAVES + CW - 1; ++r) {
;                 if (r + 4 < CW) { wt[(r + 4) & 7][0] = wq[0]; wt[(r + 4) & 7][1] = wq[1]; wq += D / 4; asm volatile("" : "+v"(wq)); }
;                 const u32x4 xv = *(const LAS u32x4*)(lds + (4 * wave + r) * 2048 + p * 1024 + lane * 16);
;                 f32x2 x[4];
; #pragma unroll
;                 for (int i = 0; i < 4; ++i) x[i] = (f32x2){__uint_as_float(xv[i] << 16), __uint_as_float(xv[i] & 0xffff0000u)};
; #pragma unroll
;                 for (int j = 0; j < 4; ++j) { const int w = r - j;
;                     if (w >= 0 && w < CW) {
; #pragma unroll
;                         for (int c = 0; c < 4; ++c) { const f32x4 wv = wt[w & 7][c >> 1]; const f32x2 w2 = (c & 1) ? (f32x2){wv.z, wv.w} : (f32x2){wv.x, wv.y}; acc[p][j][c] = __builtin_elementwise_fma(w2, x[c], acc[p][j][c]); } } }
.LBB0_89:
	s_or_b64 exec, exec, s[4:5]
	s_waitcnt lgkmcnt(0)
	s_barrier
	global_load_dwordx4 v[56:59], v[84:85], off offset:16
	global_load_dwordx4 v[60:63], v[84:85], off
	v_mov_b64_e32 v[0:1], v[96:97]
	global_load_dwordx4 v[48:51], v[0:1], off offset:16
	global_load_dwordx4 v[52:55], v[0:1], off
	v_lshl_add_u64 v[0:1], v[0:1], 0, s[0:1]
	global_load_dwordx4 v[40:43], v[0:1], off offset:16
	global_load_dwordx4 v[44:47], v[0:1], off
	v_lshl_add_u64 v[0:1], v[0:1], 0, s[0:1]
	global_load_dwordx4 v[24:27], v[0:1], off offset:16
	global_load_dwordx4 v[28:31], v[0:1], off
	v_lshl_add_u64 v[8:9], v[0:1], 0, s[0:1]
	global_load_dwordx4 v[0:3], v[8:9], off offset:16
	global_load_dwordx4 v[4:7], v[8:9], off
	v_lshl_add_u64 v[16:17], v[8:9], 0, s[0:1]
	ds_read_b128 v[8:11], v134
	v_lshl_add_u64 v[36:37], v[16:17], 0, s[0:1]
	v_cmp_lt_i32_e64 s[40:41], v226, v225
	s_mov_b32 s4, 0x3727c5ac
	s_waitcnt lgkmcnt(0)
	v_lshlrev_b32_e32 v12, 16, v11
	v_and_b32_e32 v13, 0xffff0000, v11
	v_lshlrev_b32_e32 v14, 16, v10
	v_and_b32_e32 v15, 0xffff0000, v10
	v_lshlrev_b32_e32 v10, 16, v9
	v_and_b32_e32 v11, 0xffff0000, v9
	v_lshlrev_b32_e32 v18, 16, v8
	v_and_b32_e32 v19, 0xffff0000, v8
	v_add_u32_e32 v140, v140, v133
	s_waitcnt vmcnt(9)
	v_pk_fma_f32 v[32:33], v[56:57], v[14:15], 0 op_sel_hi:[1,1,0]
	s_waitcnt vmcnt(8)
	v_pk_fma_f32 v[20:21], v[60:61], v[18:19], 0 op_sel_hi:[1,1,0]
	v_pk_fma_f32 v[22:23], v[62:63], v[10:11], 0 op_sel_hi:[1,1,0]
	v_pk_fma_f32 v[34:35], v[58:59], v[12:13], 0 op_sel_hi:[1,1,0]
	global_load_dwordx4 v[8:11], v[16:17], off offset:16
	global_load_dwordx4 v[12:15], v[16:17], off
	ds_read_b128 v[16:19], v134 offset:2048
	v_lshl_add_u64 v[104:105], v[36:37], 0, s[0:1]
	s_waitcnt lgkmcnt(0)
	v_lshlrev_b32_e32 v38, 16, v16
	v_and_b32_e32 v39, 0xffff0000, v16
	v_lshlrev_b32_e32 v16, 16, v17
	v_and_b32_e32 v17, 0xffff0000, v17
	v_lshlrev_b32_e32 v64, 16, v18
	v_and_b32_e32 v65, 0xffff0000, v18
	v_lshlrev_b32_e32 v18, 16, v19
	v_and_b32_e32 v19, 0xffff0000, v19
	s_waitcnt vmcnt(8)
	v_pk_fma_f32 v[66:67], v[52:53], v[38:39], v[20:21]
	v_pk_fma_f32 v[68:69], v[54:55], v[16:17], v[22:23]
	v_pk_fma_f32 v[72:73], v[50:51], v[18:19], v[34:35]
	v_pk_fma_f32 v[74:75], v[62:63], v[16:17], 0 op_sel_hi:[1,1,0]
	v_pk_fma_f32 v[78:79], v[58:59], v[18:19], 0 op_sel_hi:[1,1,0]
	global_load_dwordx4 v[16:19], v[36:37], off offset:16
	global_load_dwordx4 v[20:23], v[36:37], off
	v_pk_fma_f32 v[70:71], v[48:49], v[64:65], v[32:33]
	ds_read_b128 v[32:35], v134 offset:4096
	v_pk_fma_f32 v[38:39], v[60:61], v[38:39], 0 op_sel_hi:[1,1,0]
	v_pk_fma_f32 v[76:77], v[56:57], v[64:65], 0 op_sel_hi:[1,1,0]
	v_lshl_add_u64 v[108:109], v[104:105], 0, s[0:1]
	s_waitcnt lgkmcnt(0)
	v_lshlrev_b32_e32 v36, 16, v32
	v_and_b32_e32 v37, 0xffff0000, v32
	v_lshlrev_b32_e32 v32, 16, v33
	v_and_b32_e32 v33, 0xffff0000, v33
	v_lshlrev_b32_e32 v80, 16, v34
	v_and_b32_e32 v81, 0xffff0000, v34
	v_lshlrev_b32_e32 v34, 16, v35
	v_and_b32_e32 v35, 0xffff0000, v35
	s_waitcnt vmcnt(8)
	v_pk_fma_f32 v[102:103], v[44:45], v[36:37], v[66:67]
	v_pk_fma_f32 v[100:101], v[46:47], v[32:33], v[68:69]
	v_pk_fma_f32 v[82:83], v[40:41], v[80:81], v[70:71]
	v_pk_fma_f32 v[64:65], v[42:43], v[34:35], v[72:73]
	v_pk_fma_f32 v[66:67], v[52:53], v[36:37], v[38:39]
	v_pk_fma_f32 v[68:69], v[54:55], v[32:33], v[74:75]
	v_pk_fma_f32 v[70:71], v[48:49], v[80:81], v[76:77]
	v_pk_fma_f32 v[72:73], v[50:51], v[34:35], v[78:79]
	v_pk_fma_f32 v[74:75], v[60:61], v[36:37], 0 op_sel_hi:[1,1,0]
	v_pk_fma_f32 v[76:77], v[62:63], v[32:33], 0 op_sel_hi:[1,1,0]
	v_pk_fma_f32 v[78:79], v[56:57], v[80:81], 0 op_sel_hi:[1,1,0]
	v_pk_fma_f32 v[80:81], v[58:59], v[34:35], 0 op_sel_hi:[1,1,0]
	global_load_dwordx4 v[32:35], v[104:105], off offset:16
	global_load_dwordx4 v[36:39], v[104:105], off
	ds_read_b128 v[104:107], v134 offset:6144
	s_waitcnt lgkmcnt(0)
	v_lshlrev_b32_e32 v110, 16, v104
	v_and_b32_e32 v111, 0xffff0000, v104
	v_lshlrev_b32_e32 v104, 16, v105
	v_and_b32_e32 v105, 0xffff0000, v105
	v_lshlrev_b32_e32 v112, 16, v106
	v_and_b32_e32 v113, 0xffff0000, v106
	v_lshlrev_b32_e32 v106, 16, v107
	v_and_b32_e32 v107, 0xffff0000, v107
	s_waitcnt vmcnt(8)
	v_pk_fma_f32 v[102:103], v[28:29], v[110:111], v[102:103]
	v_pk_fma_f32 v[100:101], v[30:31], v[104:105], v[100:101]
	v_pk_fma_f32 v[82:83], v[24:25], v[112:113], v[82:83]
	v_pk_fma_f32 v[114:115], v[26:27], v[106:107], v[64:65]
	v_pk_fma_f32 v[116:117], v[44:45], v[110:111], v[66:67]
	v_pk_fma_f32 v[68:69], v[46:47], v[104:105], v[68:69]
	v_pk_fma_f32 v[70:71], v[40:41], v[112:113], v[70:71]
	v_pk_fma_f32 v[72:73], v[42:43], v[106:107], v[72:73]
	v_pk_fma_f32 v[74:75], v[52:53], v[110:111], v[74:75]
	v_pk_fma_f32 v[76:77], v[54:55], v[104:105], v[76:77]
	v_pk_fma_f32 v[78:79], v[48:49], v[112:113], v[78:79]
	v_pk_fma_f32 v[80:81], v[50:51], v[106:107], v[80:81]
	v_pk_fma_f32 v[110:111], v[60:61], v[110:111], 0 op_sel_hi:[1,1,0]
	v_pk_fma_f32 v[104:105], v[62:63], v[104:105], 0 op_sel_hi:[1,1,0]
	v_pk_fma_f32 v[112:113], v[56:57], v[112:113], 0 op_sel_hi:[1,1,0]
	v_pk_fma_f32 v[106:107], v[58:59], v[106:107], 0 op_sel_hi:[1,1,0]
	global_load_dwordx4 v[56:59], v[108:109], off offset:16
	global_load_dwordx4 v[60:63], v[108:109], off
	v_lshl_add_u64 v[108:109], v[108:109], 0, s[0:1]
	ds_read_b128 v[64:67], v134 offset:8192
	s_waitcnt lgkmcnt(0)
; #define LAS __attribute__((address_space(3)))
; __device__ __forceinline__ void conv_phase(LAS unsigned char* lds, const bf16_t* U, bf16_t* C, const float* wdw, const float* bdw, const float* lng, const float* lnb,
;                                            int first, int stride, int end, int tid, int wave, int lane) {
;     ...
;             for (int r = 0; r < TT / NWAVES + CW - 1; ++r) {
;                 if (r + 4 < CW) { wt[(r + 4) & 7][0] = wq[0]; wt[(r + 4) & 7][1] = wq[1]; wq += D / 4; asm volatile("" : "+v"(wq)); }
;                 const u32x4 xv = *(const LAS u32x4*)(lds + (4 * wave + r) * 2048 + p * 1024 + lane * 16);
;                 f32x2 x[4];
; #pragma unroll
;                 for (int i = 0; i < 4; ++i) x[i] = (f32x2){__uint_as_float(xv[i] << 16), __uint_as_float(xv[i] & 0xffff0000u)};
; #pragma unroll
;                 for (int j = 0; j < 4; ++j) { const int w = r - j;
;                     if (w >= 0 && w < CW) {
; #pragma unroll
;                         for (int c = 0; c < 4; ++c) { const f32x4 wv = wt[w & 7][c >> 1]; const f32x2 w2 = (c & 1) ? (f32x2){wv.z, wv.w} : (f32x2){wv.x, wv.y}; acc[p][j][c] = __builtin_elementwise_fma(w2, x[c], acc[p][j][c]); } } }
;                 asm volatile("" ::: "memory");
	v_lshlrev_b32_e32 v118, 16, v64
	v_and_b32_e32 v119, 0xffff0000, v64
	v_lshlrev_b32_e32 v64, 16, v65
	v_and_b32_e32 v65, 0xffff0000, v65
	v_lshlrev_b32_e32 v120, 16, v66
	v_and_b32_e32 v121, 0xffff0000, v66
	v_lshlrev_b32_e32 v66, 16, v67
	v_and_b32_e32 v67, 0xffff0000, v67
	v_pk_fma_f32 v[110:111], v[52:53], v[118:119], v[110:111]
	v_pk_fma_f32 v[104:105], v[54:55], v[64:65], v[104:105]
	v_pk_fma_f32 v[112:113], v[48:49], v[120:121], v[112:113]
	v_pk_fma_f32 v[106:107], v[50:51], v[66:67], v[106:107]
	global_load_dwordx4 v[48:51], v[108:109], off offset:16
	global_load_dwordx4 v[52:55], v[108:109], off
	v_lshl_add_u64 v[108:109], v[108:109], 0, s[0:1]
	s_waitcnt vmcnt(10)
	v_pk_fma_f32 v[100:101], v[6:7], v[64:65], v[100:101]
	v_pk_fma_f32 v[114:115], v[2:3], v[66:67], v[114:115]
	v_pk_fma_f32 v[68:69], v[30:31], v[64:65], v[68:69]
	v_pk_fma_f32 v[72:73], v[26:27], v[66:67], v[72:73]
	v_pk_fma_f32 v[76:77], v[46:47], v[64:65], v[76:77]
	v_pk_fma_f32 v[80:81], v[42:43], v[66:67], v[80:81]
	ds_read_b128 v[64:67], v134 offset:10240
	v_pk_fma_f32 v[102:103], v[4:5], v[118:119], v[102:103]
	v_pk_fma_f32 v[82:83], v[0:1], v[120:121], v[82:83]
	v_pk_fma_f32 v[116:117], v[28:29], v[118:119], v[116:117]
	v_pk_fma_f32 v[70:71], v[24:25], v[120:121], v[70:71]
	v_pk_fma_f32 v[74:75], v[44:45], v[118:119], v[74:75]
	v_pk_fma_f32 v[78:79], v[40:41], v[120:121], v[78:79]
	s_waitcnt lgkmcnt(0)
	v_lshlrev_b32_e32 v118, 16, v64
	v_and_b32_e32 v119, 0xffff0000, v64
	v_lshlrev_b32_e32 v64, 16, v65
	v_and_b32_e32 v65, 0xffff0000, v65
	v_lshlrev_b32_e32 v120, 16, v66
	v_and_b32_e32 v121, 0xffff0000, v66
	v_lshlrev_b32_e32 v66, 16, v67
	v_and_b32_e32 v67, 0xffff0000, v67
	v_pk_fma_f32 v[110:111], v[44:45], v[118:119], v[110:111]
	v_pk_fma_f32 v[104:105], v[46:47], v[64:65], v[104:105]
	v_pk_fma_f32 v[112:113], v[40:41], v[120:121], v[112:113]
	v_pk_fma_f32 v[106:107], v[42:43], v[66:67], v[106:107]
	global_load_dwordx4 v[40:43], v[108:109], off offset:16
	global_load_dwordx4 v[44:47], v[108:109], off
	v_lshl_add_u64 v[108:109], v[108:109], 0, s[0:1]
	s_waitcnt vmcnt(10)
	v_pk_fma_f32 v[100:101], v[14:15], v[64:65], v[100:101]
	v_pk_fma_f32 v[114:115], v[10:11], v[66:67], v[114:115]
	v_pk_fma_f32 v[68:69], v[6:7], v[64:65], v[68:69]
	v_pk_fma_f32 v[72:73], v[2:3], v[66:67], v[72:73]
	v_pk_fma_f32 v[76:77], v[30:31], v[64:65], v[76:77]
	v_pk_fma_f32 v[80:81], v[26:27], v[66:67], v[80:81]
	ds_read_b128 v[64:67], v134 offset:12288
	v_pk_fma_f32 v[102:103], v[12:13], v[118:119], v[102:103]
	v_pk_fma_f32 v[82:83], v[8:9], v[120:121], v[82:83]
	v_pk_fma_f32 v[116:117], v[4:5], v[118:119], v[116:117]
	v_pk_fma_f32 v[70:71], v[0:1], v[120:121], v[70:71]
	v_pk_fma_f32 v[74:75], v[28:29], v[118:119], v[74:75]
	v_pk_fma_f32 v[78:79], v[24:25], v[120:121], v[78:79]
	s_waitcnt lgkmcnt(0)
	v_lshlrev_b32_e32 v118, 16, v64
	v_and_b32_e32 v119, 0xffff0000, v64
	v_lshlrev_b32_e32 v64, 16, v65
	v_and_b32_e32 v65, 0xffff0000, v65
	v_lshlrev_b32_e32 v120, 16, v66
	v_and_b32_e32 v121, 0xffff0000, v66
	v_lshlrev_b32_e32 v66, 16, v67
	v_and_b32_e32 v67, 0xffff0000, v67
	s_waitcnt vmcnt(8)
	v_pk_fma_f32 v[100:101], v[22:23], v[64:65], v[100:101]
	v_pk_fma_f32 v[114:115], v[18:19], v[66:67], v[114:115]
	v_pk_fma_f32 v[68:69], v[14:15], v[64:65], v[68:69]
	v_pk_fma_f32 v[72:73], v[10:11], v[66:67], v[72:73]
	v_pk_fma_f32 v[76:77], v[6:7], v[64:65], v[76:77]
	v_pk_fma_f32 v[80:81], v[2:3], v[66:67], v[80:81]
	v_pk_fma_f32 v[104:105], v[30:31], v[64:65], v[104:105]
	v_pk_fma_f32 v[112:113], v[24:25], v[120:121], v[112:113]
	v_pk_fma_f32 v[106:107], v[26:27], v[66:67], v[106:107]
	global_load_dwordx4 v[24:27], v[108:109], off offset:16
	global_load_dwordx4 v[64:67], v[108:109], off
	v_lshl_add_u64 v[108:109], v[108:109], 0, s[0:1]
	v_pk_fma_f32 v[110:111], v[28:29], v[118:119], v[110:111]
	ds_read_b128 v[28:31], v134 offset:14336
	v_pk_fma_f32 v[102:103], v[20:21], v[118:119], v[102:103]
	v_pk_fma_f32 v[82:83], v[16:17], v[120:121], v[82:83]
	v_pk_fma_f32 v[116:117], v[12:13], v[118:119], v[116:117]
	v_pk_fma_f32 v[70:71], v[8:9], v[120:121], v[70:71]
	v_pk_fma_f32 v[74:75], v[4:5], v[118:119], v[74:75]
	v_pk_fma_f32 v[78:79], v[0:1], v[120:121], v[78:79]
	s_waitcnt lgkmcnt(0)
	v_lshlrev_b32_e32 v118, 16, v28
	v_and_b32_e32 v119, 0xffff0000, v28
	v_lshlrev_b32_e32 v28, 16, v29
	v_and_b32_e32 v29, 0xffff0000, v29
	v_lshlrev_b32_e32 v120, 16, v30
	v_and_b32_e32 v121, 0xffff0000, v30
	v_lshlrev_b32_e32 v30, 16, v31
	v_and_b32_e32 v31, 0xffff0000, v31
	s_waitcnt vmcnt(8)
	v_pk_fma_f32 v[100:101], v[38:39], v[28:29], v[100:101]
	v_pk_fma_f32 v[114:115], v[34:35], v[30:31], v[114:115]
	v_pk_fma_f32 v[122:123], v[22:23], v[28:29], v[68:69]
	v_pk_fma_f32 v[124:125], v[16:17], v[120:121], v[70:71]
	v_pk_fma_f32 v[72:73], v[18:19], v[30:31], v[72:73]
	v_pk_fma_f32 v[76:77], v[14:15], v[28:29], v[76:77]
	v_pk_fma_f32 v[80:81], v[10:11], v[30:31], v[80:81]
	v_pk_fma_f32 v[28:29], v[6:7], v[28:29], v[104:105]
	v_pk_fma_f32 v[104:105], v[0:1], v[120:121], v[112:113]
	v_pk_fma_f32 v[30:31], v[2:3], v[30:31], v[106:107]
	global_load_dwordx4 v[0:3], v[108:109], off offset:16
	global_load_dwordx4 v[68:71], v[108:109], off
	v_lshl_add_u64 v[106:107], v[108:109], 0, s[0:1]
	v_pk_fma_f32 v[110:111], v[4:5], v[118:119], v[110:111]
	ds_read_b128 v[4:7], v134 offset:16384
	v_pk_fma_f32 v[74:75], v[12:13], v[118:119], v[74:75]
	v_pk_fma_f32 v[102:103], v[36:37], v[118:119], v[102:103]
	v_pk_fma_f32 v[82:83], v[32:33], v[120:121], v[82:83]
	s_waitcnt lgkmcnt(0)
; #define LAS __attribute__((address_space(3)))
; __device__ __forceinline__ void conv_phase(LAS unsigned char* lds, const bf16_t* U, bf16_t* C, const float* wdw, const float* bdw, const float* lng, const float* lnb,
;                                            int first, int stride, int end, int tid, int wave, int lane) {
;     ...
;             for (int r = 0; r < TT / NWAVES + CW - 1; ++r) {
;                 if (r + 4 < CW) { wt[(r + 4) & 7][0] = wq[0]; wt[(r + 4) & 7][1] = wq[1]; wq += D / 4; asm volatile("" : "+v"(wq)); }
;                 const u32x4 xv = *(const LAS u32x4*)(lds + (4 * wave + r) * 2048 + p * 1024 + lane * 16);
;                 f32x2 x[4];
; #pragma unroll
;                 for (int i = 0; i < 4; ++i) x[i] = (f32x2){__uint_as_float(xv[i] << 16), __uint_as_float(xv[i] & 0xffff0000u)};
; #pragma unroll
;                 for (int j = 0; j < 4; ++j) { const int w = r - j;
;                     if (w >= 0 && w < CW) {
; #pragma unroll
;                         for (int c = 0; c < 4; ++c) { const f32x4 wv = wt[w & 7][c >> 1]; const f32x2 w2 = (c & 1) ? (f32x2){wv.z, wv.w} : (f32x2){wv.x, wv.y}; acc[p][j][c] = __builtin_elementwise_fma(w2, x[c], acc[p][j][c]); } } }
;                 asm volatile("" ::: "memory");
	v_lshlrev_b32_e32 v108, 16, v4
	v_and_b32_e32 v109, 0xffff0000, v4
	v_lshlrev_b32_e32 v4, 16, v5
	v_and_b32_e32 v5, 0xffff0000, v5
	v_lshlrev_b32_e32 v112, 16, v6
	v_and_b32_e32 v113, 0xffff0000, v6
	v_lshlrev_b32_e32 v6, 16, v7
	v_and_b32_e32 v7, 0xffff0000, v7
	v_pk_fma_f32 v[116:117], v[20:21], v[118:119], v[116:117]
	v_pk_fma_f32 v[78:79], v[8:9], v[120:121], v[78:79]
	s_waitcnt vmcnt(8)
	v_pk_fma_f32 v[100:101], v[62:63], v[4:5], v[100:101]
	v_pk_fma_f32 v[114:115], v[58:59], v[6:7], v[114:115]
	v_pk_fma_f32 v[118:119], v[38:39], v[4:5], v[122:123]
	v_pk_fma_f32 v[120:121], v[32:33], v[112:113], v[124:125]
	v_pk_fma_f32 v[122:123], v[34:35], v[6:7], v[72:73]
	v_pk_fma_f32 v[124:125], v[20:21], v[108:109], v[74:75]
	v_pk_fma_f32 v[76:77], v[22:23], v[4:5], v[76:77]
	v_pk_fma_f32 v[80:81], v[18:19], v[6:7], v[80:81]
	v_pk_fma_f32 v[14:15], v[14:15], v[4:5], v[28:29]
	v_pk_fma_f32 v[30:31], v[10:11], v[6:7], v[30:31]
	global_load_dwordx4 v[4:7], v[106:107], off offset:16
	global_load_dwordx4 v[72:75], v[106:107], off
	v_pk_fma_f32 v[28:29], v[8:9], v[112:113], v[104:105]
	v_lshl_add_u64 v[104:105], v[106:107], 0, s[0:1]
	ds_read_b128 v[8:11], v134 offset:18432
	v_pk_fma_f32 v[102:103], v[60:61], v[108:109], v[102:103]
	v_pk_fma_f32 v[116:117], v[36:37], v[108:109], v[116:117]
	v_pk_fma_f32 v[78:79], v[16:17], v[112:113], v[78:79]
	v_pk_fma_f32 v[12:13], v[12:13], v[108:109], v[110:111]
	s_waitcnt lgkmcnt(0)
	v_lshlrev_b32_e32 v106, 16, v8
	v_and_b32_e32 v107, 0xffff0000, v8
	v_lshlrev_b32_e32 v8, 16, v9
	v_and_b32_e32 v9, 0xffff0000, v9
	v_lshlrev_b32_e32 v108, 16, v10
	v_and_b32_e32 v109, 0xffff0000, v10
	v_lshlrev_b32_e32 v10, 16, v11
	v_and_b32_e32 v11, 0xffff0000, v11
	v_pk_fma_f32 v[82:83], v[56:57], v[112:113], v[82:83]
	s_waitcnt vmcnt(8)
	v_pk_fma_f32 v[100:101], v[54:55], v[8:9], v[100:101]
	v_pk_fma_f32 v[110:111], v[50:51], v[10:11], v[114:115]
	v_pk_fma_f32 v[112:113], v[60:61], v[106:107], v[116:117]
	v_pk_fma_f32 v[114:115], v[62:63], v[8:9], v[118:119]
	v_pk_fma_f32 v[116:117], v[56:57], v[108:109], v[120:121]
	v_pk_fma_f32 v[118:119], v[58:59], v[10:11], v[122:123]
	v_pk_fma_f32 v[120:121], v[36:37], v[106:107], v[124:125]
	v_pk_fma_f32 v[122:123], v[38:39], v[8:9], v[76:77]
	v_pk_fma_f32 v[124:125], v[32:33], v[108:109], v[78:79]
	v_pk_fma_f32 v[80:81], v[34:35], v[10:11], v[80:81]
	v_pk_fma_f32 v[22:23], v[22:23], v[8:9], v[14:15]
	v_pk_fma_f32 v[16:17], v[16:17], v[108:109], v[28:29]
	v_pk_fma_f32 v[18:19], v[18:19], v[10:11], v[30:31]
	global_load_dwordx4 v[8:11], v[104:105], off offset:16
	global_load_dwordx4 v[76:79], v[104:105], off
	v_lshl_add_u64 v[28:29], v[104:105], 0, s[0:1]
	v_pk_fma_f32 v[20:21], v[20:21], v[106:107], v[12:13]
	ds_read_b128 v[12:15], v134 offset:20480
	v_pk_fma_f32 v[102:103], v[52:53], v[106:107], v[102:103]
	v_pk_fma_f32 v[82:83], v[48:49], v[108:109], v[82:83]
	s_waitcnt lgkmcnt(0)
	v_lshlrev_b32_e32 v30, 16, v12
	v_and_b32_e32 v31, 0xffff0000, v12
	v_lshlrev_b32_e32 v12, 16, v13
	v_and_b32_e32 v13, 0xffff0000, v13
	v_lshlrev_b32_e32 v104, 16, v14
	v_and_b32_e32 v105, 0xffff0000, v14
	v_lshlrev_b32_e32 v14, 16, v15
	v_and_b32_e32 v15, 0xffff0000, v15
	s_waitcnt vmcnt(8)
	v_pk_fma_f32 v[102:103], v[44:45], v[30:31], v[102:103]
	v_pk_fma_f32 v[100:101], v[46:47], v[12:13], v[100:101]
	v_pk_fma_f32 v[106:107], v[42:43], v[14:15], v[110:111]
	v_pk_fma_f32 v[108:109], v[52:53], v[30:31], v[112:113]
	v_pk_fma_f32 v[110:111], v[54:55], v[12:13], v[114:115]
	v_pk_fma_f32 v[112:113], v[48:49], v[104:105], v[116:117]
	v_pk_fma_f32 v[114:115], v[50:51], v[14:15], v[118:119]
	v_pk_fma_f32 v[116:117], v[60:61], v[30:31], v[120:121]
	v_pk_fma_f32 v[118:119], v[62:63], v[12:13], v[122:123]
	v_pk_fma_f32 v[80:81], v[58:59], v[14:15], v[80:81]
	v_pk_fma_f32 v[20:21], v[36:37], v[30:31], v[20:21]
	v_pk_fma_f32 v[22:23], v[38:39], v[12:13], v[22:23]
	v_pk_fma_f32 v[30:31], v[32:33], v[104:105], v[16:17]
	v_pk_fma_f32 v[32:33], v[34:35], v[14:15], v[18:19]
	global_load_dwordx4 v[12:15], v[28:29], off offset:16
	global_load_dwordx4 v[36:39], v[28:29], off
	v_lshl_add_u64 v[28:29], v[28:29], 0, s[0:1]
	ds_read_b128 v[16:19], v134 offset:22528
	v_pk_fma_f32 v[82:83], v[40:41], v[104:105], v[82:83]
	v_pk_fma_f32 v[120:121], v[56:57], v[104:105], v[124:125]
	s_waitcnt lgkmcnt(0)
	v_lshlrev_b32_e32 v34, 16, v16
	v_and_b32_e32 v35, 0xffff0000, v16
	v_lshlrev_b32_e32 v16, 16, v17
	v_and_b32_e32 v17, 0xffff0000, v17
	v_lshlrev_b32_e32 v104, 16, v18
	v_and_b32_e32 v105, 0xffff0000, v18
	v_lshlrev_b32_e32 v18, 16, v19
	v_and_b32_e32 v19, 0xffff0000, v19
	s_waitcnt vmcnt(8)
	v_pk_fma_f32 v[102:103], v[64:65], v[34:35], v[102:103]
	v_pk_fma_f32 v[100:101], v[66:67], v[16:17], v[100:101]
	v_pk_fma_f32 v[106:107], v[26:27], v[18:19], v[106:107]
	v_pk_fma_f32 v[108:109], v[44:45], v[34:35], v[108:109]
	v_pk_fma_f32 v[110:111], v[46:47], v[16:17], v[110:111]
	v_pk_fma_f32 v[114:115], v[42:43], v[18:19], v[114:115]
	v_pk_fma_f32 v[116:117], v[52:53], v[34:35], v[116:117]
	v_pk_fma_f32 v[118:119], v[54:55], v[16:17], v[118:119]
	v_pk_fma_f32 v[80:81], v[50:51], v[18:19], v[80:81]
	v_pk_fma_f32 v[34:35], v[60:61], v[34:35], v[20:21]
	v_pk_fma_f32 v[60:61], v[62:63], v[16:17], v[22:23]
	v_pk_fma_f32 v[30:31], v[56:57], v[104:105], v[30:31]
	v_pk_fma_f32 v[32:33], v[58:59], v[18:19], v[32:33]
	global_load_dwordx4 v[16:19], v[28:29], off offset:16
	global_load_dwordx4 v[56:59], v[28:29], off
	v_lshl_add_u64 v[28:29], v[28:29], 0, s[0:1]
	ds_read_b128 v[20:23], v134 offset:24576
	v_pk_fma_f32 v[82:83], v[24:25], v[104:105], v[82:83]
	v_pk_fma_f32 v[112:113], v[40:41], v[104:105], v[112:113]
	v_pk_fma_f32 v[120:121], v[48:49], v[104:105], v[120:121]
	s_waitcnt lgkmcnt(0)
; #define LAS __attribute__((address_space(3)))
; __device__ __forceinline__ void conv_phase(LAS unsigned char* lds, const bf16_t* U, bf16_t* C, const float* wdw, const float* bdw, const float* lng, const float* lnb,
;                                            int first, int stride, int end, int tid, int wave, int lane) {
;     ...
;             for (int r = 0; r < TT / NWAVES + CW - 1; ++r) {
;                 if (r + 4 < CW) { wt[(r + 4) & 7][0] = wq[0]; wt[(r + 4) & 7][1] = wq[1]; wq += D / 4; asm volatile("" : "+v"(wq)); }
;                 const u32x4 xv = *(const LAS u32x4*)(lds + (4 * wave + r) * 2048 + p * 1024 + lane * 16);
;                 f32x2 x[4];
; #pragma unroll
;                 for (int i = 0; i < 4; ++i) x[i] = (f32x2){__uint_as_float(xv[i] << 16), __uint_as_float(xv[i] & 0xffff0000u)};
; #pragma unroll
;                 for (int j = 0; j < 4; ++j) { const int w = r - j;
;                     if (w >= 0 && w < CW) {
; #pragma unroll
;                         for (int c = 0; c < 4; ++c) { const f32x4 wv = wt[w & 7][c >> 1]; const f32x2 w2 = (c & 1) ? (f32x2){wv.z, wv.w} : (f32x2){wv.x, wv.y}; acc[p][j][c] = __builtin_elementwise_fma(w2, x[c], acc[p][j][c]); } } }
;                 asm volatile("" ::: "memory");
	v_lshlrev_b32_e32 v62, 16, v20
	v_and_b32_e32 v63, 0xffff0000, v20
	v_lshlrev_b32_e32 v20, 16, v21
	v_and_b32_e32 v21, 0xffff0000, v21
	v_lshlrev_b32_e32 v104, 16, v22
	v_and_b32_e32 v105, 0xffff0000, v22
	v_lshlrev_b32_e32 v22, 16, v23
	v_and_b32_e32 v23, 0xffff0000, v23
	s_waitcnt vmcnt(8)
	v_pk_fma_f32 v[100:101], v[70:71], v[20:21], v[100:101]
	v_pk_fma_f32 v[106:107], v[2:3], v[22:23], v[106:107]
	v_pk_fma_f32 v[110:111], v[66:67], v[20:21], v[110:111]
	v_pk_fma_f32 v[114:115], v[26:27], v[22:23], v[114:115]
	v_pk_fma_f32 v[118:119], v[46:47], v[20:21], v[118:119]
	v_pk_fma_f32 v[80:81], v[42:43], v[22:23], v[80:81]
	v_pk_fma_f32 v[34:35], v[52:53], v[62:63], v[34:35]
	v_pk_fma_f32 v[52:53], v[54:55], v[20:21], v[60:61]
	v_pk_fma_f32 v[54:55], v[48:49], v[104:105], v[30:31]
	v_pk_fma_f32 v[32:33], v[50:51], v[22:23], v[32:33]
	global_load_dwordx4 v[20:23], v[28:29], off offset:16
	global_load_dwordx4 v[48:51], v[28:29], off
	v_lshl_add_u64 v[60:61], v[28:29], 0, s[0:1]
	ds_read_b128 v[28:31], v134 offset:26624
	v_pk_fma_f32 v[102:103], v[68:69], v[62:63], v[102:103]
	v_pk_fma_f32 v[82:83], v[0:1], v[104:105], v[82:83]
	v_pk_fma_f32 v[108:109], v[64:65], v[62:63], v[108:109]
	v_pk_fma_f32 v[112:113], v[24:25], v[104:105], v[112:113]
	v_pk_fma_f32 v[116:117], v[44:45], v[62:63], v[116:117]
	v_pk_fma_f32 v[120:121], v[40:41], v[104:105], v[120:121]
	s_waitcnt lgkmcnt(0)
	v_lshlrev_b32_e32 v62, 16, v28
	v_and_b32_e32 v63, 0xffff0000, v28
	v_lshlrev_b32_e32 v28, 16, v29
	v_and_b32_e32 v29, 0xffff0000, v29
	v_lshlrev_b32_e32 v104, 16, v30
	v_and_b32_e32 v105, 0xffff0000, v30
	v_lshlrev_b32_e32 v30, 16, v31
	v_and_b32_e32 v31, 0xffff0000, v31
	s_waitcnt vmcnt(8)
	v_pk_fma_f32 v[100:101], v[74:75], v[28:29], v[100:101]
	v_pk_fma_f32 v[106:107], v[6:7], v[30:31], v[106:107]
	v_pk_fma_f32 v[110:111], v[70:71], v[28:29], v[110:111]
	v_pk_fma_f32 v[114:115], v[2:3], v[30:31], v[114:115]
	v_pk_fma_f32 v[118:119], v[66:67], v[28:29], v[118:119]
	v_pk_fma_f32 v[80:81], v[26:27], v[30:31], v[80:81]
	v_pk_fma_f32 v[46:47], v[46:47], v[28:29], v[52:53]
	v_pk_fma_f32 v[52:53], v[40:41], v[104:105], v[54:55]
	v_pk_fma_f32 v[54:55], v[42:43], v[30:31], v[32:33]
	global_load_dwordx4 v[28:31], v[60:61], off offset:16
	global_load_dwordx4 v[40:43], v[60:61], off
	v_lshl_add_u64 v[60:61], v[60:61], 0, s[0:1]
	v_pk_fma_f32 v[44:45], v[44:45], v[62:63], v[34:35]
	ds_read_b128 v[32:35], v134 offset:28672
	v_pk_fma_f32 v[102:103], v[72:73], v[62:63], v[102:103]
	v_pk_fma_f32 v[82:83], v[4:5], v[104:105], v[82:83]
	v_pk_fma_f32 v[108:109], v[68:69], v[62:63], v[108:109]
	v_pk_fma_f32 v[112:113], v[0:1], v[104:105], v[112:113]
	v_pk_fma_f32 v[116:117], v[64:65], v[62:63], v[116:117]
	v_pk_fma_f32 v[120:121], v[24:25], v[104:105], v[120:121]
	s_waitcnt lgkmcnt(0)
	v_lshlrev_b32_e32 v62, 16, v32
	v_and_b32_e32 v63, 0xffff0000, v32
	v_lshlrev_b32_e32 v32, 16, v33
	v_and_b32_e32 v33, 0xffff0000, v33
	v_lshlrev_b32_e32 v104, 16, v34
	v_and_b32_e32 v105, 0xffff0000, v34
	v_lshlrev_b32_e32 v34, 16, v35
	v_and_b32_e32 v35, 0xffff0000, v35
	s_waitcnt vmcnt(8)
	v_pk_fma_f32 v[102:103], v[76:77], v[62:63], v[102:103]
	v_pk_fma_f32 v[108:109], v[72:73], v[62:63], v[108:109]
	v_pk_fma_f32 v[116:117], v[68:69], v[62:63], v[116:117]
	v_pk_fma_f32 v[62:63], v[64:65], v[62:63], v[44:45]
	v_pk_fma_f32 v[64:65], v[66:67], v[32:33], v[46:47]
	v_pk_fma_f32 v[52:53], v[24:25], v[104:105], v[52:53]
	v_pk_fma_f32 v[54:55], v[26:27], v[34:35], v[54:55]
	global_load_dwordx4 v[24:27], v[60:61], off offset:16
	global_load_dwordx4 v[44:47], v[60:61], off
	v_lshl_add_u64 v[60:61], v[60:61], 0, s[0:1]
	v_pk_fma_f32 v[100:101], v[78:79], v[32:33], v[100:101]
	v_pk_fma_f32 v[106:107], v[10:11], v[34:35], v[106:107]
	v_pk_fma_f32 v[110:111], v[74:75], v[32:33], v[110:111]
	v_pk_fma_f32 v[114:115], v[6:7], v[34:35], v[114:115]
	v_pk_fma_f32 v[118:119], v[70:71], v[32:33], v[118:119]
	v_pk_fma_f32 v[80:81], v[2:3], v[34:35], v[80:81]
	ds_read_b128 v[32:35], v134 offset:30720
	v_pk_fma_f32 v[82:83], v[8:9], v[104:105], v[82:83]
	v_pk_fma_f32 v[112:113], v[4:5], v[104:105], v[112:113]
	v_pk_fma_f32 v[120:121], v[0:1], v[104:105], v[120:121]
	s_waitcnt lgkmcnt(0)
	v_lshlrev_b32_e32 v66, 16, v32
	v_and_b32_e32 v67, 0xffff0000, v32
	v_lshlrev_b32_e32 v104, 16, v34
	v_and_b32_e32 v105, 0xffff0000, v34
	v_lshlrev_b32_e32 v34, 16, v35
	v_and_b32_e32 v35, 0xffff0000, v35
	s_waitcnt vmcnt(8)
	v_pk_fma_f32 v[102:103], v[36:37], v[66:67], v[102:103]
	v_pk_fma_f32 v[108:109], v[76:77], v[66:67], v[108:109]
	v_pk_fma_f32 v[116:117], v[72:73], v[66:67], v[116:117]
	v_pk_fma_f32 v[62:63], v[68:69], v[66:67], v[62:63]
	v_pk_fma_f32 v[66:67], v[0:1], v[104:105], v[52:53]
	v_pk_fma_f32 v[68:69], v[2:3], v[34:35], v[54:55]
	global_load_dwordx4 v[0:3], v[60:61], off offset:16
	global_load_dwordx4 v[52:55], v[60:61], off
	v_lshlrev_b32_e32 v32, 16, v33
	v_and_b32_e32 v33, 0xffff0000, v33
	v_pk_fma_f32 v[64:65], v[70:71], v[32:33], v[64:65]
	v_lshl_add_u64 v[70:71], v[60:61], 0, s[0:1]
	v_pk_fma_f32 v[100:101], v[38:39], v[32:33], v[100:101]
	v_pk_fma_f32 v[106:107], v[14:15], v[34:35], v[106:107]
	v_pk_fma_f32 v[110:111], v[78:79], v[32:33], v[110:111]
	v_pk_fma_f32 v[114:115], v[10:11], v[34:35], v[114:115]
	v_pk_fma_f32 v[118:119], v[74:75], v[32:33], v[118:119]
	v_pk_fma_f32 v[80:81], v[6:7], v[34:35], v[80:81]
	ds_read_b128 v[32:35], v134 offset:32768
	v_pk_fma_f32 v[82:83], v[12:13], v[104:105], v[82:83]
	v_pk_fma_f32 v[112:113], v[8:9], v[104:105], v[112:113]
	v_pk_fma_f32 v[120:121], v[4:5], v[104:105], v[120:121]
	s_waitcnt lgkmcnt(0)
; #define LAS __attribute__((address_space(3)))
; __device__ __forceinline__ void conv_phase(LAS unsigned char* lds, const bf16_t* U, bf16_t* C, const float* wdw, const float* bdw, const float* lng, const float* lnb,
;                                            int first, int stride, int end, int tid, int wave, int lane) {
;     ...
;             for (int r = 0; r < TT / NWAVES + CW - 1; ++r) {
;                 if (r + 4 < CW) { wt[(r + 4) & 7][0] = wq[0]; wt[(r + 4) & 7][1] = wq[1]; wq += D / 4; asm volatile("" : "+v"(wq)); }
;                 const u32x4 xv = *(const LAS u32x4*)(lds + (4 * wave + r) * 2048 + p * 1024 + lane * 16);
;                 f32x2 x[4];
; #pragma unroll
;                 for (int i = 0; i < 4; ++i) x[i] = (f32x2){__uint_as_float(xv[i] << 16), __uint_as_float(xv[i] & 0xffff0000u)};
; #pragma unroll
;                 for (int j = 0; j < 4; ++j) { const int w = r - j;
;                     if (w >= 0 && w < CW) {
; #pragma unroll
;                         for (int c = 0; c < 4; ++c) { const f32x4 wv = wt[w & 7][c >> 1]; const f32x2 w2 = (c & 1) ? (f32x2){wv.z, wv.w} : (f32x2){wv.x, wv.y}; acc[p][j][c] = __builtin_elementwise_fma(w2, x[c], acc[p][j][c]); } } }
;                 asm volatile("" ::: "memory");
	v_lshlrev_b32_e32 v60, 16, v32
	v_and_b32_e32 v61, 0xffff0000, v32
	v_lshlrev_b32_e32 v104, 16, v34
	v_and_b32_e32 v105, 0xffff0000, v34
	v_lshlrev_b32_e32 v34, 16, v35
	v_and_b32_e32 v35, 0xffff0000, v35
	v_lshlrev_b32_e32 v32, 16, v33
	v_and_b32_e32 v33, 0xffff0000, v33
	s_waitcnt vmcnt(8)
	v_pk_fma_f32 v[102:103], v[56:57], v[60:61], v[102:103]
	v_pk_fma_f32 v[108:109], v[36:37], v[60:61], v[108:109]
	v_pk_fma_f32 v[116:117], v[76:77], v[60:61], v[116:117]
	v_pk_fma_f32 v[72:73], v[72:73], v[60:61], v[62:63]
	v_pk_fma_f32 v[66:67], v[4:5], v[104:105], v[66:67]
	v_pk_fma_f32 v[68:69], v[6:7], v[34:35], v[68:69]
	global_load_dwordx4 v[4:7], v[70:71], off offset:16
	global_load_dwordx4 v[60:63], v[70:71], off
	v_lshl_add_u64 v[70:71], v[70:71], 0, s[0:1]
	v_pk_fma_f32 v[100:101], v[58:59], v[32:33], v[100:101]
	v_pk_fma_f32 v[106:107], v[18:19], v[34:35], v[106:107]
	v_pk_fma_f32 v[110:111], v[38:39], v[32:33], v[110:111]
	v_pk_fma_f32 v[114:115], v[14:15], v[34:35], v[114:115]
	v_pk_fma_f32 v[118:119], v[78:79], v[32:33], v[118:119]
	v_pk_fma_f32 v[80:81], v[10:11], v[34:35], v[80:81]
	v_pk_fma_f32 v[64:65], v[74:75], v[32:33], v[64:65]
	ds_read_b128 v[32:35], v134 offset:34816
	v_pk_fma_f32 v[82:83], v[16:17], v[104:105], v[82:83]
	v_pk_fma_f32 v[112:113], v[12:13], v[104:105], v[112:113]
	v_pk_fma_f32 v[120:121], v[8:9], v[104:105], v[120:121]
	s_waitcnt lgkmcnt(0)
	v_lshlrev_b32_e32 v74, 16, v32
	v_and_b32_e32 v75, 0xffff0000, v32
	v_lshlrev_b32_e32 v32, 16, v33
	v_and_b32_e32 v33, 0xffff0000, v33
	v_lshlrev_b32_e32 v104, 16, v34
	v_and_b32_e32 v105, 0xffff0000, v34
	v_lshlrev_b32_e32 v34, 16, v35
	v_and_b32_e32 v35, 0xffff0000, v35
	s_waitcnt vmcnt(8)
	v_pk_fma_f32 v[102:103], v[48:49], v[74:75], v[102:103]
	v_pk_fma_f32 v[108:109], v[56:57], v[74:75], v[108:109]
	v_pk_fma_f32 v[116:117], v[36:37], v[74:75], v[116:117]
	v_pk_fma_f32 v[72:73], v[76:77], v[74:75], v[72:73]
	v_pk_fma_f32 v[74:75], v[78:79], v[32:33], v[64:65]
	v_lshl_add_u64 v[78:79], v[70:71], 0, s[0:1]
	v_pk_fma_f32 v[100:101], v[50:51], v[32:33], v[100:101]
	v_pk_fma_f32 v[106:107], v[22:23], v[34:35], v[106:107]
	v_pk_fma_f32 v[110:111], v[58:59], v[32:33], v[110:111]
	v_pk_fma_f32 v[114:115], v[18:19], v[34:35], v[114:115]
	v_pk_fma_f32 v[118:119], v[38:39], v[32:33], v[118:119]
	v_pk_fma_f32 v[80:81], v[14:15], v[34:35], v[80:81]
	v_pk_fma_f32 v[76:77], v[8:9], v[104:105], v[66:67]
	v_pk_fma_f32 v[68:69], v[10:11], v[34:35], v[68:69]
	global_load_dwordx4 v[32:35], v[70:71], off offset:16
	global_load_dwordx4 v[64:67], v[70:71], off
	ds_read_b128 v[8:11], v134 offset:36864
	v_pk_fma_f32 v[82:83], v[20:21], v[104:105], v[82:83]
	v_pk_fma_f32 v[112:113], v[16:17], v[104:105], v[112:113]
	v_pk_fma_f32 v[120:121], v[12:13], v[104:105], v[120:121]
	s_waitcnt lgkmcnt(0)
	v_lshlrev_b32_e32 v70, 16, v8
	v_and_b32_e32 v71, 0xffff0000, v8
	v_lshlrev_b32_e32 v8, 16, v9
	v_and_b32_e32 v9, 0xffff0000, v9
	v_lshlrev_b32_e32 v104, 16, v10
	v_and_b32_e32 v105, 0xffff0000, v10
	v_lshlrev_b32_e32 v10, 16, v11
	v_and_b32_e32 v11, 0xffff0000, v11
	s_waitcnt vmcnt(8)
	v_pk_fma_f32 v[102:103], v[40:41], v[70:71], v[102:103]
	v_pk_fma_f32 v[108:109], v[48:49], v[70:71], v[108:109]
	v_pk_fma_f32 v[116:117], v[56:57], v[70:71], v[116:117]
	v_pk_fma_f32 v[72:73], v[36:37], v[70:71], v[72:73]
	v_pk_fma_f32 v[74:75], v[38:39], v[8:9], v[74:75]
	v_pk_fma_f32 v[14:15], v[14:15], v[10:11], v[68:69]
	global_load_dwordx4 v[36:39], v[78:79], off offset:16
	global_load_dwordx4 v[68:71], v[78:79], off
	v_pk_fma_f32 v[12:13], v[12:13], v[104:105], v[76:77]
	v_lshl_add_u64 v[76:77], v[78:79], 0, s[0:1]
	v_pk_fma_f32 v[100:101], v[42:43], v[8:9], v[100:101]
	v_pk_fma_f32 v[106:107], v[30:31], v[10:11], v[106:107]
	v_pk_fma_f32 v[110:111], v[50:51], v[8:9], v[110:111]
	v_pk_fma_f32 v[114:115], v[22:23], v[10:11], v[114:115]
	v_pk_fma_f32 v[118:119], v[58:59], v[8:9], v[118:119]
	v_pk_fma_f32 v[80:81], v[18:19], v[10:11], v[80:81]
	ds_read_b128 v[8:11], v134 offset:38912
	v_pk_fma_f32 v[82:83], v[28:29], v[104:105], v[82:83]
	v_pk_fma_f32 v[112:113], v[20:21], v[104:105], v[112:113]
	v_pk_fma_f32 v[120:121], v[16:17], v[104:105], v[120:121]
	s_waitcnt lgkmcnt(0)
	v_lshlrev_b32_e32 v78, 16, v8
	v_and_b32_e32 v79, 0xffff0000, v8
	v_lshlrev_b32_e32 v8, 16, v9
	v_and_b32_e32 v9, 0xffff0000, v9
	v_lshlrev_b32_e32 v104, 16, v10
	v_and_b32_e32 v105, 0xffff0000, v10
	v_lshlrev_b32_e32 v10, 16, v11
	v_and_b32_e32 v11, 0xffff0000, v11
	s_waitcnt vmcnt(8)
	v_pk_fma_f32 v[102:103], v[44:45], v[78:79], v[102:103]
	v_pk_fma_f32 v[108:109], v[40:41], v[78:79], v[108:109]
	v_pk_fma_f32 v[116:117], v[48:49], v[78:79], v[116:117]
	v_pk_fma_f32 v[78:79], v[56:57], v[78:79], v[72:73]
	v_pk_fma_f32 v[122:123], v[58:59], v[8:9], v[74:75]
	v_pk_fma_f32 v[12:13], v[16:17], v[104:105], v[12:13]
	global_load_dwordx4 v[56:59], v[76:77], off offset:16
	global_load_dwordx4 v[72:75], v[76:77], off
	v_lshl_add_u64 v[16:17], v[76:77], 0, s[0:1]
	v_pk_fma_f32 v[100:101], v[46:47], v[8:9], v[100:101]
	v_pk_fma_f32 v[106:107], v[26:27], v[10:11], v[106:107]
	v_pk_fma_f32 v[110:111], v[42:43], v[8:9], v[110:111]
	v_pk_fma_f32 v[114:115], v[30:31], v[10:11], v[114:115]
	v_pk_fma_f32 v[118:119], v[50:51], v[8:9], v[118:119]
	v_pk_fma_f32 v[80:81], v[22:23], v[10:11], v[80:81]
	v_pk_fma_f32 v[14:15], v[18:19], v[10:11], v[14:15]
	ds_read_b128 v[8:11], v134 offset:40960
	v_pk_fma_f32 v[82:83], v[24:25], v[104:105], v[82:83]
	v_pk_fma_f32 v[112:113], v[28:29], v[104:105], v[112:113]
	v_pk_fma_f32 v[120:121], v[20:21], v[104:105], v[120:121]
	s_waitcnt lgkmcnt(0)
; #define LAS __attribute__((address_space(3)))
; __device__ __forceinline__ void conv_phase(LAS unsigned char* lds, const bf16_t* U, bf16_t* C, const float* wdw, const float* bdw, const float* lng, const float* lnb,
;                                            int first, int stride, int end, int tid, int wave, int lane) {
;     ...
;             for (int r = 0; r < TT / NWAVES + CW - 1; ++r) {
;                 if (r + 4 < CW) { wt[(r + 4) & 7][0] = wq[0]; wt[(r + 4) & 7][1] = wq[1]; wq += D / 4; asm volatile("" : "+v"(wq)); }
;                 const u32x4 xv = *(const LAS u32x4*)(lds + (4 * wave + r) * 2048 + p * 1024 + lane * 16);
;                 f32x2 x[4];
; #pragma unroll
;                 for (int i = 0; i < 4; ++i) x[i] = (f32x2){__uint_as_float(xv[i] << 16), __uint_as_float(xv[i] & 0xffff0000u)};
; #pragma unroll
;                 for (int j = 0; j < 4; ++j) { const int w = r - j;
;                     if (w >= 0 && w < CW) {
; #pragma unroll
;                         for (int c = 0; c < 4; ++c) { const f32x4 wv = wt[w & 7][c >> 1]; const f32x2 w2 = (c & 1) ? (f32x2){wv.z, wv.w} : (f32x2){wv.x, wv.y}; acc[p][j][c] = __builtin_elementwise_fma(w2, x[c], acc[p][j][c]); } } }
;                 asm volatile("" ::: "memory");
	v_lshlrev_b32_e32 v18, 16, v8
	v_and_b32_e32 v19, 0xffff0000, v8
	v_lshlrev_b32_e32 v8, 16, v9
	v_and_b32_e32 v9, 0xffff0000, v9
	v_lshlrev_b32_e32 v76, 16, v10
	v_and_b32_e32 v77, 0xffff0000, v10
	v_lshlrev_b32_e32 v10, 16, v11
	v_and_b32_e32 v11, 0xffff0000, v11
	s_waitcnt vmcnt(8)
	v_pk_fma_f32 v[102:103], v[52:53], v[18:19], v[102:103]
	v_pk_fma_f32 v[82:83], v[0:1], v[76:77], v[82:83]
	v_pk_fma_f32 v[104:105], v[2:3], v[10:11], v[106:107]
	v_pk_fma_f32 v[106:107], v[44:45], v[18:19], v[108:109]
	v_pk_fma_f32 v[108:109], v[46:47], v[8:9], v[110:111]
	v_pk_fma_f32 v[110:111], v[24:25], v[76:77], v[112:113]
	v_pk_fma_f32 v[112:113], v[26:27], v[10:11], v[114:115]
	v_pk_fma_f32 v[114:115], v[40:41], v[18:19], v[116:117]
	v_pk_fma_f32 v[116:117], v[42:43], v[8:9], v[118:119]
	v_pk_fma_f32 v[118:119], v[28:29], v[76:77], v[120:121]
	v_pk_fma_f32 v[18:19], v[48:49], v[18:19], v[78:79]
	v_pk_fma_f32 v[120:121], v[50:51], v[8:9], v[122:123]
	v_pk_fma_f32 v[12:13], v[20:21], v[76:77], v[12:13]
	global_load_dwordx4 v[48:51], v[16:17], off offset:16
	global_load_dwordx4 v[76:79], v[16:17], off
	v_lshl_add_u64 v[16:17], v[16:17], 0, s[0:1]
	v_pk_fma_f32 v[100:101], v[54:55], v[8:9], v[100:101]
	v_pk_fma_f32 v[80:81], v[30:31], v[10:11], v[80:81]
	v_pk_fma_f32 v[14:15], v[22:23], v[10:11], v[14:15]
	ds_read_b128 v[8:11], v134 offset:43008
	s_waitcnt lgkmcnt(0)
	v_lshlrev_b32_e32 v20, 16, v8
	v_and_b32_e32 v21, 0xffff0000, v8
	v_lshlrev_b32_e32 v8, 16, v9
	v_and_b32_e32 v9, 0xffff0000, v9
	v_lshlrev_b32_e32 v22, 16, v10
	v_and_b32_e32 v23, 0xffff0000, v10
	v_lshlrev_b32_e32 v10, 16, v11
	v_and_b32_e32 v11, 0xffff0000, v11
	s_waitcnt vmcnt(8)
	v_pk_fma_f32 v[102:103], v[60:61], v[20:21], v[102:103]
	v_pk_fma_f32 v[106:107], v[52:53], v[20:21], v[106:107]
	v_pk_fma_f32 v[114:115], v[44:45], v[20:21], v[114:115]
	v_pk_fma_f32 v[18:19], v[40:41], v[20:21], v[18:19]
	v_pk_fma_f32 v[20:21], v[42:43], v[8:9], v[120:121]
	v_pk_fma_f32 v[12:13], v[28:29], v[22:23], v[12:13]
	v_pk_fma_f32 v[14:15], v[30:31], v[10:11], v[14:15]
	global_load_dwordx4 v[28:31], v[16:17], off offset:16
	global_load_dwordx4 v[40:43], v[16:17], off
	v_lshl_add_u64 v[16:17], v[16:17], 0, s[0:1]
	v_pk_fma_f32 v[100:101], v[62:63], v[8:9], v[100:101]
	v_pk_fma_f32 v[104:105], v[6:7], v[10:11], v[104:105]
	v_pk_fma_f32 v[108:109], v[54:55], v[8:9], v[108:109]
	v_pk_fma_f32 v[112:113], v[2:3], v[10:11], v[112:113]
	v_pk_fma_f32 v[116:117], v[46:47], v[8:9], v[116:117]
	v_pk_fma_f32 v[80:81], v[26:27], v[10:11], v[80:81]
	ds_read_b128 v[8:11], v134 offset:45056
	v_pk_fma_f32 v[82:83], v[4:5], v[22:23], v[82:83]
	v_pk_fma_f32 v[110:111], v[0:1], v[22:23], v[110:111]
	v_pk_fma_f32 v[118:119], v[24:25], v[22:23], v[118:119]
	s_waitcnt lgkmcnt(0)
	v_lshlrev_b32_e32 v120, 16, v10
	v_and_b32_e32 v121, 0xffff0000, v10
	v_lshlrev_b32_e32 v22, 16, v8
	v_and_b32_e32 v23, 0xffff0000, v8
	v_lshlrev_b32_e32 v8, 16, v9
	v_and_b32_e32 v9, 0xffff0000, v9
	v_lshlrev_b32_e32 v10, 16, v11
	v_and_b32_e32 v11, 0xffff0000, v11
	s_waitcnt vmcnt(9)
	v_pk_fma_f32 v[82:83], v[32:33], v[120:121], v[82:83]
	v_pk_fma_f32 v[110:111], v[4:5], v[120:121], v[110:111]
	v_pk_fma_f32 v[118:119], v[0:1], v[120:121], v[118:119]
	v_pk_fma_f32 v[12:13], v[24:25], v[120:121], v[12:13]
	v_lshl_add_u64 v[120:121], v[16:17], 0, s[0:1]
	s_waitcnt vmcnt(8)
	v_pk_fma_f32 v[100:101], v[66:67], v[8:9], v[100:101]
	v_pk_fma_f32 v[104:105], v[34:35], v[10:11], v[104:105]
	v_pk_fma_f32 v[108:109], v[62:63], v[8:9], v[108:109]
	v_pk_fma_f32 v[112:113], v[6:7], v[10:11], v[112:113]
	v_pk_fma_f32 v[116:117], v[54:55], v[8:9], v[116:117]
	v_pk_fma_f32 v[80:81], v[2:3], v[10:11], v[80:81]
	v_pk_fma_f32 v[18:19], v[44:45], v[22:23], v[18:19]
	v_pk_fma_f32 v[20:21], v[46:47], v[8:9], v[20:21]
	v_pk_fma_f32 v[14:15], v[26:27], v[10:11], v[14:15]
	global_load_dwordx4 v[24:27], v[16:17], off offset:16
	global_load_dwordx4 v[44:47], v[16:17], off
	ds_read_b128 v[8:11], v134 offset:47104
	v_pk_fma_f32 v[102:103], v[64:65], v[22:23], v[102:103]
	v_pk_fma_f32 v[106:107], v[60:61], v[22:23], v[106:107]
	v_pk_fma_f32 v[114:115], v[52:53], v[22:23], v[114:115]
	s_waitcnt lgkmcnt(0)
	v_lshlrev_b32_e32 v16, 16, v8
	v_and_b32_e32 v17, 0xffff0000, v8
	v_lshlrev_b32_e32 v8, 16, v9
	v_and_b32_e32 v9, 0xffff0000, v9
	v_lshlrev_b32_e32 v22, 16, v10
	v_and_b32_e32 v23, 0xffff0000, v10
	s_waitcnt vmcnt(8)
	v_pk_fma_f32 v[102:103], v[68:69], v[16:17], v[102:103]
	v_pk_fma_f32 v[100:101], v[70:71], v[8:9], v[100:101]
	v_pk_fma_f32 v[82:83], v[36:37], v[22:23], v[82:83]
	v_pk_fma_f32 v[106:107], v[64:65], v[16:17], v[106:107]
	v_pk_fma_f32 v[108:109], v[66:67], v[8:9], v[108:109]
	v_pk_fma_f32 v[110:111], v[32:33], v[22:23], v[110:111]
	v_pk_fma_f32 v[114:115], v[60:61], v[16:17], v[114:115]
	v_pk_fma_f32 v[116:117], v[62:63], v[8:9], v[116:117]
	v_pk_fma_f32 v[118:119], v[4:5], v[22:23], v[118:119]
	v_pk_fma_f32 v[52:53], v[52:53], v[16:17], v[18:19]
	v_pk_fma_f32 v[8:9], v[54:55], v[8:9], v[20:21]
	v_pk_fma_f32 v[12:13], v[0:1], v[22:23], v[12:13]
	global_load_dwordx4 v[16:19], v[120:121], off offset:16
	global_load_dwordx4 v[20:23], v[120:121], off
	v_lshlrev_b32_e32 v10, 16, v11
	v_and_b32_e32 v11, 0xffff0000, v11
	v_lshl_add_u64 v[54:55], v[120:121], 0, s[0:1]
	v_pk_fma_f32 v[104:105], v[38:39], v[10:11], v[104:105]
	v_pk_fma_f32 v[112:113], v[34:35], v[10:11], v[112:113]
	v_pk_fma_f32 v[80:81], v[6:7], v[10:11], v[80:81]
	v_pk_fma_f32 v[10:11], v[2:3], v[10:11], v[14:15]
	ds_read_b128 v[0:3], v134 offset:49152
	s_waitcnt lgkmcnt(0)
; #define LAS __attribute__((address_space(3)))
; __device__ __forceinline__ void conv_phase(LAS unsigned char* lds, const bf16_t* U, bf16_t* C, const float* wdw, const float* bdw, const float* lng, const float* lnb,
;                                            int first, int stride, int end, int tid, int wave, int lane) {
;     ...
;             for (int r = 0; r < TT / NWAVES + CW - 1; ++r) {
;                 if (r + 4 < CW) { wt[(r + 4) & 7][0] = wq[0]; wt[(r + 4) & 7][1] = wq[1]; wq += D / 4; asm volatile("" : "+v"(wq)); }
;                 const u32x4 xv = *(const LAS u32x4*)(lds + (4 * wave + r) * 2048 + p * 1024 + lane * 16);
;                 f32x2 x[4];
; #pragma unroll
;                 for (int i = 0; i < 4; ++i) x[i] = (f32x2){__uint_as_float(xv[i] << 16), __uint_as_float(xv[i] & 0xffff0000u)};
; #pragma unroll
;                 for (int j = 0; j < 4; ++j) { const int w = r - j;
;                     if (w >= 0 && w < CW) {
; #pragma unroll
;                         for (int c = 0; c < 4; ++c) { const f32x4 wv = wt[w & 7][c >> 1]; const f32x2 w2 = (c & 1) ? (f32x2){wv.z, wv.w} : (f32x2){wv.x, wv.y}; acc[p][j][c] = __builtin_elementwise_fma(w2, x[c], acc[p][j][c]); } } }
;                 asm volatile("" ::: "memory");
	v_lshlrev_b32_e32 v14, 16, v0
	v_and_b32_e32 v15, 0xffff0000, v0
	v_lshlrev_b32_e32 v0, 16, v1
	v_and_b32_e32 v1, 0xffff0000, v1
	v_lshlrev_b32_e32 v120, 16, v2
	v_and_b32_e32 v121, 0xffff0000, v2
	v_lshlrev_b32_e32 v2, 16, v3
	v_and_b32_e32 v3, 0xffff0000, v3
	s_waitcnt vmcnt(8)
	v_pk_fma_f32 v[102:103], v[72:73], v[14:15], v[102:103]
	v_pk_fma_f32 v[106:107], v[68:69], v[14:15], v[106:107]
	v_pk_fma_f32 v[114:115], v[64:65], v[14:15], v[114:115]
	v_pk_fma_f32 v[52:53], v[60:61], v[14:15], v[52:53]
	v_pk_fma_f32 v[60:61], v[62:63], v[0:1], v[8:9]
	v_pk_fma_f32 v[4:5], v[4:5], v[120:121], v[12:13]
	v_pk_fma_f32 v[6:7], v[6:7], v[2:3], v[10:11]
	global_load_dwordx4 v[8:11], v[54:55], off offset:16
	global_load_dwordx4 v[12:15], v[54:55], off
	v_lshl_add_u64 v[54:55], v[54:55], 0, s[0:1]
	v_pk_fma_f32 v[100:101], v[74:75], v[0:1], v[100:101]
	v_pk_fma_f32 v[104:105], v[58:59], v[2:3], v[104:105]
	v_pk_fma_f32 v[108:109], v[70:71], v[0:1], v[108:109]
	v_pk_fma_f32 v[112:113], v[38:39], v[2:3], v[112:113]
	v_pk_fma_f32 v[116:117], v[66:67], v[0:1], v[116:117]
	v_pk_fma_f32 v[80:81], v[34:35], v[2:3], v[80:81]
	ds_read_b128 v[0:3], v134 offset:51200
	v_pk_fma_f32 v[82:83], v[56:57], v[120:121], v[82:83]
	v_pk_fma_f32 v[110:111], v[36:37], v[120:121], v[110:111]
	v_pk_fma_f32 v[118:119], v[32:33], v[120:121], v[118:119]
	s_waitcnt lgkmcnt(0)
	v_lshlrev_b32_e32 v62, 16, v0
	v_and_b32_e32 v63, 0xffff0000, v0
	v_lshlrev_b32_e32 v0, 16, v1
	v_and_b32_e32 v1, 0xffff0000, v1
	v_lshlrev_b32_e32 v120, 16, v2
	v_and_b32_e32 v121, 0xffff0000, v2
	v_lshlrev_b32_e32 v2, 16, v3
	v_and_b32_e32 v3, 0xffff0000, v3
	s_waitcnt vmcnt(8)
	v_pk_fma_f32 v[102:103], v[76:77], v[62:63], v[102:103]
	v_pk_fma_f32 v[100:101], v[78:79], v[0:1], v[100:101]
	v_pk_fma_f32 v[104:105], v[50:51], v[2:3], v[104:105]
	v_pk_fma_f32 v[106:107], v[72:73], v[62:63], v[106:107]
	v_pk_fma_f32 v[108:109], v[74:75], v[0:1], v[108:109]
	v_pk_fma_f32 v[112:113], v[58:59], v[2:3], v[112:113]
	v_pk_fma_f32 v[114:115], v[68:69], v[62:63], v[114:115]
	v_pk_fma_f32 v[116:117], v[70:71], v[0:1], v[116:117]
	v_pk_fma_f32 v[80:81], v[38:39], v[2:3], v[80:81]
	v_pk_fma_f32 v[52:53], v[64:65], v[62:63], v[52:53]
	v_pk_fma_f32 v[60:61], v[66:67], v[0:1], v[60:61]
	v_pk_fma_f32 v[62:63], v[32:33], v[120:121], v[4:5]
	v_pk_fma_f32 v[64:65], v[34:35], v[2:3], v[6:7]
	global_load_dwordx4 v[4:7], v[54:55], off offset:16
	global_load_dwordx4 v[0:3], v[54:55], off
	v_lshl_add_u64 v[32:33], v[54:55], 0, s[0:1]
	ds_read_b128 v[32:35], v134 offset:53248
	v_pk_fma_f32 v[82:83], v[48:49], v[120:121], v[82:83]
	v_pk_fma_f32 v[110:111], v[56:57], v[120:121], v[110:111]
	v_pk_fma_f32 v[118:119], v[36:37], v[120:121], v[118:119]
	s_waitcnt lgkmcnt(0)
	v_lshlrev_b32_e32 v54, 16, v32
	v_and_b32_e32 v55, 0xffff0000, v32
	v_lshlrev_b32_e32 v32, 16, v33
	v_and_b32_e32 v33, 0xffff0000, v33
	v_lshlrev_b32_e32 v66, 16, v34
	v_and_b32_e32 v67, 0xffff0000, v34
	v_lshlrev_b32_e32 v34, 16, v35
	v_and_b32_e32 v35, 0xffff0000, v35
	s_waitcnt vmcnt(8)
	v_pk_fma_f32 v[102:103], v[40:41], v[54:55], v[102:103]
	v_pk_fma_f32 v[100:101], v[42:43], v[32:33], v[100:101]
	v_pk_fma_f32 v[104:105], v[30:31], v[34:35], v[104:105]
	v_pk_fma_f32 v[106:107], v[76:77], v[54:55], v[106:107]
	v_pk_fma_f32 v[108:109], v[78:79], v[32:33], v[108:109]
	v_pk_fma_f32 v[112:113], v[50:51], v[34:35], v[112:113]
	v_pk_fma_f32 v[114:115], v[72:73], v[54:55], v[114:115]
	v_pk_fma_f32 v[116:117], v[74:75], v[32:33], v[116:117]
	v_pk_fma_f32 v[80:81], v[58:59], v[34:35], v[80:81]
	v_pk_fma_f32 v[52:53], v[68:69], v[54:55], v[52:53]
	v_pk_fma_f32 v[54:55], v[70:71], v[32:33], v[60:61]
	v_pk_fma_f32 v[38:39], v[38:39], v[34:35], v[64:65]
	ds_read_b128 v[32:35], v134 offset:55296
	v_pk_fma_f32 v[36:37], v[36:37], v[66:67], v[62:63]
	v_pk_fma_f32 v[82:83], v[28:29], v[66:67], v[82:83]
	v_pk_fma_f32 v[110:111], v[48:49], v[66:67], v[110:111]
	s_waitcnt lgkmcnt(0)
	v_lshlrev_b32_e32 v60, 16, v32
	v_and_b32_e32 v61, 0xffff0000, v32
	v_lshlrev_b32_e32 v32, 16, v33
	v_and_b32_e32 v33, 0xffff0000, v33
	v_lshlrev_b32_e32 v62, 16, v34
	v_and_b32_e32 v63, 0xffff0000, v34
	v_lshlrev_b32_e32 v34, 16, v35
	v_and_b32_e32 v35, 0xffff0000, v35
	v_pk_fma_f32 v[118:119], v[56:57], v[66:67], v[118:119]
	s_waitcnt vmcnt(6)
	v_pk_fma_f32 v[66:67], v[46:47], v[32:33], v[100:101]
	v_pk_fma_f32 v[70:71], v[26:27], v[34:35], v[104:105]
	v_pk_fma_f32 v[100:101], v[42:43], v[32:33], v[108:109]
	v_pk_fma_f32 v[104:105], v[30:31], v[34:35], v[112:113]
	v_pk_fma_f32 v[108:109], v[78:79], v[32:33], v[116:117]
	v_pk_fma_f32 v[80:81], v[50:51], v[34:35], v[80:81]
	v_pk_fma_f32 v[54:55], v[74:75], v[32:33], v[54:55]
	v_pk_fma_f32 v[38:39], v[58:59], v[34:35], v[38:39]
	ds_read_b128 v[32:35], v134 offset:57344
	v_pk_fma_f32 v[36:37], v[56:57], v[62:63], v[36:37]
	v_pk_fma_f32 v[64:65], v[44:45], v[60:61], v[102:103]
	v_pk_fma_f32 v[68:69], v[24:25], v[62:63], v[82:83]
	s_waitcnt lgkmcnt(0)
	v_lshlrev_b32_e32 v56, 16, v32
	v_and_b32_e32 v57, 0xffff0000, v32
	v_lshlrev_b32_e32 v32, 16, v33
	v_and_b32_e32 v33, 0xffff0000, v33
	v_lshlrev_b32_e32 v58, 16, v34
	v_and_b32_e32 v59, 0xffff0000, v34
	v_lshlrev_b32_e32 v34, 16, v35
	v_and_b32_e32 v35, 0xffff0000, v35
	v_pk_fma_f32 v[102:103], v[28:29], v[62:63], v[110:111]
	v_pk_fma_f32 v[110:111], v[48:49], v[62:63], v[118:119]
	s_waitcnt vmcnt(4)
; #define LAS __attribute__((address_space(3)))
; __device__ __forceinline__ void conv_phase(LAS unsigned char* lds, const bf16_t* U, bf16_t* C, const float* wdw, const float* bdw, const float* lng, const float* lnb,
;                                            int first, int stride, int end, int tid, int wave, int lane) {
;     ...
;             for (int r = 0; r < TT / NWAVES + CW - 1; ++r) {
;                 if (r + 4 < CW) { wt[(r + 4) & 7][0] = wq[0]; wt[(r + 4) & 7][1] = wq[1]; wq += D / 4; asm volatile("" : "+v"(wq)); }
;                 const u32x4 xv = *(const LAS u32x4*)(lds + (4 * wave + r) * 2048 + p * 1024 + lane * 16);
;                 f32x2 x[4];
; #pragma unroll
;                 for (int i = 0; i < 4; ++i) x[i] = (f32x2){__uint_as_float(xv[i] << 16), __uint_as_float(xv[i] & 0xffff0000u)};
; #pragma unroll
;                 for (int j = 0; j < 4; ++j) { const int w = r - j;
;                     if (w >= 0 && w < CW) {
; #pragma unroll
;                         for (int c = 0; c < 4; ++c) { const f32x4 wv = wt[w & 7][c >> 1]; const f32x2 w2 = (c & 1) ? (f32x2){wv.z, wv.w} : (f32x2){wv.x, wv.y}; acc[p][j][c] = __builtin_elementwise_fma(w2, x[c], acc[p][j][c]); } } }
;                 asm volatile("" ::: "memory");
;             }
;             const f32x4 b0 = *(const f32x4*)(bdw + p * 512 + lane * 8), b1 = *(const f32x4*)(bdw + p * 512 + lane * 8 + 4);
; #pragma unroll
;             for (int j = 0; j < 4; ++j) { acc[p][j][0] += (f32x2){b0.x, b0.y}; acc[p][j][1] += (f32x2){b0.z, b0.w}; acc[p][j][2] += (f32x2){b1.x, b1.y}; acc[p][j][3] += (f32x2){b1.z, b1.w}; }
	v_pk_fma_f32 v[62:63], v[22:23], v[32:33], v[66:67]
	v_pk_fma_f32 v[66:67], v[18:19], v[34:35], v[70:71]
	v_pk_fma_f32 v[70:71], v[46:47], v[32:33], v[100:101]
	v_pk_fma_f32 v[74:75], v[26:27], v[34:35], v[104:105]
	v_pk_fma_f32 v[100:101], v[42:43], v[32:33], v[108:109]
	v_pk_fma_f32 v[80:81], v[30:31], v[34:35], v[80:81]
	v_pk_fma_f32 v[54:55], v[78:79], v[32:33], v[54:55]
	v_pk_fma_f32 v[38:39], v[50:51], v[34:35], v[38:39]
	ds_read_b128 v[32:35], v134 offset:59392
	v_pk_fma_f32 v[36:37], v[48:49], v[58:59], v[36:37]
	v_pk_fma_f32 v[52:53], v[72:73], v[60:61], v[52:53]
	v_pk_fma_f32 v[72:73], v[24:25], v[58:59], v[102:103]
	s_waitcnt lgkmcnt(0)
	v_lshlrev_b32_e32 v50, 16, v34
	v_and_b32_e32 v51, 0xffff0000, v34
	v_lshlrev_b32_e32 v34, 16, v35
	v_and_b32_e32 v35, 0xffff0000, v35
	v_pk_fma_f32 v[102:103], v[28:29], v[58:59], v[110:111]
	v_pk_fma_f32 v[36:37], v[28:29], v[50:51], v[36:37]
	v_pk_fma_f32 v[38:39], v[30:31], v[34:35], v[38:39]
	ds_read_b128 v[28:31], v134 offset:61440
	v_pk_fma_f32 v[82:83], v[40:41], v[60:61], v[106:107]
	v_pk_fma_f32 v[106:107], v[76:77], v[60:61], v[114:115]
	v_pk_fma_f32 v[60:61], v[20:21], v[56:57], v[64:65]
	v_pk_fma_f32 v[64:65], v[16:17], v[58:59], v[68:69]
	v_pk_fma_f32 v[68:69], v[44:45], v[56:57], v[82:83]
	v_pk_fma_f32 v[82:83], v[40:41], v[56:57], v[106:107]
	v_pk_fma_f32 v[52:53], v[76:77], v[56:57], v[52:53]
	v_lshlrev_b32_e32 v48, 16, v32
	v_and_b32_e32 v49, 0xffff0000, v32
	v_lshlrev_b32_e32 v32, 16, v33
	v_and_b32_e32 v33, 0xffff0000, v33
	s_waitcnt vmcnt(2)
	v_pk_fma_f32 v[56:57], v[12:13], v[48:49], v[60:61]
	v_pk_fma_f32 v[60:61], v[8:9], v[50:51], v[64:65]
	v_pk_fma_f32 v[64:65], v[20:21], v[48:49], v[68:69]
	v_pk_fma_f32 v[68:69], v[16:17], v[50:51], v[72:73]
	v_pk_fma_f32 v[72:73], v[44:45], v[48:49], v[82:83]
	v_pk_fma_f32 v[76:77], v[24:25], v[50:51], v[102:103]
	v_pk_fma_f32 v[40:41], v[40:41], v[48:49], v[52:53]
	v_pk_fma_f32 v[42:43], v[42:43], v[32:33], v[54:55]
	s_waitcnt lgkmcnt(0)
	v_lshlrev_b32_e32 v48, 16, v28
	v_and_b32_e32 v49, 0xffff0000, v28
	v_lshlrev_b32_e32 v50, 16, v29
	v_and_b32_e32 v51, 0xffff0000, v29
	v_lshlrev_b32_e32 v52, 16, v30
	v_and_b32_e32 v53, 0xffff0000, v30
	v_lshlrev_b32_e32 v54, 16, v31
	v_and_b32_e32 v55, 0xffff0000, v31
	v_pk_fma_f32 v[58:59], v[14:15], v[32:33], v[62:63]
	v_pk_fma_f32 v[62:63], v[10:11], v[34:35], v[66:67]
	v_pk_fma_f32 v[66:67], v[22:23], v[32:33], v[70:71]
	v_pk_fma_f32 v[70:71], v[18:19], v[34:35], v[74:75]
	v_pk_fma_f32 v[74:75], v[46:47], v[32:33], v[100:101]
	v_pk_fma_f32 v[78:79], v[26:27], v[34:35], v[80:81]
	v_pk_fma_f32 v[40:41], v[44:45], v[48:49], v[40:41]
	v_pk_fma_f32 v[42:43], v[46:47], v[50:51], v[42:43]
	v_pk_fma_f32 v[44:45], v[24:25], v[52:53], v[36:37]
	v_pk_fma_f32 v[46:47], v[26:27], v[54:55], v[38:39]
	ds_read_b128 v[24:27], v134 offset:63488
	s_waitcnt vmcnt(0)
	v_pk_fma_f32 v[28:29], v[0:1], v[48:49], v[56:57]
	v_pk_fma_f32 v[30:31], v[2:3], v[50:51], v[58:59]
	v_pk_fma_f32 v[32:33], v[4:5], v[52:53], v[60:61]
	v_pk_fma_f32 v[34:35], v[6:7], v[54:55], v[62:63]
	v_pk_fma_f32 v[56:57], v[12:13], v[48:49], v[64:65]
	v_pk_fma_f32 v[58:59], v[14:15], v[50:51], v[66:67]
	v_pk_fma_f32 v[60:61], v[8:9], v[52:53], v[68:69]
	v_pk_fma_f32 v[62:63], v[10:11], v[54:55], v[70:71]
	v_pk_fma_f32 v[64:65], v[20:21], v[48:49], v[72:73]
	v_pk_fma_f32 v[66:67], v[22:23], v[50:51], v[74:75]
	v_pk_fma_f32 v[68:69], v[16:17], v[52:53], v[76:77]
	v_pk_fma_f32 v[70:71], v[18:19], v[54:55], v[78:79]
	s_waitcnt lgkmcnt(0)
	v_lshlrev_b32_e32 v48, 16, v24
	v_and_b32_e32 v49, 0xffff0000, v24
	v_lshlrev_b32_e32 v50, 16, v25
	v_and_b32_e32 v51, 0xffff0000, v25
	v_lshlrev_b32_e32 v52, 16, v26
	v_and_b32_e32 v53, 0xffff0000, v26
	v_lshlrev_b32_e32 v54, 16, v27
	v_and_b32_e32 v55, 0xffff0000, v27
	v_pk_fma_f32 v[20:21], v[20:21], v[48:49], v[40:41]
	v_pk_fma_f32 v[22:23], v[22:23], v[50:51], v[42:43]
	v_pk_fma_f32 v[40:41], v[16:17], v[52:53], v[44:45]
	v_pk_fma_f32 v[42:43], v[18:19], v[54:55], v[46:47]
	ds_read_b128 v[16:19], v136
	v_pk_fma_f32 v[26:27], v[2:3], v[50:51], v[58:59]
	v_pk_fma_f32 v[38:39], v[6:7], v[54:55], v[62:63]
	v_pk_fma_f32 v[58:59], v[14:15], v[50:51], v[66:67]
	v_pk_fma_f32 v[62:63], v[10:11], v[54:55], v[70:71]
	s_waitcnt lgkmcnt(0)
	v_lshlrev_b32_e32 v44, 16, v16
	v_and_b32_e32 v45, 0xffff0000, v16
	v_lshlrev_b32_e32 v16, 16, v17
	v_and_b32_e32 v17, 0xffff0000, v17
	v_lshlrev_b32_e32 v46, 16, v18
	v_and_b32_e32 v47, 0xffff0000, v18
	v_lshlrev_b32_e32 v18, 16, v19
	v_and_b32_e32 v19, 0xffff0000, v19
	v_pk_fma_f32 v[36:37], v[4:5], v[52:53], v[60:61]
	v_pk_fma_f32 v[60:61], v[8:9], v[52:53], v[68:69]
	v_pk_fma_f32 v[50:51], v[2:3], v[16:17], v[58:59]
	v_pk_fma_f32 v[54:55], v[6:7], v[18:19], v[62:63]
	v_pk_fma_f32 v[14:15], v[14:15], v[16:17], v[22:23]
	v_pk_fma_f32 v[16:17], v[8:9], v[46:47], v[40:41]
	v_pk_fma_f32 v[18:19], v[10:11], v[18:19], v[42:43]
	ds_read_b128 v[8:11], v137
	v_pk_fma_f32 v[24:25], v[0:1], v[48:49], v[56:57]
	v_pk_fma_f32 v[56:57], v[12:13], v[48:49], v[64:65]
	v_pk_fma_f32 v[12:13], v[12:13], v[44:45], v[20:21]
	s_waitcnt lgkmcnt(0)
	v_lshlrev_b32_e32 v20, 16, v8
	v_and_b32_e32 v21, 0xffff0000, v8
	v_lshlrev_b32_e32 v8, 16, v9
	v_and_b32_e32 v9, 0xffff0000, v9
	v_lshlrev_b32_e32 v22, 16, v10
	v_and_b32_e32 v23, 0xffff0000, v10
	v_lshlrev_b32_e32 v10, 16, v11
	v_and_b32_e32 v11, 0xffff0000, v11
	v_pk_fma_f32 v[48:49], v[0:1], v[44:45], v[56:57]
	v_pk_fma_f32 v[52:53], v[4:5], v[46:47], v[60:61]
	v_pk_fma_f32 v[10:11], v[6:7], v[10:11], v[18:19]
	v_pk_fma_f32 v[16:17], v[4:5], v[22:23], v[16:17]
	v_pk_fma_f32 v[8:9], v[2:3], v[8:9], v[14:15]
	v_pk_fma_f32 v[12:13], v[0:1], v[20:21], v[12:13]
	v_mov_b64_e32 v[0:1], v[180:181]
	v_mov_b64_e32 v[2:3], v[182:183]
	v_mov_b64_e32 v[4:5], v[184:185]
	v_mov_b64_e32 v[6:7], v[186:187]
	s_waitcnt vmcnt(1)
; #define LAS __attribute__((address_space(3)))
; __device__ __forceinline__ void conv_phase(LAS unsigned char* lds, const bf16_t* U, bf16_t* C, const float* wdw, const float* bdw, const float* lng, const float* lnb,
;                                            int first, int stride, int end, int tid, int wave, int lane) {
;     ...
;             f32x4 wt[8][2];
;             typedef const __attribute__((address_space(1))) f32x4 gf32x4;
;             const gf32x4* wq = (const gf32x4*)(wdw + p * 512 + lane * 8);
; #pragma unroll
;             for (int t = 0; t < 4; ++t) { wt[t][0] = wq[0]; wt[t][1] = wq[1]; wq += D / 4; asm volatile("" : "+v"(wq)); }
; #pragma unroll
;             for (int r = 0; r < TT / NWAVES + CW - 1; ++r) {
;                 if (r + 4 < CW) { wt[(r + 4) & 7][0] = wq[0]; wt[(r + 4) & 7][1] = wq[1]; wq += D / 4; asm volatile("" : "+v"(wq)); }
;                 const u32x4 xv = *(const LAS u32x4*)(lds + (4 * wave + r) * 2048 + p * 1024 + lane * 16);
;                 f32x2 x[4];
; #pragma unroll
;                 for (int i = 0; i < 4; ++i) x[i] = (f32x2){__uint_as_float(xv[i] << 16), __uint_as_float(xv[i] & 0xffff0000u)};
; #pragma unroll
;                 for (int j = 0; j < 4; ++j) { const int w = r - j;
;                     if (w >= 0 && w < CW) {
; #pragma unroll
;                         for (int c = 0; c < 4; ++c) { const f32x4 wv = wt[w & 7][c >> 1]; const f32x2 w2 = (c & 1) ? (f32x2){wv.z, wv.w} : (f32x2){wv.x, wv.y}; acc[p][j][c] = __builtin_elementwise_fma(w2, x[c], acc[p][j][c]); } } }
;                 asm volatile("" ::: "memory");
;             }
;             const f32x4 b0 = *(const f32x4*)(bdw + p * 512 + lane * 8), b1 = *(const f32x4*)(bdw + p * 512 + lane * 8 + 4);
; #pragma unroll
;             for (int j = 0; j < 4; ++j) { acc[p][j][0] += (f32x2){b0.x, b0.y}; acc[p][j][1] += (f32x2){b0.z, b0.w}; acc[p][j][2] += (f32x2){b1.x, b1.y}; acc[p][j][3] += (f32x2){b1.z, b1.w}; }
	v_pk_add_f32 v[118:119], v[36:37], v[0:1]
	s_waitcnt vmcnt(0)
	v_pk_add_f32 v[128:129], v[28:29], v[4:5]
	v_pk_add_f32 v[130:131], v[30:31], v[6:7]
	v_pk_add_f32 v[120:121], v[24:25], v[4:5]
	v_pk_add_f32 v[122:123], v[26:27], v[6:7]
	v_pk_add_f32 v[116:117], v[38:39], v[2:3]
	v_pk_add_f32 v[112:113], v[4:5], v[48:49]
	v_pk_add_f32 v[114:115], v[6:7], v[50:51]
	v_pk_add_f32 v[104:105], v[4:5], v[12:13]
	v_pk_add_f32 v[106:107], v[6:7], v[8:9]
	global_load_dwordx4 v[4:7], v[84:85], off offset:2064
	global_load_dwordx4 v[36:39], v[84:85], off offset:2048
	v_pk_add_f32 v[126:127], v[32:33], v[0:1]
	v_pk_add_f32 v[110:111], v[0:1], v[52:53]
	v_pk_add_f32 v[102:103], v[0:1], v[16:17]
	v_mov_b64_e32 v[0:1], v[98:99]
	v_pk_add_f32 v[100:101], v[2:3], v[10:11]
	global_load_dwordx4 v[8:11], v[0:1], off offset:16
	global_load_dwordx4 v[12:15], v[0:1], off
	v_lshl_add_u64 v[0:1], v[0:1], 0, s[0:1]
	global_load_dwordx4 v[44:47], v[0:1], off offset:16
	global_load_dwordx4 v[64:67], v[0:1], off
	v_lshl_add_u64 v[0:1], v[0:1], 0, s[0:1]
	global_load_dwordx4 v[16:19], v[0:1], off offset:16
	global_load_dwordx4 v[48:51], v[0:1], off
	v_lshl_add_u64 v[0:1], v[0:1], 0, s[0:1]
	v_pk_add_f32 v[108:109], v[2:3], v[54:55]
	global_load_dwordx4 v[20:23], v[0:1], off offset:16
	global_load_dwordx4 v[52:55], v[0:1], off
	v_lshl_add_u64 v[28:29], v[0:1], 0, s[0:1]
	v_pk_add_f32 v[124:125], v[34:35], v[2:3]
	ds_read_b128 v[0:3], v134 offset:1024
	v_lshl_add_u64 v[42:43], v[28:29], 0, s[0:1]
	s_waitcnt lgkmcnt(0)
	v_lshlrev_b32_e32 v24, 16, v3
	v_and_b32_e32 v25, 0xffff0000, v3
	v_lshlrev_b32_e32 v26, 16, v2
	v_and_b32_e32 v27, 0xffff0000, v2
	v_lshlrev_b32_e32 v2, 16, v1
	v_and_b32_e32 v3, 0xffff0000, v1
	v_lshlrev_b32_e32 v30, 16, v0
	v_and_b32_e32 v31, 0xffff0000, v0
	s_waitcnt vmcnt(9)
	v_pk_fma_f32 v[34:35], v[4:5], v[26:27], 0 op_sel_hi:[1,1,0]
	v_pk_fma_f32 v[40:41], v[6:7], v[24:25], 0 op_sel_hi:[1,1,0]
	global_load_dwordx4 v[24:27], v[28:29], off offset:16
	global_load_dwordx4 v[56:59], v[28:29], off
	s_waitcnt vmcnt(10)
	v_pk_fma_f32 v[32:33], v[38:39], v[2:3], 0 op_sel_hi:[1,1,0]
	ds_read_b128 v[0:3], v134 offset:3072
	v_pk_fma_f32 v[30:31], v[36:37], v[30:31], 0 op_sel_hi:[1,1,0]
	s_waitcnt lgkmcnt(0)
	v_lshlrev_b32_e32 v28, 16, v0
	v_and_b32_e32 v29, 0xffff0000, v0
	v_lshlrev_b32_e32 v60, 16, v2
	v_and_b32_e32 v61, 0xffff0000, v2
	v_lshlrev_b32_e32 v0, 16, v1
	v_and_b32_e32 v1, 0xffff0000, v1
	v_lshlrev_b32_e32 v2, 16, v3
	v_and_b32_e32 v3, 0xffff0000, v3
	s_waitcnt vmcnt(8)
	v_pk_fma_f32 v[68:69], v[12:13], v[28:29], v[30:31]
	v_pk_fma_f32 v[34:35], v[8:9], v[60:61], v[34:35]
	v_pk_fma_f32 v[70:71], v[36:37], v[28:29], 0 op_sel_hi:[1,1,0]
	v_pk_fma_f32 v[74:75], v[4:5], v[60:61], 0 op_sel_hi:[1,1,0]
	global_load_dwordx4 v[28:31], v[42:43], off offset:16
	global_load_dwordx4 v[60:63], v[42:43], off
	v_lshl_add_u64 v[42:43], v[42:43], 0, s[0:1]
	v_pk_fma_f32 v[32:33], v[14:15], v[0:1], v[32:33]
	v_pk_fma_f32 v[40:41], v[10:11], v[2:3], v[40:41]
	v_pk_fma_f32 v[72:73], v[38:39], v[0:1], 0 op_sel_hi:[1,1,0]
	v_pk_fma_f32 v[76:77], v[6:7], v[2:3], 0 op_sel_hi:[1,1,0]
	ds_read_b128 v[0:3], v134 offset:5120
	v_lshl_add_u64 v[150:151], v[42:43], 0, s[0:1]
	s_waitcnt lgkmcnt(0)
	v_lshlrev_b32_e32 v78, 16, v0
	v_and_b32_e32 v79, 0xffff0000, v0
	v_lshlrev_b32_e32 v0, 16, v1
	v_and_b32_e32 v1, 0xffff0000, v1
	v_lshlrev_b32_e32 v80, 16, v2
	v_and_b32_e32 v81, 0xffff0000, v2
	v_lshlrev_b32_e32 v2, 16, v3
	v_and_b32_e32 v3, 0xffff0000, v3
	s_waitcnt vmcnt(8)
	v_pk_fma_f32 v[82:83], v[66:67], v[0:1], v[32:33]
	v_pk_fma_f32 v[142:143], v[44:45], v[80:81], v[34:35]
	v_pk_fma_f32 v[144:145], v[46:47], v[2:3], v[40:41]
	v_pk_fma_f32 v[72:73], v[14:15], v[0:1], v[72:73]
	v_pk_fma_f32 v[76:77], v[10:11], v[2:3], v[76:77]
	v_pk_fma_f32 v[146:147], v[38:39], v[0:1], 0 op_sel_hi:[1,1,0]
	v_pk_fma_f32 v[148:149], v[6:7], v[2:3], 0 op_sel_hi:[1,1,0]
	global_load_dwordx4 v[0:3], v[42:43], off offset:16
	global_load_dwordx4 v[32:35], v[42:43], off
	ds_read_b128 v[40:43], v134 offset:7168
	v_pk_fma_f32 v[68:69], v[64:65], v[78:79], v[68:69]
	v_pk_fma_f32 v[70:71], v[12:13], v[78:79], v[70:71]
	v_pk_fma_f32 v[74:75], v[8:9], v[80:81], v[74:75]
	v_pk_fma_f32 v[78:79], v[36:37], v[78:79], 0 op_sel_hi:[1,1,0]
	v_pk_fma_f32 v[80:81], v[4:5], v[80:81], 0 op_sel_hi:[1,1,0]
	s_waitcnt lgkmcnt(0)
	v_lshlrev_b32_e32 v152, 16, v40
	v_and_b32_e32 v153, 0xffff0000, v40
	v_lshlrev_b32_e32 v40, 16, v41
	v_and_b32_e32 v41, 0xffff0000, v41
	v_lshlrev_b32_e32 v154, 16, v42
	v_and_b32_e32 v155, 0xffff0000, v42
	v_lshlrev_b32_e32 v42, 16, v43
	v_and_b32_e32 v43, 0xffff0000, v43
	s_waitcnt vmcnt(8)
	v_pk_fma_f32 v[68:69], v[48:49], v[152:153], v[68:69]
	v_pk_fma_f32 v[142:143], v[16:17], v[154:155], v[142:143]
	v_pk_fma_f32 v[70:71], v[64:65], v[152:153], v[70:71]
	v_pk_fma_f32 v[74:75], v[44:45], v[154:155], v[74:75]
	v_pk_fma_f32 v[78:79], v[12:13], v[152:153], v[78:79]
	v_pk_fma_f32 v[80:81], v[8:9], v[154:155], v[80:81]
	v_pk_fma_f32 v[152:153], v[36:37], v[152:153], 0 op_sel_hi:[1,1,0]
	v_pk_fma_f32 v[156:157], v[38:39], v[40:41], 0 op_sel_hi:[1,1,0]
	v_pk_fma_f32 v[154:155], v[4:5], v[154:155], 0 op_sel_hi:[1,1,0]
	v_pk_fma_f32 v[158:159], v[6:7], v[42:43], 0 op_sel_hi:[1,1,0]
	global_load_dwordx4 v[4:7], v[150:151], off offset:16
	global_load_dwordx4 v[36:39], v[150:151], off
	v_lshl_add_u64 v[150:151], v[150:151], 0, s[0:1]
	v_pk_fma_f32 v[82:83], v[50:51], v[40:41], v[82:83]
	v_pk_fma_f32 v[144:145], v[18:19], v[42:43], v[144:145]
	v_pk_fma_f32 v[72:73], v[66:67], v[40:41], v[72:73]
	v_pk_fma_f32 v[76:77], v[46:47], v[42:43], v[76:77]
	v_pk_fma_f32 v[146:147], v[14:15], v[40:41], v[146:147]
	v_pk_fma_f32 v[148:149], v[10:11], v[42:43], v[148:149]
	ds_read_b128 v[40:43], v134 offset:9216
	s_waitcnt lgkmcnt(0)
; #define LAS __attribute__((address_space(3)))
; __device__ __forceinline__ void conv_phase(LAS unsigned char* lds, const bf16_t* U, bf16_t* C, const float* wdw, const float* bdw, const float* lng, const float* lnb,
;                                            int first, int stride, int end, int tid, int wave, int lane) {
;     ...
;             for (int r = 0; r < TT / NWAVES + CW - 1; ++r) {
;                 if (r + 4 < CW) { wt[(r + 4) & 7][0] = wq[0]; wt[(r + 4) & 7][1] = wq[1]; wq += D / 4; asm volatile("" : "+v"(wq)); }
;                 const u32x4 xv = *(const LAS u32x4*)(lds + (4 * wave + r) * 2048 + p * 1024 + lane * 16);
;                 f32x2 x[4];
; #pragma unroll
;                 for (int i = 0; i < 4; ++i) x[i] = (f32x2){__uint_as_float(xv[i] << 16), __uint_as_float(xv[i] & 0xffff0000u)};
; #pragma unroll
;                 for (int j = 0; j < 4; ++j) { const int w = r - j;
;                     if (w >= 0 && w < CW) {
; #pragma unroll
;                         for (int c = 0; c < 4; ++c) { const f32x4 wv = wt[w & 7][c >> 1]; const f32x2 w2 = (c & 1) ? (f32x2){wv.z, wv.w} : (f32x2){wv.x, wv.y}; acc[p][j][c] = __builtin_elementwise_fma(w2, x[c], acc[p][j][c]); } } }
;                 asm volatile("" ::: "memory");
;             }
	v_lshlrev_b32_e32 v160, 16, v40
	v_and_b32_e32 v161, 0xffff0000, v40
	v_lshlrev_b32_e32 v40, 16, v41
	v_and_b32_e32 v41, 0xffff0000, v41
	v_lshlrev_b32_e32 v162, 16, v42
	v_and_b32_e32 v163, 0xffff0000, v42
	v_lshlrev_b32_e32 v42, 16, v43
	v_and_b32_e32 v43, 0xffff0000, v43
	s_waitcnt vmcnt(8)
	v_pk_fma_f32 v[82:83], v[54:55], v[40:41], v[82:83]
	v_pk_fma_f32 v[144:145], v[22:23], v[42:43], v[144:145]
	v_pk_fma_f32 v[72:73], v[50:51], v[40:41], v[72:73]
	v_pk_fma_f32 v[76:77], v[18:19], v[42:43], v[76:77]
	v_pk_fma_f32 v[146:147], v[66:67], v[40:41], v[146:147]
	v_pk_fma_f32 v[148:149], v[46:47], v[42:43], v[148:149]
	v_pk_fma_f32 v[156:157], v[14:15], v[40:41], v[156:157]
	v_pk_fma_f32 v[154:155], v[8:9], v[162:163], v[154:155]
	v_pk_fma_f32 v[158:159], v[10:11], v[42:43], v[158:159]
	global_load_dwordx4 v[8:11], v[150:151], off offset:16
	global_load_dwordx4 v[40:43], v[150:151], off
	v_lshl_add_u64 v[150:151], v[150:151], 0, s[0:1]
	v_pk_fma_f32 v[152:153], v[12:13], v[160:161], v[152:153]
	ds_read_b128 v[12:15], v134 offset:11264
	v_pk_fma_f32 v[68:69], v[52:53], v[160:161], v[68:69]
	v_pk_fma_f32 v[142:143], v[20:21], v[162:163], v[142:143]
	v_pk_fma_f32 v[70:71], v[48:49], v[160:161], v[70:71]
	v_pk_fma_f32 v[74:75], v[16:17], v[162:163], v[74:75]
	v_pk_fma_f32 v[78:79], v[64:65], v[160:161], v[78:79]
	v_pk_fma_f32 v[80:81], v[44:45], v[162:163], v[80:81]
	s_waitcnt lgkmcnt(0)
	v_lshlrev_b32_e32 v160, 16, v12
	v_and_b32_e32 v161, 0xffff0000, v12
	v_lshlrev_b32_e32 v12, 16, v13
	v_and_b32_e32 v13, 0xffff0000, v13
	v_lshlrev_b32_e32 v162, 16, v14
	v_and_b32_e32 v163, 0xffff0000, v14
	v_lshlrev_b32_e32 v14, 16, v15
	v_and_b32_e32 v15, 0xffff0000, v15
	s_waitcnt vmcnt(8)
	v_pk_fma_f32 v[82:83], v[58:59], v[12:13], v[82:83]
	v_pk_fma_f32 v[144:145], v[26:27], v[14:15], v[144:145]
	v_pk_fma_f32 v[72:73], v[54:55], v[12:13], v[72:73]
	v_pk_fma_f32 v[76:77], v[22:23], v[14:15], v[76:77]
	v_pk_fma_f32 v[146:147], v[50:51], v[12:13], v[146:147]
	v_pk_fma_f32 v[148:149], v[18:19], v[14:15], v[148:149]
	v_pk_fma_f32 v[156:157], v[66:67], v[12:13], v[156:157]
	v_pk_fma_f32 v[154:155], v[44:45], v[162:163], v[154:155]
	v_pk_fma_f32 v[158:159], v[46:47], v[14:15], v[158:159]
	global_load_dwordx4 v[12:15], v[150:151], off offset:16
	global_load_dwordx4 v[44:47], v[150:151], off
	v_lshl_add_u64 v[150:151], v[150:151], 0, s[0:1]
	v_pk_fma_f32 v[152:153], v[64:65], v[160:161], v[152:153]
	ds_read_b128 v[64:67], v134 offset:13312
	v_pk_fma_f32 v[68:69], v[56:57], v[160:161], v[68:69]
	v_pk_fma_f32 v[142:143], v[24:25], v[162:163], v[142:143]
	v_pk_fma_f32 v[70:71], v[52:53], v[160:161], v[70:71]
	v_pk_fma_f32 v[74:75], v[20:21], v[162:163], v[74:75]
	v_pk_fma_f32 v[78:79], v[48:49], v[160:161], v[78:79]
	v_pk_fma_f32 v[80:81], v[16:17], v[162:163], v[80:81]
	s_waitcnt lgkmcnt(0)
	v_lshlrev_b32_e32 v160, 16, v64
	v_and_b32_e32 v161, 0xffff0000, v64
	v_lshlrev_b32_e32 v64, 16, v65
	v_and_b32_e32 v65, 0xffff0000, v65
	v_lshlrev_b32_e32 v162, 16, v66
	v_and_b32_e32 v163, 0xffff0000, v66
	v_lshlrev_b32_e32 v66, 16, v67
	v_and_b32_e32 v67, 0xffff0000, v67
	v_pk_fma_f32 v[152:153], v[48:49], v[160:161], v[152:153]
	v_pk_fma_f32 v[156:157], v[50:51], v[64:65], v[156:157]
	v_pk_fma_f32 v[154:155], v[16:17], v[162:163], v[154:155]
	v_pk_fma_f32 v[158:159], v[18:19], v[66:67], v[158:159]
	global_load_dwordx4 v[16:19], v[150:151], off offset:16
	global_load_dwordx4 v[48:51], v[150:151], off
	v_lshl_add_u64 v[150:151], v[150:151], 0, s[0:1]
	s_waitcnt vmcnt(10)
	v_pk_fma_f32 v[82:83], v[62:63], v[64:65], v[82:83]
	v_pk_fma_f32 v[144:145], v[30:31], v[66:67], v[144:145]
	v_pk_fma_f32 v[72:73], v[58:59], v[64:65], v[72:73]
	v_pk_fma_f32 v[76:77], v[26:27], v[66:67], v[76:77]
	v_pk_fma_f32 v[146:147], v[54:55], v[64:65], v[146:147]
	v_pk_fma_f32 v[148:149], v[22:23], v[66:67], v[148:149]
	ds_read_b128 v[64:67], v134 offset:15360
	v_pk_fma_f32 v[68:69], v[60:61], v[160:161], v[68:69]
	v_pk_fma_f32 v[142:143], v[28:29], v[162:163], v[142:143]
	v_pk_fma_f32 v[70:71], v[56:57], v[160:161], v[70:71]
	v_pk_fma_f32 v[74:75], v[24:25], v[162:163], v[74:75]
	v_pk_fma_f32 v[78:79], v[52:53], v[160:161], v[78:79]
	v_pk_fma_f32 v[80:81], v[20:21], v[162:163], v[80:81]
	s_waitcnt lgkmcnt(0)
	v_lshlrev_b32_e32 v160, 16, v64
	v_and_b32_e32 v161, 0xffff0000, v64
	v_lshlrev_b32_e32 v64, 16, v65
	v_and_b32_e32 v65, 0xffff0000, v65
	v_lshlrev_b32_e32 v162, 16, v66
	v_and_b32_e32 v163, 0xffff0000, v66
	v_lshlrev_b32_e32 v66, 16, v67
	v_and_b32_e32 v67, 0xffff0000, v67
	v_pk_fma_f32 v[152:153], v[52:53], v[160:161], v[152:153]
	v_pk_fma_f32 v[156:157], v[54:55], v[64:65], v[156:157]
	v_pk_fma_f32 v[154:155], v[20:21], v[162:163], v[154:155]
	v_pk_fma_f32 v[158:159], v[22:23], v[66:67], v[158:159]
	global_load_dwordx4 v[20:23], v[150:151], off offset:16
	global_load_dwordx4 v[52:55], v[150:151], off
	v_lshl_add_u64 v[150:151], v[150:151], 0, s[0:1]
	s_waitcnt vmcnt(10)
	v_pk_fma_f32 v[82:83], v[34:35], v[64:65], v[82:83]
	v_pk_fma_f32 v[144:145], v[2:3], v[66:67], v[144:145]
	v_pk_fma_f32 v[72:73], v[62:63], v[64:65], v[72:73]
	v_pk_fma_f32 v[76:77], v[30:31], v[66:67], v[76:77]
	v_pk_fma_f32 v[146:147], v[58:59], v[64:65], v[146:147]
	v_pk_fma_f32 v[148:149], v[26:27], v[66:67], v[148:149]
	ds_read_b128 v[64:67], v134 offset:17408
	v_pk_fma_f32 v[68:69], v[32:33], v[160:161], v[68:69]
	v_pk_fma_f32 v[142:143], v[0:1], v[162:163], v[142:143]
	v_pk_fma_f32 v[70:71], v[60:61], v[160:161], v[70:71]
	v_pk_fma_f32 v[74:75], v[28:29], v[162:163], v[74:75]
	v_pk_fma_f32 v[78:79], v[56:57], v[160:161], v[78:79]
	v_pk_fma_f32 v[80:81], v[24:25], v[162:163], v[80:81]
	s_waitcnt lgkmcnt(0)
; #define LAS __attribute__((address_space(3)))
; __device__ __forceinline__ void conv_phase(LAS unsigned char* lds, const bf16_t* U, bf16_t* C, const float* wdw, const float* bdw, const float* lng, const float* lnb,
;                                            int first, int stride, int end, int tid, int wave, int lane) {
;     ...
;             for (int r = 0; r < TT / NWAVES + CW - 1; ++r) {
;                 if (r + 4 < CW) { wt[(r + 4) & 7][0] = wq[0]; wt[(r + 4) & 7][1] = wq[1]; wq += D / 4; asm volatile("" : "+v"(wq)); }
;                 const u32x4 xv = *(const LAS u32x4*)(lds + (4 * wave + r) * 2048 + p * 1024 + lane * 16);
;                 f32x2 x[4];
; #pragma unroll
;                 for (int i = 0; i < 4; ++i) x[i] = (f32x2){__uint_as_float(xv[i] << 16), __uint_as_float(xv[i] & 0xffff0000u)};
; #pragma unroll
;                 for (int j = 0; j < 4; ++j) { const int w = r - j;
;                     if (w >= 0 && w < CW) {
; #pragma unroll
;                         for (int c = 0; c < 4; ++c) { const f32x4 wv = wt[w & 7][c >> 1]; const f32x2 w2 = (c & 1) ? (f32x2){wv.z, wv.w} : (f32x2){wv.x, wv.y}; acc[p][j][c] = __builtin_elementwise_fma(w2, x[c], acc[p][j][c]); } } }
;                 asm volatile("" ::: "memory");
;             }
	v_lshlrev_b32_e32 v160, 16, v64
	v_and_b32_e32 v161, 0xffff0000, v64
	v_lshlrev_b32_e32 v64, 16, v65
	v_and_b32_e32 v65, 0xffff0000, v65
	v_lshlrev_b32_e32 v162, 16, v66
	v_and_b32_e32 v163, 0xffff0000, v66
	v_lshlrev_b32_e32 v66, 16, v67
	v_and_b32_e32 v67, 0xffff0000, v67
	v_pk_fma_f32 v[152:153], v[56:57], v[160:161], v[152:153]
	v_pk_fma_f32 v[156:157], v[58:59], v[64:65], v[156:157]
	v_pk_fma_f32 v[154:155], v[24:25], v[162:163], v[154:155]
	v_pk_fma_f32 v[158:159], v[26:27], v[66:67], v[158:159]
	global_load_dwordx4 v[24:27], v[150:151], off offset:16
	global_load_dwordx4 v[56:59], v[150:151], off
	v_lshl_add_u64 v[150:151], v[150:151], 0, s[0:1]
	s_waitcnt vmcnt(10)
	v_pk_fma_f32 v[82:83], v[38:39], v[64:65], v[82:83]
	v_pk_fma_f32 v[144:145], v[6:7], v[66:67], v[144:145]
	v_pk_fma_f32 v[72:73], v[34:35], v[64:65], v[72:73]
	v_pk_fma_f32 v[76:77], v[2:3], v[66:67], v[76:77]
	v_pk_fma_f32 v[146:147], v[62:63], v[64:65], v[146:147]
	v_pk_fma_f32 v[148:149], v[30:31], v[66:67], v[148:149]
	ds_read_b128 v[64:67], v134 offset:19456
	v_pk_fma_f32 v[68:69], v[36:37], v[160:161], v[68:69]
	v_pk_fma_f32 v[142:143], v[4:5], v[162:163], v[142:143]
	v_pk_fma_f32 v[70:71], v[32:33], v[160:161], v[70:71]
	v_pk_fma_f32 v[74:75], v[0:1], v[162:163], v[74:75]
	v_pk_fma_f32 v[78:79], v[60:61], v[160:161], v[78:79]
	v_pk_fma_f32 v[80:81], v[28:29], v[162:163], v[80:81]
	s_waitcnt lgkmcnt(0)
	v_lshlrev_b32_e32 v160, 16, v64
	v_and_b32_e32 v161, 0xffff0000, v64
	v_lshlrev_b32_e32 v64, 16, v65
	v_and_b32_e32 v65, 0xffff0000, v65
	v_lshlrev_b32_e32 v162, 16, v66
	v_and_b32_e32 v163, 0xffff0000, v66
	v_lshlrev_b32_e32 v66, 16, v67
	v_and_b32_e32 v67, 0xffff0000, v67
	v_pk_fma_f32 v[152:153], v[60:61], v[160:161], v[152:153]
	v_pk_fma_f32 v[156:157], v[62:63], v[64:65], v[156:157]
	v_pk_fma_f32 v[154:155], v[28:29], v[162:163], v[154:155]
	v_pk_fma_f32 v[158:159], v[30:31], v[66:67], v[158:159]
	global_load_dwordx4 v[28:31], v[150:151], off offset:16
	global_load_dwordx4 v[60:63], v[150:151], off
	v_lshl_add_u64 v[150:151], v[150:151], 0, s[0:1]
	s_waitcnt vmcnt(10)
	v_pk_fma_f32 v[82:83], v[42:43], v[64:65], v[82:83]
	v_pk_fma_f32 v[144:145], v[10:11], v[66:67], v[144:145]
	v_pk_fma_f32 v[72:73], v[38:39], v[64:65], v[72:73]
	v_pk_fma_f32 v[76:77], v[6:7], v[66:67], v[76:77]
	v_pk_fma_f32 v[146:147], v[34:35], v[64:65], v[146:147]
	v_pk_fma_f32 v[148:149], v[2:3], v[66:67], v[148:149]
	ds_read_b128 v[64:67], v134 offset:21504
	v_pk_fma_f32 v[68:69], v[40:41], v[160:161], v[68:69]
	v_pk_fma_f32 v[142:143], v[8:9], v[162:163], v[142:143]
	v_pk_fma_f32 v[70:71], v[36:37], v[160:161], v[70:71]
	v_pk_fma_f32 v[74:75], v[4:5], v[162:163], v[74:75]
	v_pk_fma_f32 v[78:79], v[32:33], v[160:161], v[78:79]
	v_pk_fma_f32 v[80:81], v[0:1], v[162:163], v[80:81]
	s_waitcnt lgkmcnt(0)
	v_lshlrev_b32_e32 v160, 16, v64
	v_and_b32_e32 v161, 0xffff0000, v64
	v_lshlrev_b32_e32 v64, 16, v65
	v_and_b32_e32 v65, 0xffff0000, v65
	v_lshlrev_b32_e32 v162, 16, v66
	v_and_b32_e32 v163, 0xffff0000, v66
	v_lshlrev_b32_e32 v66, 16, v67
	v_and_b32_e32 v67, 0xffff0000, v67
	v_pk_fma_f32 v[152:153], v[32:33], v[160:161], v[152:153]
	v_pk_fma_f32 v[156:157], v[34:35], v[64:65], v[156:157]
	v_pk_fma_f32 v[154:155], v[0:1], v[162:163], v[154:155]
	v_pk_fma_f32 v[158:159], v[2:3], v[66:67], v[158:159]
	global_load_dwordx4 v[0:3], v[150:151], off offset:16
	global_load_dwordx4 v[32:35], v[150:151], off
	v_lshl_add_u64 v[150:151], v[150:151], 0, s[0:1]
	s_waitcnt vmcnt(10)
	v_pk_fma_f32 v[82:83], v[46:47], v[64:65], v[82:83]
	v_pk_fma_f32 v[144:145], v[14:15], v[66:67], v[144:145]
	v_pk_fma_f32 v[72:73], v[42:43], v[64:65], v[72:73]
	v_pk_fma_f32 v[76:77], v[10:11], v[66:67], v[76:77]
	v_pk_fma_f32 v[146:147], v[38:39], v[64:65], v[146:147]
	v_pk_fma_f32 v[148:149], v[6:7], v[66:67], v[148:149]
	ds_read_b128 v[64:67], v134 offset:23552
	v_pk_fma_f32 v[68:69], v[44:45], v[160:161], v[68:69]
	v_pk_fma_f32 v[142:143], v[12:13], v[162:163], v[142:143]
	v_pk_fma_f32 v[70:71], v[40:41], v[160:161], v[70:71]
	v_pk_fma_f32 v[74:75], v[8:9], v[162:163], v[74:75]
	v_pk_fma_f32 v[78:79], v[36:37], v[160:161], v[78:79]
	v_pk_fma_f32 v[80:81], v[4:5], v[162:163], v[80:81]
	s_waitcnt lgkmcnt(0)
	v_lshlrev_b32_e32 v160, 16, v64
	v_and_b32_e32 v161, 0xffff0000, v64
	v_lshlrev_b32_e32 v64, 16, v65
	v_and_b32_e32 v65, 0xffff0000, v65
	v_lshlrev_b32_e32 v162, 16, v66
	v_and_b32_e32 v163, 0xffff0000, v66
	v_lshlrev_b32_e32 v66, 16, v67
	v_and_b32_e32 v67, 0xffff0000, v67
	v_pk_fma_f32 v[152:153], v[36:37], v[160:161], v[152:153]
	v_pk_fma_f32 v[156:157], v[38:39], v[64:65], v[156:157]
	v_pk_fma_f32 v[154:155], v[4:5], v[162:163], v[154:155]
	v_pk_fma_f32 v[158:159], v[6:7], v[66:67], v[158:159]
	global_load_dwordx4 v[4:7], v[150:151], off offset:16
	global_load_dwordx4 v[36:39], v[150:151], off
	v_lshl_add_u64 v[150:151], v[150:151], 0, s[0:1]
	s_waitcnt vmcnt(10)
	v_pk_fma_f32 v[82:83], v[50:51], v[64:65], v[82:83]
	v_pk_fma_f32 v[144:145], v[18:19], v[66:67], v[144:145]
	v_pk_fma_f32 v[72:73], v[46:47], v[64:65], v[72:73]
	v_pk_fma_f32 v[76:77], v[14:15], v[66:67], v[76:77]
	v_pk_fma_f32 v[146:147], v[42:43], v[64:65], v[146:147]
	v_pk_fma_f32 v[148:149], v[10:11], v[66:67], v[148:149]
	ds_read_b128 v[64:67], v134 offset:25600
	v_pk_fma_f32 v[68:69], v[48:49], v[160:161], v[68:69]
	v_pk_fma_f32 v[142:143], v[16:17], v[162:163], v[142:143]
	v_pk_fma_f32 v[70:71], v[44:45], v[160:161], v[70:71]
	v_pk_fma_f32 v[74:75], v[12:13], v[162:163], v[74:75]
	v_pk_fma_f32 v[78:79], v[40:41], v[160:161], v[78:79]
	v_pk_fma_f32 v[80:81], v[8:9], v[162:163], v[80:81]
	s_waitcnt lgkmcnt(0)
; #define LAS __attribute__((address_space(3)))
; __device__ __forceinline__ void conv_phase(LAS unsigned char* lds, const bf16_t* U, bf16_t* C, const float* wdw, const float* bdw, const float* lng, const float* lnb,
;                                            int first, int stride, int end, int tid, int wave, int lane) {
;     ...
;             for (int r = 0; r < TT / NWAVES + CW - 1; ++r) {
;                 if (r + 4 < CW) { wt[(r + 4) & 7][0] = wq[0]; wt[(r + 4) & 7][1] = wq[1]; wq += D / 4; asm volatile("" : "+v"(wq)); }
;                 const u32x4 xv = *(const LAS u32x4*)(lds + (4 * wave + r) * 2048 + p * 1024 + lane * 16);
;                 f32x2 x[4];
; #pragma unroll
;                 for (int i = 0; i < 4; ++i) x[i] = (f32x2){__uint_as_float(xv[i] << 16), __uint_as_float(xv[i] & 0xffff0000u)};
; #pragma unroll
;                 for (int j = 0; j < 4; ++j) { const int w = r - j;
;                     if (w >= 0 && w < CW) {
; #pragma unroll
;                         for (int c = 0; c < 4; ++c) { const f32x4 wv = wt[w & 7][c >> 1]; const f32x2 w2 = (c & 1) ? (f32x2){wv.z, wv.w} : (f32x2){wv.x, wv.y}; acc[p][j][c] = __builtin_elementwise_fma(w2, x[c], acc[p][j][c]); } } }
;                 asm volatile("" ::: "memory");
;             }
	v_lshlrev_b32_e32 v160, 16, v64
	v_and_b32_e32 v161, 0xffff0000, v64
	v_lshlrev_b32_e32 v64, 16, v65
	v_and_b32_e32 v65, 0xffff0000, v65
	v_lshlrev_b32_e32 v162, 16, v66
	v_and_b32_e32 v163, 0xffff0000, v66
	v_lshlrev_b32_e32 v66, 16, v67
	v_and_b32_e32 v67, 0xffff0000, v67
	v_pk_fma_f32 v[152:153], v[40:41], v[160:161], v[152:153]
	v_pk_fma_f32 v[156:157], v[42:43], v[64:65], v[156:157]
	v_pk_fma_f32 v[154:155], v[8:9], v[162:163], v[154:155]
	v_pk_fma_f32 v[158:159], v[10:11], v[66:67], v[158:159]
	global_load_dwordx4 v[8:11], v[150:151], off offset:16
	global_load_dwordx4 v[40:43], v[150:151], off
	v_lshl_add_u64 v[150:151], v[150:151], 0, s[0:1]
	s_waitcnt vmcnt(10)
	v_pk_fma_f32 v[82:83], v[54:55], v[64:65], v[82:83]
	v_pk_fma_f32 v[144:145], v[22:23], v[66:67], v[144:145]
	v_pk_fma_f32 v[72:73], v[50:51], v[64:65], v[72:73]
	v_pk_fma_f32 v[76:77], v[18:19], v[66:67], v[76:77]
	v_pk_fma_f32 v[146:147], v[46:47], v[64:65], v[146:147]
	v_pk_fma_f32 v[148:149], v[14:15], v[66:67], v[148:149]
	ds_read_b128 v[64:67], v134 offset:27648
	v_pk_fma_f32 v[68:69], v[52:53], v[160:161], v[68:69]
	v_pk_fma_f32 v[142:143], v[20:21], v[162:163], v[142:143]
	v_pk_fma_f32 v[70:71], v[48:49], v[160:161], v[70:71]
	v_pk_fma_f32 v[74:75], v[16:17], v[162:163], v[74:75]
	v_pk_fma_f32 v[78:79], v[44:45], v[160:161], v[78:79]
	v_pk_fma_f32 v[80:81], v[12:13], v[162:163], v[80:81]
	s_waitcnt lgkmcnt(0)
	v_lshlrev_b32_e32 v160, 16, v64
	v_and_b32_e32 v161, 0xffff0000, v64
	v_lshlrev_b32_e32 v64, 16, v65
	v_and_b32_e32 v65, 0xffff0000, v65
	v_lshlrev_b32_e32 v162, 16, v66
	v_and_b32_e32 v163, 0xffff0000, v66
	v_lshlrev_b32_e32 v66, 16, v67
	v_and_b32_e32 v67, 0xffff0000, v67
	v_pk_fma_f32 v[152:153], v[44:45], v[160:161], v[152:153]
	v_pk_fma_f32 v[156:157], v[46:47], v[64:65], v[156:157]
	v_pk_fma_f32 v[154:155], v[12:13], v[162:163], v[154:155]
	v_pk_fma_f32 v[158:159], v[14:15], v[66:67], v[158:159]
	global_load_dwordx4 v[12:15], v[150:151], off offset:16
	global_load_dwordx4 v[44:47], v[150:151], off
	v_lshl_add_u64 v[150:151], v[150:151], 0, s[0:1]
	s_waitcnt vmcnt(10)
	v_pk_fma_f32 v[82:83], v[58:59], v[64:65], v[82:83]
	v_pk_fma_f32 v[144:145], v[26:27], v[66:67], v[144:145]
	v_pk_fma_f32 v[72:73], v[54:55], v[64:65], v[72:73]
	v_pk_fma_f32 v[76:77], v[22:23], v[66:67], v[76:77]
	v_pk_fma_f32 v[146:147], v[50:51], v[64:65], v[146:147]
	v_pk_fma_f32 v[148:149], v[18:19], v[66:67], v[148:149]
	ds_read_b128 v[64:67], v134 offset:29696
	v_pk_fma_f32 v[68:69], v[56:57], v[160:161], v[68:69]
	v_pk_fma_f32 v[142:143], v[24:25], v[162:163], v[142:143]
	v_pk_fma_f32 v[70:71], v[52:53], v[160:161], v[70:71]
	v_pk_fma_f32 v[74:75], v[20:21], v[162:163], v[74:75]
	v_pk_fma_f32 v[78:79], v[48:49], v[160:161], v[78:79]
	v_pk_fma_f32 v[80:81], v[16:17], v[162:163], v[80:81]
	s_waitcnt lgkmcnt(0)
	v_lshlrev_b32_e32 v160, 16, v64
	v_and_b32_e32 v161, 0xffff0000, v64
	v_lshlrev_b32_e32 v64, 16, v65
	v_and_b32_e32 v65, 0xffff0000, v65
	v_lshlrev_b32_e32 v162, 16, v66
	v_and_b32_e32 v163, 0xffff0000, v66
	v_lshlrev_b32_e32 v66, 16, v67
	v_and_b32_e32 v67, 0xffff0000, v67
	v_pk_fma_f32 v[152:153], v[48:49], v[160:161], v[152:153]
	v_pk_fma_f32 v[156:157], v[50:51], v[64:65], v[156:157]
	v_pk_fma_f32 v[154:155], v[16:17], v[162:163], v[154:155]
	v_pk_fma_f32 v[158:159], v[18:19], v[66:67], v[158:159]
	global_load_dwordx4 v[16:19], v[150:151], off offset:16
	global_load_dwordx4 v[48:51], v[150:151], off
	v_lshl_add_u64 v[150:151], v[150:151], 0, s[0:1]
	s_waitcnt vmcnt(10)
	v_pk_fma_f32 v[82:83], v[62:63], v[64:65], v[82:83]
	v_pk_fma_f32 v[144:145], v[30:31], v[66:67], v[144:145]
	v_pk_fma_f32 v[72:73], v[58:59], v[64:65], v[72:73]
	v_pk_fma_f32 v[76:77], v[26:27], v[66:67], v[76:77]
	v_pk_fma_f32 v[146:147], v[54:55], v[64:65], v[146:147]
	v_pk_fma_f32 v[148:149], v[22:23], v[66:67], v[148:149]
	ds_read_b128 v[64:67], v134 offset:31744
	v_pk_fma_f32 v[68:69], v[60:61], v[160:161], v[68:69]
	v_pk_fma_f32 v[142:143], v[28:29], v[162:163], v[142:143]
	v_pk_fma_f32 v[70:71], v[56:57], v[160:161], v[70:71]
	v_pk_fma_f32 v[74:75], v[24:25], v[162:163], v[74:75]
	v_pk_fma_f32 v[78:79], v[52:53], v[160:161], v[78:79]
	v_pk_fma_f32 v[80:81], v[20:21], v[162:163], v[80:81]
	s_waitcnt lgkmcnt(0)
	v_lshlrev_b32_e32 v160, 16, v64
	v_and_b32_e32 v161, 0xffff0000, v64
	v_lshlrev_b32_e32 v64, 16, v65
	v_and_b32_e32 v65, 0xffff0000, v65
	v_lshlrev_b32_e32 v162, 16, v66
	v_and_b32_e32 v163, 0xffff0000, v66
	v_lshlrev_b32_e32 v66, 16, v67
	v_and_b32_e32 v67, 0xffff0000, v67
	v_pk_fma_f32 v[152:153], v[52:53], v[160:161], v[152:153]
	v_pk_fma_f32 v[156:157], v[54:55], v[64:65], v[156:157]
	v_pk_fma_f32 v[154:155], v[20:21], v[162:163], v[154:155]
	v_pk_fma_f32 v[158:159], v[22:23], v[66:67], v[158:159]
	global_load_dwordx4 v[20:23], v[150:151], off offset:16
	global_load_dwordx4 v[52:55], v[150:151], off
	v_lshl_add_u64 v[150:151], v[150:151], 0, s[0:1]
	s_waitcnt vmcnt(10)
	v_pk_fma_f32 v[82:83], v[34:35], v[64:65], v[82:83]
	v_pk_fma_f32 v[144:145], v[2:3], v[66:67], v[144:145]
	v_pk_fma_f32 v[72:73], v[62:63], v[64:65], v[72:73]
	v_pk_fma_f32 v[76:77], v[30:31], v[66:67], v[76:77]
	v_pk_fma_f32 v[146:147], v[58:59], v[64:65], v[146:147]
	v_pk_fma_f32 v[148:149], v[26:27], v[66:67], v[148:149]
	ds_read_b128 v[64:67], v134 offset:33792
	v_pk_fma_f32 v[68:69], v[32:33], v[160:161], v[68:69]
	v_pk_fma_f32 v[142:143], v[0:1], v[162:163], v[142:143]
	v_pk_fma_f32 v[70:71], v[60:61], v[160:161], v[70:71]
	v_pk_fma_f32 v[74:75], v[28:29], v[162:163], v[74:75]
	v_pk_fma_f32 v[78:79], v[56:57], v[160:161], v[78:79]
	v_pk_fma_f32 v[80:81], v[24:25], v[162:163], v[80:81]
	s_waitcnt lgkmcnt(0)
; #define LAS __attribute__((address_space(3)))
; __device__ __forceinline__ void conv_phase(LAS unsigned char* lds, const bf16_t* U, bf16_t* C, const float* wdw, const float* bdw, const float* lng, const float* lnb,
;                                            int first, int stride, int end, int tid, int wave, int lane) {
;     ...
;             for (int r = 0; r < TT / NWAVES + CW - 1; ++r) {
;                 if (r + 4 < CW) { wt[(r + 4) & 7][0] = wq[0]; wt[(r + 4) & 7][1] = wq[1]; wq += D / 4; asm volatile("" : "+v"(wq)); }
;                 const u32x4 xv = *(const LAS u32x4*)(lds + (4 * wave + r) * 2048 + p * 1024 + lane * 16);
;                 f32x2 x[4];
; #pragma unroll
;                 for (int i = 0; i < 4; ++i) x[i] = (f32x2){__uint_as_float(xv[i] << 16), __uint_as_float(xv[i] & 0xffff0000u)};
; #pragma unroll
;                 for (int j = 0; j < 4; ++j) { const int w = r - j;
;                     if (w >= 0 && w < CW) {
; #pragma unroll
;                         for (int c = 0; c < 4; ++c) { const f32x4 wv = wt[w & 7][c >> 1]; const f32x2 w2 = (c & 1) ? (f32x2){wv.z, wv.w} : (f32x2){wv.x, wv.y}; acc[p][j][c] = __builtin_elementwise_fma(w2, x[c], acc[p][j][c]); } } }
;                 asm volatile("" ::: "memory");
;             }
	v_lshlrev_b32_e32 v160, 16, v64
	v_and_b32_e32 v161, 0xffff0000, v64
	v_lshlrev_b32_e32 v64, 16, v65
	v_and_b32_e32 v65, 0xffff0000, v65
	v_lshlrev_b32_e32 v162, 16, v66
	v_and_b32_e32 v163, 0xffff0000, v66
	v_lshlrev_b32_e32 v66, 16, v67
	v_and_b32_e32 v67, 0xffff0000, v67
	v_pk_fma_f32 v[152:153], v[56:57], v[160:161], v[152:153]
	v_pk_fma_f32 v[156:157], v[58:59], v[64:65], v[156:157]
	v_pk_fma_f32 v[154:155], v[24:25], v[162:163], v[154:155]
	v_pk_fma_f32 v[158:159], v[26:27], v[66:67], v[158:159]
	global_load_dwordx4 v[24:27], v[150:151], off offset:16
	global_load_dwordx4 v[56:59], v[150:151], off
	v_lshl_add_u64 v[150:151], v[150:151], 0, s[0:1]
	s_waitcnt vmcnt(10)
	v_pk_fma_f32 v[82:83], v[38:39], v[64:65], v[82:83]
	v_pk_fma_f32 v[144:145], v[6:7], v[66:67], v[144:145]
	v_pk_fma_f32 v[72:73], v[34:35], v[64:65], v[72:73]
	v_pk_fma_f32 v[76:77], v[2:3], v[66:67], v[76:77]
	v_pk_fma_f32 v[146:147], v[62:63], v[64:65], v[146:147]
	v_pk_fma_f32 v[148:149], v[30:31], v[66:67], v[148:149]
	ds_read_b128 v[64:67], v134 offset:35840
	v_pk_fma_f32 v[68:69], v[36:37], v[160:161], v[68:69]
	v_pk_fma_f32 v[142:143], v[4:5], v[162:163], v[142:143]
	v_pk_fma_f32 v[70:71], v[32:33], v[160:161], v[70:71]
	v_pk_fma_f32 v[74:75], v[0:1], v[162:163], v[74:75]
	v_pk_fma_f32 v[78:79], v[60:61], v[160:161], v[78:79]
	v_pk_fma_f32 v[80:81], v[28:29], v[162:163], v[80:81]
	s_waitcnt lgkmcnt(0)
	v_lshlrev_b32_e32 v160, 16, v64
	v_and_b32_e32 v161, 0xffff0000, v64
	v_lshlrev_b32_e32 v64, 16, v65
	v_and_b32_e32 v65, 0xffff0000, v65
	v_lshlrev_b32_e32 v162, 16, v66
	v_and_b32_e32 v163, 0xffff0000, v66
	v_lshlrev_b32_e32 v66, 16, v67
	v_and_b32_e32 v67, 0xffff0000, v67
	v_pk_fma_f32 v[152:153], v[60:61], v[160:161], v[152:153]
	v_pk_fma_f32 v[156:157], v[62:63], v[64:65], v[156:157]
	v_pk_fma_f32 v[154:155], v[28:29], v[162:163], v[154:155]
	v_pk_fma_f32 v[158:159], v[30:31], v[66:67], v[158:159]
	global_load_dwordx4 v[28:31], v[150:151], off offset:16
	global_load_dwordx4 v[60:63], v[150:151], off
	v_lshl_add_u64 v[150:151], v[150:151], 0, s[0:1]
	s_waitcnt vmcnt(10)
	v_pk_fma_f32 v[82:83], v[42:43], v[64:65], v[82:83]
	v_pk_fma_f32 v[144:145], v[10:11], v[66:67], v[144:145]
	v_pk_fma_f32 v[72:73], v[38:39], v[64:65], v[72:73]
	v_pk_fma_f32 v[76:77], v[6:7], v[66:67], v[76:77]
	v_pk_fma_f32 v[146:147], v[34:35], v[64:65], v[146:147]
	v_pk_fma_f32 v[148:149], v[2:3], v[66:67], v[148:149]
	ds_read_b128 v[64:67], v134 offset:37888
	v_pk_fma_f32 v[68:69], v[40:41], v[160:161], v[68:69]
	v_pk_fma_f32 v[142:143], v[8:9], v[162:163], v[142:143]
	v_pk_fma_f32 v[70:71], v[36:37], v[160:161], v[70:71]
	v_pk_fma_f32 v[74:75], v[4:5], v[162:163], v[74:75]
	v_pk_fma_f32 v[78:79], v[32:33], v[160:161], v[78:79]
	v_pk_fma_f32 v[80:81], v[0:1], v[162:163], v[80:81]
	s_waitcnt lgkmcnt(0)
	v_lshlrev_b32_e32 v160, 16, v64
	v_and_b32_e32 v161, 0xffff0000, v64
	v_lshlrev_b32_e32 v64, 16, v65
	v_and_b32_e32 v65, 0xffff0000, v65
	v_lshlrev_b32_e32 v162, 16, v66
	v_and_b32_e32 v163, 0xffff0000, v66
	v_lshlrev_b32_e32 v66, 16, v67
	v_and_b32_e32 v67, 0xffff0000, v67
	s_waitcnt vmcnt(8)
	v_pk_fma_f32 v[82:83], v[46:47], v[64:65], v[82:83]
	v_pk_fma_f32 v[144:145], v[14:15], v[66:67], v[144:145]
	v_pk_fma_f32 v[72:73], v[42:43], v[64:65], v[72:73]
	v_pk_fma_f32 v[76:77], v[10:11], v[66:67], v[76:77]
	v_pk_fma_f32 v[146:147], v[38:39], v[64:65], v[146:147]
	v_pk_fma_f32 v[148:149], v[6:7], v[66:67], v[148:149]
	v_pk_fma_f32 v[152:153], v[32:33], v[160:161], v[152:153]
	v_pk_fma_f32 v[156:157], v[34:35], v[64:65], v[156:157]
	v_pk_fma_f32 v[158:159], v[2:3], v[66:67], v[158:159]
	global_load_dwordx4 v[32:35], v[150:151], off offset:16
	global_load_dwordx4 v[64:67], v[150:151], off
	v_lshl_add_u64 v[150:151], v[150:151], 0, s[0:1]
	v_pk_fma_f32 v[154:155], v[0:1], v[162:163], v[154:155]
	ds_read_b128 v[0:3], v134 offset:39936
	v_pk_fma_f32 v[68:69], v[44:45], v[160:161], v[68:69]
	v_pk_fma_f32 v[70:71], v[40:41], v[160:161], v[70:71]
	v_pk_fma_f32 v[78:79], v[36:37], v[160:161], v[78:79]
	s_waitcnt lgkmcnt(0)
	v_lshlrev_b32_e32 v160, 16, v0
	v_and_b32_e32 v161, 0xffff0000, v0
	v_lshlrev_b32_e32 v0, 16, v1
	v_and_b32_e32 v1, 0xffff0000, v1
	v_pk_fma_f32 v[142:143], v[12:13], v[162:163], v[142:143]
	v_pk_fma_f32 v[74:75], v[8:9], v[162:163], v[74:75]
	v_pk_fma_f32 v[80:81], v[4:5], v[162:163], v[80:81]
	v_lshlrev_b32_e32 v162, 16, v2
	v_and_b32_e32 v163, 0xffff0000, v2
	v_lshlrev_b32_e32 v2, 16, v3
	v_and_b32_e32 v3, 0xffff0000, v3
	s_waitcnt vmcnt(8)
	v_pk_fma_f32 v[164:165], v[48:49], v[160:161], v[68:69]
	v_pk_fma_f32 v[166:167], v[44:45], v[160:161], v[70:71]
	v_pk_fma_f32 v[152:153], v[36:37], v[160:161], v[152:153]
	v_pk_fma_f32 v[156:157], v[38:39], v[0:1], v[156:157]
	global_load_dwordx4 v[36:39], v[150:151], off offset:16
	global_load_dwordx4 v[68:71], v[150:151], off
	v_lshl_add_u64 v[150:151], v[150:151], 0, s[0:1]
	v_pk_fma_f32 v[82:83], v[50:51], v[0:1], v[82:83]
	v_pk_fma_f32 v[144:145], v[18:19], v[2:3], v[144:145]
	v_pk_fma_f32 v[72:73], v[46:47], v[0:1], v[72:73]
	v_pk_fma_f32 v[76:77], v[14:15], v[2:3], v[76:77]
	v_pk_fma_f32 v[146:147], v[42:43], v[0:1], v[146:147]
	v_pk_fma_f32 v[148:149], v[10:11], v[2:3], v[148:149]
	v_pk_fma_f32 v[6:7], v[6:7], v[2:3], v[158:159]
	ds_read_b128 v[0:3], v134 offset:41984
	v_pk_fma_f32 v[74:75], v[12:13], v[162:163], v[74:75]
	v_pk_fma_f32 v[78:79], v[40:41], v[160:161], v[78:79]
	v_pk_fma_f32 v[4:5], v[4:5], v[162:163], v[154:155]
	s_waitcnt lgkmcnt(0)
	v_lshlrev_b32_e32 v154, 16, v0
	v_and_b32_e32 v155, 0xffff0000, v0
	v_lshlrev_b32_e32 v0, 16, v1
	v_and_b32_e32 v1, 0xffff0000, v1
	v_lshlrev_b32_e32 v158, 16, v2
	v_and_b32_e32 v159, 0xffff0000, v2
	v_pk_fma_f32 v[142:143], v[16:17], v[162:163], v[142:143]
	v_pk_fma_f32 v[80:81], v[8:9], v[162:163], v[80:81]
	s_waitcnt vmcnt(8)
; #define LAS __attribute__((address_space(3)))
; __device__ __forceinline__ void conv_phase(LAS unsigned char* lds, const bf16_t* U, bf16_t* C, const float* wdw, const float* bdw, const float* lng, const float* lnb,
;                                            int first, int stride, int end, int tid, int wave, int lane) {
;     ...
;             for (int r = 0; r < TT / NWAVES + CW - 1; ++r) {
;                 if (r + 4 < CW) { wt[(r + 4) & 7][0] = wq[0]; wt[(r + 4) & 7][1] = wq[1]; wq += D / 4; asm volatile("" : "+v"(wq)); }
;                 const u32x4 xv = *(const LAS u32x4*)(lds + (4 * wave + r) * 2048 + p * 1024 + lane * 16);
;                 f32x2 x[4];
; #pragma unroll
;                 for (int i = 0; i < 4; ++i) x[i] = (f32x2){__uint_as_float(xv[i] << 16), __uint_as_float(xv[i] & 0xffff0000u)};
; #pragma unroll
;                 for (int j = 0; j < 4; ++j) { const int w = r - j;
;                     if (w >= 0 && w < CW) {
; #pragma unroll
;                         for (int c = 0; c < 4; ++c) { const f32x4 wv = wt[w & 7][c >> 1]; const f32x2 w2 = (c & 1) ? (f32x2){wv.z, wv.w} : (f32x2){wv.x, wv.y}; acc[p][j][c] = __builtin_elementwise_fma(w2, x[c], acc[p][j][c]); } } }
;                 asm volatile("" ::: "memory");
;             }
	v_pk_fma_f32 v[160:161], v[52:53], v[154:155], v[164:165]
	v_pk_fma_f32 v[162:163], v[48:49], v[154:155], v[166:167]
	v_pk_fma_f32 v[164:165], v[50:51], v[0:1], v[72:73]
	v_pk_fma_f32 v[166:167], v[16:17], v[158:159], v[74:75]
	v_pk_fma_f32 v[78:79], v[44:45], v[154:155], v[78:79]
	v_pk_fma_f32 v[152:153], v[40:41], v[154:155], v[152:153]
	v_pk_fma_f32 v[154:155], v[42:43], v[0:1], v[156:157]
	global_load_dwordx4 v[40:43], v[150:151], off offset:16
	global_load_dwordx4 v[72:75], v[150:151], off
	v_lshlrev_b32_e32 v2, 16, v3
	v_and_b32_e32 v3, 0xffff0000, v3
	v_pk_fma_f32 v[4:5], v[8:9], v[158:159], v[4:5]
	v_lshl_add_u64 v[8:9], v[150:151], 0, s[0:1]
	v_pk_fma_f32 v[82:83], v[54:55], v[0:1], v[82:83]
	v_pk_fma_f32 v[144:145], v[22:23], v[2:3], v[144:145]
	v_pk_fma_f32 v[76:77], v[18:19], v[2:3], v[76:77]
	v_pk_fma_f32 v[146:147], v[46:47], v[0:1], v[146:147]
	v_pk_fma_f32 v[148:149], v[14:15], v[2:3], v[148:149]
	v_pk_fma_f32 v[6:7], v[10:11], v[2:3], v[6:7]
	ds_read_b128 v[0:3], v134 offset:44032
	v_pk_fma_f32 v[142:143], v[20:21], v[158:159], v[142:143]
	v_pk_fma_f32 v[80:81], v[12:13], v[158:159], v[80:81]
	s_waitcnt lgkmcnt(0)
	v_lshlrev_b32_e32 v10, 16, v0
	v_and_b32_e32 v11, 0xffff0000, v0
	v_lshlrev_b32_e32 v0, 16, v1
	v_and_b32_e32 v1, 0xffff0000, v1
	v_lshlrev_b32_e32 v150, 16, v2
	v_and_b32_e32 v151, 0xffff0000, v2
	v_lshlrev_b32_e32 v2, 16, v3
	v_and_b32_e32 v3, 0xffff0000, v3
	s_waitcnt vmcnt(8)
	v_pk_fma_f32 v[156:157], v[56:57], v[10:11], v[160:161]
	v_pk_fma_f32 v[158:159], v[52:53], v[10:11], v[162:163]
	v_pk_fma_f32 v[160:161], v[54:55], v[0:1], v[164:165]
	v_pk_fma_f32 v[162:163], v[20:21], v[150:151], v[166:167]
	v_pk_fma_f32 v[164:165], v[22:23], v[2:3], v[76:77]
	v_pk_fma_f32 v[166:167], v[48:49], v[10:11], v[78:79]
	v_pk_fma_f32 v[10:11], v[44:45], v[10:11], v[152:153]
	v_pk_fma_f32 v[152:153], v[46:47], v[0:1], v[154:155]
	global_load_dwordx4 v[44:47], v[8:9], off offset:16
	global_load_dwordx4 v[76:79], v[8:9], off
	v_lshl_add_u64 v[8:9], v[8:9], 0, s[0:1]
	v_pk_fma_f32 v[82:83], v[58:59], v[0:1], v[82:83]
	v_pk_fma_f32 v[144:145], v[26:27], v[2:3], v[144:145]
	v_pk_fma_f32 v[146:147], v[50:51], v[0:1], v[146:147]
	v_pk_fma_f32 v[148:149], v[18:19], v[2:3], v[148:149]
	v_pk_fma_f32 v[6:7], v[14:15], v[2:3], v[6:7]
	ds_read_b128 v[0:3], v134 offset:46080
	v_pk_fma_f32 v[80:81], v[16:17], v[150:151], v[80:81]
	v_pk_fma_f32 v[4:5], v[12:13], v[150:151], v[4:5]
	v_pk_fma_f32 v[142:143], v[24:25], v[150:151], v[142:143]
	s_waitcnt lgkmcnt(0)
	v_lshlrev_b32_e32 v12, 16, v0
	v_and_b32_e32 v13, 0xffff0000, v0
	v_lshlrev_b32_e32 v0, 16, v1
	v_and_b32_e32 v1, 0xffff0000, v1
	v_lshlrev_b32_e32 v14, 16, v2
	v_and_b32_e32 v15, 0xffff0000, v2
	v_lshlrev_b32_e32 v2, 16, v3
	v_and_b32_e32 v3, 0xffff0000, v3
	s_waitcnt vmcnt(8)
	v_pk_fma_f32 v[150:151], v[60:61], v[12:13], v[156:157]
	v_pk_fma_f32 v[154:155], v[62:63], v[0:1], v[82:83]
	v_pk_fma_f32 v[156:157], v[56:57], v[12:13], v[158:159]
	v_pk_fma_f32 v[158:159], v[58:59], v[0:1], v[160:161]
	v_pk_fma_f32 v[160:161], v[24:25], v[14:15], v[162:163]
	v_pk_fma_f32 v[162:163], v[26:27], v[2:3], v[164:165]
	v_pk_fma_f32 v[164:165], v[52:53], v[12:13], v[166:167]
	v_pk_fma_f32 v[166:167], v[20:21], v[14:15], v[80:81]
	v_pk_fma_f32 v[10:11], v[48:49], v[12:13], v[10:11]
	v_pk_fma_f32 v[12:13], v[50:51], v[0:1], v[152:153]
	global_load_dwordx4 v[48:51], v[8:9], off offset:16
	global_load_dwordx4 v[80:83], v[8:9], off
	v_lshl_add_u64 v[8:9], v[8:9], 0, s[0:1]
	v_pk_fma_f32 v[144:145], v[30:31], v[2:3], v[144:145]
	v_pk_fma_f32 v[146:147], v[54:55], v[0:1], v[146:147]
	v_pk_fma_f32 v[148:149], v[22:23], v[2:3], v[148:149]
	v_pk_fma_f32 v[6:7], v[18:19], v[2:3], v[6:7]
	ds_read_b128 v[0:3], v134 offset:48128
	v_pk_fma_f32 v[142:143], v[28:29], v[14:15], v[142:143]
	v_pk_fma_f32 v[4:5], v[16:17], v[14:15], v[4:5]
	s_waitcnt lgkmcnt(0)
	v_lshlrev_b32_e32 v14, 16, v0
	v_and_b32_e32 v15, 0xffff0000, v0
	v_lshlrev_b32_e32 v0, 16, v1
	v_and_b32_e32 v1, 0xffff0000, v1
	v_lshlrev_b32_e32 v16, 16, v2
	v_and_b32_e32 v17, 0xffff0000, v2
	v_lshlrev_b32_e32 v2, 16, v3
	v_and_b32_e32 v3, 0xffff0000, v3
	v_pk_fma_f32 v[10:11], v[52:53], v[14:15], v[10:11]
	v_lshl_add_u64 v[52:53], v[8:9], 0, s[0:1]
	s_waitcnt vmcnt(8)
	v_pk_fma_f32 v[152:153], v[66:67], v[0:1], v[154:155]
	v_pk_fma_f32 v[142:143], v[32:33], v[16:17], v[142:143]
	v_pk_fma_f32 v[144:145], v[34:35], v[2:3], v[144:145]
	v_pk_fma_f32 v[154:155], v[60:61], v[14:15], v[156:157]
	v_pk_fma_f32 v[156:157], v[62:63], v[0:1], v[158:159]
	v_pk_fma_f32 v[158:159], v[28:29], v[16:17], v[160:161]
	v_pk_fma_f32 v[160:161], v[30:31], v[2:3], v[162:163]
	v_pk_fma_f32 v[162:163], v[56:57], v[14:15], v[164:165]
	v_pk_fma_f32 v[146:147], v[58:59], v[0:1], v[146:147]
	v_pk_fma_f32 v[164:165], v[24:25], v[16:17], v[166:167]
	v_pk_fma_f32 v[148:149], v[26:27], v[2:3], v[148:149]
	v_pk_fma_f32 v[12:13], v[54:55], v[0:1], v[12:13]
	v_pk_fma_f32 v[4:5], v[20:21], v[16:17], v[4:5]
	v_pk_fma_f32 v[6:7], v[22:23], v[2:3], v[6:7]
	global_load_dwordx4 v[16:19], v[8:9], off offset:16
	global_load_dwordx4 v[20:23], v[8:9], off
	ds_read_b128 v[0:3], v134 offset:50176
	v_pk_fma_f32 v[150:151], v[64:65], v[14:15], v[150:151]
	s_waitcnt lgkmcnt(0)
	v_lshlrev_b32_e32 v14, 16, v2
	v_and_b32_e32 v15, 0xffff0000, v2
	v_lshlrev_b32_e32 v8, 16, v0
	v_and_b32_e32 v9, 0xffff0000, v0
	v_lshlrev_b32_e32 v0, 16, v1
	v_and_b32_e32 v1, 0xffff0000, v1
	v_lshlrev_b32_e32 v2, 16, v3
	v_and_b32_e32 v3, 0xffff0000, v3
	v_pk_fma_f32 v[4:5], v[24:25], v[14:15], v[4:5]
	v_lshl_add_u64 v[24:25], v[52:53], 0, s[0:1]
	s_waitcnt vmcnt(8)
; #define LAS __attribute__((address_space(3)))
; __device__ __forceinline__ void conv_phase(LAS unsigned char* lds, const bf16_t* U, bf16_t* C, const float* wdw, const float* bdw, const float* lng, const float* lnb,
;                                            int first, int stride, int end, int tid, int wave, int lane) {
;     ...
;             for (int r = 0; r < TT / NWAVES + CW - 1; ++r) {
;                 if (r + 4 < CW) { wt[(r + 4) & 7][0] = wq[0]; wt[(r + 4) & 7][1] = wq[1]; wq += D / 4; asm volatile("" : "+v"(wq)); }
;                 const u32x4 xv = *(const LAS u32x4*)(lds + (4 * wave + r) * 2048 + p * 1024 + lane * 16);
;                 f32x2 x[4];
; #pragma unroll
;                 for (int i = 0; i < 4; ++i) x[i] = (f32x2){__uint_as_float(xv[i] << 16), __uint_as_float(xv[i] & 0xffff0000u)};
; #pragma unroll
;                 for (int j = 0; j < 4; ++j) { const int w = r - j;
;                     if (w >= 0 && w < CW) {
; #pragma unroll
;                         for (int c = 0; c < 4; ++c) { const f32x4 wv = wt[w & 7][c >> 1]; const f32x2 w2 = (c & 1) ? (f32x2){wv.z, wv.w} : (f32x2){wv.x, wv.y}; acc[p][j][c] = __builtin_elementwise_fma(w2, x[c], acc[p][j][c]); } } }
;                 asm volatile("" ::: "memory");
;             }
	v_pk_fma_f32 v[54:55], v[68:69], v[8:9], v[150:151]
	v_pk_fma_f32 v[150:151], v[70:71], v[0:1], v[152:153]
	v_pk_fma_f32 v[142:143], v[36:37], v[14:15], v[142:143]
	v_pk_fma_f32 v[144:145], v[38:39], v[2:3], v[144:145]
	v_pk_fma_f32 v[152:153], v[64:65], v[8:9], v[154:155]
	v_pk_fma_f32 v[154:155], v[66:67], v[0:1], v[156:157]
	v_pk_fma_f32 v[156:157], v[32:33], v[14:15], v[158:159]
	v_pk_fma_f32 v[158:159], v[34:35], v[2:3], v[160:161]
	v_pk_fma_f32 v[160:161], v[60:61], v[8:9], v[162:163]
	v_pk_fma_f32 v[146:147], v[62:63], v[0:1], v[146:147]
	v_pk_fma_f32 v[162:163], v[28:29], v[14:15], v[164:165]
	v_pk_fma_f32 v[148:149], v[30:31], v[2:3], v[148:149]
	v_pk_fma_f32 v[56:57], v[56:57], v[8:9], v[10:11]
	v_pk_fma_f32 v[58:59], v[58:59], v[0:1], v[12:13]
	v_pk_fma_f32 v[6:7], v[26:27], v[2:3], v[6:7]
	global_load_dwordx4 v[8:11], v[52:53], off offset:16
	global_load_dwordx4 v[12:15], v[52:53], off
	ds_read_b128 v[0:3], v134 offset:52224
	s_waitcnt lgkmcnt(0)
	v_lshlrev_b32_e32 v26, 16, v0
	v_and_b32_e32 v27, 0xffff0000, v0
	v_lshlrev_b32_e32 v0, 16, v1
	v_and_b32_e32 v1, 0xffff0000, v1
	v_lshlrev_b32_e32 v52, 16, v2
	v_and_b32_e32 v53, 0xffff0000, v2
	v_lshlrev_b32_e32 v2, 16, v3
	v_and_b32_e32 v3, 0xffff0000, v3
	s_waitcnt vmcnt(8)
	v_pk_fma_f32 v[150:151], v[74:75], v[0:1], v[150:151]
	v_pk_fma_f32 v[144:145], v[42:43], v[2:3], v[144:145]
	v_pk_fma_f32 v[154:155], v[70:71], v[0:1], v[154:155]
	v_pk_fma_f32 v[158:159], v[38:39], v[2:3], v[158:159]
	v_pk_fma_f32 v[146:147], v[66:67], v[0:1], v[146:147]
	v_pk_fma_f32 v[148:149], v[34:35], v[2:3], v[148:149]
	v_pk_fma_f32 v[58:59], v[62:63], v[0:1], v[58:59]
	v_pk_fma_f32 v[28:29], v[28:29], v[52:53], v[4:5]
	v_pk_fma_f32 v[30:31], v[30:31], v[2:3], v[6:7]
	global_load_dwordx4 v[4:7], v[24:25], off offset:16
	global_load_dwordx4 v[0:3], v[24:25], off
	v_lshl_add_u64 v[24:25], v[24:25], 0, s[0:1]
	v_pk_fma_f32 v[54:55], v[72:73], v[26:27], v[54:55]
	v_pk_fma_f32 v[152:153], v[68:69], v[26:27], v[152:153]
	v_pk_fma_f32 v[160:161], v[64:65], v[26:27], v[160:161]
	v_pk_fma_f32 v[56:57], v[60:61], v[26:27], v[56:57]
	ds_read_b128 v[24:27], v134 offset:54272
	v_pk_fma_f32 v[142:143], v[40:41], v[52:53], v[142:143]
	v_pk_fma_f32 v[156:157], v[36:37], v[52:53], v[156:157]
	v_pk_fma_f32 v[162:163], v[32:33], v[52:53], v[162:163]
	s_waitcnt lgkmcnt(0)
	v_lshlrev_b32_e32 v52, 16, v24
	v_and_b32_e32 v53, 0xffff0000, v24
	v_lshlrev_b32_e32 v24, 16, v25
	v_and_b32_e32 v25, 0xffff0000, v25
	v_lshlrev_b32_e32 v60, 16, v26
	v_and_b32_e32 v61, 0xffff0000, v26
	v_lshlrev_b32_e32 v26, 16, v27
	v_and_b32_e32 v27, 0xffff0000, v27
	s_waitcnt vmcnt(8)
	v_pk_fma_f32 v[54:55], v[76:77], v[52:53], v[54:55]
	v_pk_fma_f32 v[62:63], v[78:79], v[24:25], v[150:151]
	v_pk_fma_f32 v[144:145], v[46:47], v[26:27], v[144:145]
	v_pk_fma_f32 v[150:151], v[72:73], v[52:53], v[152:153]
	v_pk_fma_f32 v[152:153], v[74:75], v[24:25], v[154:155]
	v_pk_fma_f32 v[154:155], v[40:41], v[60:61], v[156:157]
	v_pk_fma_f32 v[156:157], v[42:43], v[26:27], v[158:159]
	v_pk_fma_f32 v[158:159], v[68:69], v[52:53], v[160:161]
	v_pk_fma_f32 v[146:147], v[70:71], v[24:25], v[146:147]
	v_pk_fma_f32 v[148:149], v[38:39], v[26:27], v[148:149]
	v_pk_fma_f32 v[52:53], v[64:65], v[52:53], v[56:57]
	v_pk_fma_f32 v[56:57], v[66:67], v[24:25], v[58:59]
	v_pk_fma_f32 v[30:31], v[34:35], v[26:27], v[30:31]
	ds_read_b128 v[24:27], v134 offset:56320
	v_pk_fma_f32 v[28:29], v[32:33], v[60:61], v[28:29]
	v_pk_fma_f32 v[142:143], v[44:45], v[60:61], v[142:143]
	v_pk_fma_f32 v[160:161], v[36:37], v[60:61], v[162:163]
	s_waitcnt lgkmcnt(0)
	v_lshlrev_b32_e32 v32, 16, v24
	v_and_b32_e32 v33, 0xffff0000, v24
	v_lshlrev_b32_e32 v24, 16, v25
	v_and_b32_e32 v25, 0xffff0000, v25
	v_lshlrev_b32_e32 v34, 16, v26
	v_and_b32_e32 v35, 0xffff0000, v26
	v_lshlrev_b32_e32 v26, 16, v27
	v_and_b32_e32 v27, 0xffff0000, v27
	s_waitcnt vmcnt(6)
	v_pk_fma_f32 v[54:55], v[80:81], v[32:33], v[54:55]
	v_pk_fma_f32 v[58:59], v[82:83], v[24:25], v[62:63]
	v_pk_fma_f32 v[62:63], v[50:51], v[26:27], v[144:145]
	v_pk_fma_f32 v[64:65], v[76:77], v[32:33], v[150:151]
	v_pk_fma_f32 v[66:67], v[78:79], v[24:25], v[152:153]
	v_pk_fma_f32 v[144:145], v[46:47], v[26:27], v[156:157]
	v_pk_fma_f32 v[150:151], v[72:73], v[32:33], v[158:159]
	v_pk_fma_f32 v[146:147], v[74:75], v[24:25], v[146:147]
	v_pk_fma_f32 v[148:149], v[42:43], v[26:27], v[148:149]
	v_pk_fma_f32 v[32:33], v[68:69], v[32:33], v[52:53]
	v_pk_fma_f32 v[52:53], v[70:71], v[24:25], v[56:57]
	v_pk_fma_f32 v[30:31], v[38:39], v[26:27], v[30:31]
	ds_read_b128 v[24:27], v134 offset:58368
	v_pk_fma_f32 v[60:61], v[48:49], v[34:35], v[142:143]
	v_pk_fma_f32 v[142:143], v[44:45], v[34:35], v[154:155]
	v_pk_fma_f32 v[152:153], v[40:41], v[34:35], v[160:161]
	v_pk_fma_f32 v[28:29], v[36:37], v[34:35], v[28:29]
	s_waitcnt lgkmcnt(0)
	v_lshlrev_b32_e32 v34, 16, v24
	v_and_b32_e32 v35, 0xffff0000, v24
	v_lshlrev_b32_e32 v24, 16, v25
	v_and_b32_e32 v25, 0xffff0000, v25
	v_lshlrev_b32_e32 v36, 16, v26
	v_and_b32_e32 v37, 0xffff0000, v26
	v_lshlrev_b32_e32 v26, 16, v27
	v_and_b32_e32 v27, 0xffff0000, v27
	s_waitcnt vmcnt(4)
	v_pk_fma_f32 v[38:39], v[20:21], v[34:35], v[54:55]
	v_pk_fma_f32 v[54:55], v[22:23], v[24:25], v[58:59]
	v_pk_fma_f32 v[56:57], v[16:17], v[36:37], v[60:61]
	v_pk_fma_f32 v[58:59], v[18:19], v[26:27], v[62:63]
	v_pk_fma_f32 v[60:61], v[80:81], v[34:35], v[64:65]
	v_pk_fma_f32 v[62:63], v[82:83], v[24:25], v[66:67]
	v_pk_fma_f32 v[66:67], v[50:51], v[26:27], v[144:145]
	v_pk_fma_f32 v[68:69], v[76:77], v[34:35], v[150:151]
	v_pk_fma_f32 v[70:71], v[78:79], v[24:25], v[146:147]
	v_pk_fma_f32 v[144:145], v[46:47], v[26:27], v[148:149]
	v_pk_fma_f32 v[32:33], v[72:73], v[34:35], v[32:33]
	v_pk_fma_f32 v[34:35], v[74:75], v[24:25], v[52:53]
	v_pk_fma_f32 v[30:31], v[42:43], v[26:27], v[30:31]
	ds_read_b128 v[24:27], v134 offset:60416
	v_pk_fma_f32 v[64:65], v[48:49], v[36:37], v[142:143]
	v_pk_fma_f32 v[142:143], v[44:45], v[36:37], v[152:153]
	v_pk_fma_f32 v[28:29], v[40:41], v[36:37], v[28:29]
	s_waitcnt lgkmcnt(0)
; #define LAS __attribute__((address_space(3)))
; __device__ __forceinline__ void conv_phase(LAS unsigned char* lds, const bf16_t* U, bf16_t* C, const float* wdw, const float* bdw, const float* lng, const float* lnb,
;                                            int first, int stride, int end, int tid, int wave, int lane) {
;     ...
;             for (int r = 0; r < TT / NWAVES + CW - 1; ++r) {
;                 if (r + 4 < CW) { wt[(r + 4) & 7][0] = wq[0]; wt[(r + 4) & 7][1] = wq[1]; wq += D / 4; asm volatile("" : "+v"(wq)); }
;                 const u32x4 xv = *(const LAS u32x4*)(lds + (4 * wave + r) * 2048 + p * 1024 + lane * 16);
;                 f32x2 x[4];
; #pragma unroll
;                 for (int i = 0; i < 4; ++i) x[i] = (f32x2){__uint_as_float(xv[i] << 16), __uint_as_float(xv[i] & 0xffff0000u)};
; #pragma unroll
;                 for (int j = 0; j < 4; ++j) { const int w = r - j;
;                     if (w >= 0 && w < CW) {
; #pragma unroll
;                         for (int c = 0; c < 4; ++c) { const f32x4 wv = wt[w & 7][c >> 1]; const f32x2 w2 = (c & 1) ? (f32x2){wv.z, wv.w} : (f32x2){wv.x, wv.y}; acc[p][j][c] = __builtin_elementwise_fma(w2, x[c], acc[p][j][c]); } } }
;                 asm volatile("" ::: "memory");
;             }
;             const f32x4 b0 = *(const f32x4*)(bdw + p * 512 + lane * 8), b1 = *(const f32x4*)(bdw + p * 512 + lane * 8 + 4);
; #pragma unroll
;             for (int j = 0; j < 4; ++j) { acc[p][j][0] += (f32x2){b0.x, b0.y}; acc[p][j][1] += (f32x2){b0.z, b0.w}; acc[p][j][2] += (f32x2){b1.x, b1.y}; acc[p][j][3] += (f32x2){b1.z, b1.w}; }
	v_lshlrev_b32_e32 v36, 16, v24
	v_and_b32_e32 v37, 0xffff0000, v24
	v_lshlrev_b32_e32 v24, 16, v25
	v_and_b32_e32 v25, 0xffff0000, v25
	v_lshlrev_b32_e32 v40, 16, v26
	v_and_b32_e32 v41, 0xffff0000, v26
	v_lshlrev_b32_e32 v26, 16, v27
	v_and_b32_e32 v27, 0xffff0000, v27
	s_waitcnt vmcnt(2)
	v_pk_fma_f32 v[38:39], v[12:13], v[36:37], v[38:39]
	v_pk_fma_f32 v[42:43], v[14:15], v[24:25], v[54:55]
	v_pk_fma_f32 v[52:53], v[8:9], v[40:41], v[56:57]
	v_pk_fma_f32 v[54:55], v[10:11], v[26:27], v[58:59]
	v_pk_fma_f32 v[56:57], v[20:21], v[36:37], v[60:61]
	v_pk_fma_f32 v[58:59], v[22:23], v[24:25], v[62:63]
	v_pk_fma_f32 v[60:61], v[16:17], v[40:41], v[64:65]
	v_pk_fma_f32 v[62:63], v[18:19], v[26:27], v[66:67]
	v_pk_fma_f32 v[64:65], v[80:81], v[36:37], v[68:69]
	v_pk_fma_f32 v[66:67], v[82:83], v[24:25], v[70:71]
	v_pk_fma_f32 v[68:69], v[48:49], v[40:41], v[142:143]
	v_pk_fma_f32 v[70:71], v[50:51], v[26:27], v[144:145]
	v_pk_fma_f32 v[32:33], v[76:77], v[36:37], v[32:33]
	v_pk_fma_f32 v[34:35], v[78:79], v[24:25], v[34:35]
	v_pk_fma_f32 v[36:37], v[44:45], v[40:41], v[28:29]
	v_pk_fma_f32 v[40:41], v[46:47], v[26:27], v[30:31]
	ds_read_b128 v[24:27], v134 offset:62464
	s_waitcnt lgkmcnt(0)
	v_lshlrev_b32_e32 v44, 16, v24
	v_and_b32_e32 v45, 0xffff0000, v24
	v_lshlrev_b32_e32 v46, 16, v25
	v_and_b32_e32 v47, 0xffff0000, v25
	v_lshlrev_b32_e32 v72, 16, v26
	v_and_b32_e32 v73, 0xffff0000, v26
	v_lshlrev_b32_e32 v74, 16, v27
	v_and_b32_e32 v75, 0xffff0000, v27
	s_waitcnt vmcnt(0)
	v_pk_fma_f32 v[24:25], v[0:1], v[44:45], v[38:39]
	v_pk_fma_f32 v[26:27], v[2:3], v[46:47], v[42:43]
	v_pk_fma_f32 v[38:39], v[12:13], v[44:45], v[56:57]
	v_pk_fma_f32 v[42:43], v[14:15], v[46:47], v[58:59]
	v_pk_fma_f32 v[56:57], v[20:21], v[44:45], v[64:65]
	v_pk_fma_f32 v[58:59], v[22:23], v[46:47], v[66:67]
	v_pk_fma_f32 v[44:45], v[80:81], v[44:45], v[32:33]
	v_pk_fma_f32 v[46:47], v[82:83], v[46:47], v[34:35]
	ds_read_b128 v[32:35], v134 offset:64512
	v_pk_fma_f32 v[28:29], v[4:5], v[72:73], v[52:53]
	v_pk_fma_f32 v[52:53], v[8:9], v[72:73], v[60:61]
	v_pk_fma_f32 v[60:61], v[16:17], v[72:73], v[68:69]
	v_pk_fma_f32 v[48:49], v[48:49], v[72:73], v[36:37]
	v_pk_fma_f32 v[40:41], v[50:51], v[74:75], v[40:41]
	s_waitcnt lgkmcnt(0)
	v_lshlrev_b32_e32 v66, 16, v34
	v_and_b32_e32 v67, 0xffff0000, v34
	v_lshlrev_b32_e32 v68, 16, v35
	v_and_b32_e32 v69, 0xffff0000, v35
	v_pk_fma_f32 v[30:31], v[6:7], v[74:75], v[54:55]
	v_pk_fma_f32 v[54:55], v[10:11], v[74:75], v[62:63]
	v_pk_fma_f32 v[62:63], v[18:19], v[74:75], v[70:71]
	v_pk_fma_f32 v[48:49], v[16:17], v[66:67], v[48:49]
	v_pk_fma_f32 v[40:41], v[18:19], v[68:69], v[40:41]
	ds_read_b128 v[16:19], v138
	v_lshlrev_b32_e32 v50, 16, v32
	v_and_b32_e32 v51, 0xffff0000, v32
	v_lshlrev_b32_e32 v64, 16, v33
	v_and_b32_e32 v65, 0xffff0000, v33
	v_pk_fma_f32 v[32:33], v[0:1], v[50:51], v[38:39]
	v_pk_fma_f32 v[34:35], v[2:3], v[64:65], v[42:43]
	v_pk_fma_f32 v[38:39], v[6:7], v[68:69], v[54:55]
	v_pk_fma_f32 v[42:43], v[12:13], v[50:51], v[56:57]
	v_pk_fma_f32 v[54:55], v[8:9], v[66:67], v[60:61]
	v_pk_fma_f32 v[56:57], v[10:11], v[68:69], v[62:63]
	v_pk_fma_f32 v[44:45], v[20:21], v[50:51], v[44:45]
	s_waitcnt lgkmcnt(0)
	v_lshlrev_b32_e32 v50, 16, v16
	v_and_b32_e32 v51, 0xffff0000, v16
	v_lshlrev_b32_e32 v60, 16, v18
	v_and_b32_e32 v61, 0xffff0000, v18
	v_lshlrev_b32_e32 v62, 16, v19
	v_and_b32_e32 v63, 0xffff0000, v19
	v_pk_fma_f32 v[36:37], v[4:5], v[66:67], v[52:53]
	v_pk_fma_f32 v[52:53], v[14:15], v[64:65], v[58:59]
	v_lshlrev_b32_e32 v58, 16, v17
	v_and_b32_e32 v59, 0xffff0000, v17
	v_pk_fma_f32 v[16:17], v[0:1], v[50:51], v[42:43]
	v_pk_fma_f32 v[42:43], v[8:9], v[60:61], v[48:49]
	v_pk_fma_f32 v[40:41], v[10:11], v[62:63], v[40:41]
	ds_read_b128 v[8:11], v139
	v_pk_fma_f32 v[46:47], v[22:23], v[64:65], v[46:47]
	v_pk_fma_f32 v[12:13], v[12:13], v[50:51], v[44:45]
	v_pk_fma_f32 v[14:15], v[14:15], v[58:59], v[46:47]
	s_waitcnt lgkmcnt(0)
	v_lshlrev_b32_e32 v46, 16, v8
	v_and_b32_e32 v47, 0xffff0000, v8
	v_lshlrev_b32_e32 v8, 16, v9
	v_and_b32_e32 v9, 0xffff0000, v9
	v_lshlrev_b32_e32 v44, 16, v10
	v_and_b32_e32 v45, 0xffff0000, v10
	v_lshlrev_b32_e32 v10, 16, v11
	v_and_b32_e32 v11, 0xffff0000, v11
	v_pk_fma_f32 v[18:19], v[2:3], v[58:59], v[52:53]
	v_pk_fma_f32 v[20:21], v[4:5], v[60:61], v[54:55]
	v_pk_fma_f32 v[22:23], v[6:7], v[62:63], v[56:57]
	v_pk_fma_f32 v[40:41], v[6:7], v[10:11], v[40:41]
	v_pk_fma_f32 v[42:43], v[4:5], v[44:45], v[42:43]
	v_pk_fma_f32 v[44:45], v[2:3], v[8:9], v[14:15]
	v_pk_fma_f32 v[8:9], v[0:1], v[46:47], v[12:13]
	v_mov_b64_e32 v[0:1], v[188:189]
	v_mov_b64_e32 v[2:3], v[190:191]
	v_mov_b64_e32 v[4:5], v[192:193]
	v_mov_b64_e32 v[6:7], v[194:195]
	s_waitcnt vmcnt(1)
	v_pk_add_f32 v[50:51], v[28:29], v[0:1]
	s_waitcnt vmcnt(0)
; __device__ __forceinline__ void conv_phase(LAS unsigned char* lds, const bf16_t* U, bf16_t* C, const float* wdw, const float* bdw, const float* lng, const float* lnb,
;                                            int first, int stride, int end, int tid, int wave, int lane) {
;     ...
;             for (int j = 0; j < 4; ++j) { acc[p][j][0] += (f32x2){b0.x, b0.y}; acc[p][j][1] += (f32x2){b0.z, b0.w}; acc[p][j][2] += (f32x2){b1.x, b1.y}; acc[p][j][3] += (f32x2){b1.z, b1.w}; }
;         }
;         float mean[4], rstd[4];
; #pragma unroll
;         for (int j = 0; j < 4; ++j) { f32x2 s2 = (f32x2){0.f, 0.f};
; #pragma unroll
;             for (int p = 0; p < 2; ++p)
; #pragma unroll
;                 for (int c = 0; c < 4; ++c) s2 += acc[p][j][c];
;             mean[j] = wave_sum(s2.x + s2.y) * (1.f / D); f32x2 q2 = (f32x2){0.f, 0.f};
; #pragma unroll
;             for (int p = 0; p < 2; ++p)
; #pragma unroll
;                 for (int c = 0; c < 4; ++c) { const f32x2 d = acc[p][j][c] - mean[j]; q2 += d * d; }
;             rstd[j] = rsqrtf(wave_sum(q2.x + q2.y) * (1.f / D) + LN_EPS); }
	v_pk_add_f32 v[46:47], v[24:25], v[4:5]
	v_pk_add_f32 v[48:49], v[26:27], v[6:7]
	v_pk_add_f32 v[52:53], v[30:31], v[2:3]
	v_pk_add_f32 v[32:33], v[32:33], v[4:5]
	v_pk_add_f32 v[30:31], v[34:35], v[6:7]
	v_pk_add_f32 v[24:25], v[36:37], v[0:1]
	v_pk_add_f32 v[26:27], v[38:39], v[2:3]
	v_pk_add_f32 v[34:35], v[4:5], v[16:17]
	v_pk_add_f32 v[12:13], v[0:1], v[20:21]
	v_pk_add_f32 v[10:11], v[2:3], v[22:23]
	v_pk_add_f32 v[8:9], v[4:5], v[8:9]
	v_pk_add_f32 v[4:5], v[0:1], v[42:43]
	v_pk_add_f32 v[0:1], v[2:3], v[40:41]
	v_cndmask_b32_e64 v2, v224, v226, s[40:41]
	v_cmp_lt_i32_e64 s[40:41], v227, v225
	v_lshlrev_b32_e32 v41, 2, v2
	v_pk_add_f32 v[14:15], v[6:7], v[18:19]
	v_cndmask_b32_e64 v2, v224, v227, s[40:41]
	v_cmp_lt_i32_e64 s[40:41], v228, v225
	v_pk_add_f32 v[6:7], v[6:7], v[44:45]
	v_lshlrev_b32_e32 v44, 2, v2
	v_cndmask_b32_e64 v2, v224, v228, s[40:41]
	v_cmp_lt_i32_e64 s[40:41], v229, v225
	v_lshlrev_b32_e32 v45, 2, v2
	s_nop 0
	v_cndmask_b32_e64 v2, v224, v229, s[40:41]
	v_cmp_lt_i32_e64 s[40:41], v230, v225
	v_lshlrev_b32_e32 v54, 2, v2
	s_nop 0
	v_cndmask_b32_e64 v2, v224, v230, s[40:41]
	v_cmp_lt_i32_e64 s[40:41], v231, v225
	v_lshlrev_b32_e32 v55, 2, v2
	s_nop 0
	v_cndmask_b32_e64 v2, v224, v231, s[40:41]
	v_lshlrev_b32_e32 v76, 2, v2
	v_pk_add_f32 v[2:3], v[128:129], 0 op_sel_hi:[1,0]
	s_nop 0
	v_pk_add_f32 v[2:3], v[130:131], v[2:3]
	s_nop 0
	v_pk_add_f32 v[2:3], v[126:127], v[2:3]
	s_nop 0
	v_pk_add_f32 v[2:3], v[124:125], v[2:3]
	s_nop 0
	v_pk_add_f32 v[2:3], v[2:3], v[46:47]
	s_nop 0
	v_pk_add_f32 v[2:3], v[48:49], v[2:3]
	s_nop 0
	v_pk_add_f32 v[2:3], v[50:51], v[2:3]
	s_nop 0
	v_pk_add_f32 v[2:3], v[52:53], v[2:3]
	s_nop 0
	v_add_f32_e32 v2, v2, v3
	s_nop 1
	v_add_f32_dpp v2, v2, v2 quad_perm:[1,0,3,2] row_mask:0xf bank_mask:0xf
	s_nop 1
	v_add_f32_dpp v2, v2, v2 quad_perm:[2,3,0,1] row_mask:0xf bank_mask:0xf
	s_nop 1
	v_add_f32_dpp v2, v2, v2 row_half_mirror row_mask:0xf bank_mask:0xf
	s_nop 1
	v_add_f32_dpp v2, v2, v2 row_mirror row_mask:0xf bank_mask:0xf
	v_mov_b32_e32 v3, v2
	s_nop 1
	v_permlane16_swap_b32_e32 v2, v3
	s_waitcnt lgkmcnt(0)
	v_add_f32_e32 v2, v2, v3
	v_mov_b32_e32 v3, v2
	s_nop 1
	v_permlane32_swap_b32_e32 v2, v3
	s_waitcnt lgkmcnt(0)
	v_add_f32_e32 v2, v2, v3
	v_mul_f32_e32 v2, 0x3a800000, v2
	v_pk_add_f32 v[62:63], v[130:131], v[2:3] op_sel_hi:[1,0] neg_lo:[0,1] neg_hi:[0,1]
	v_pk_add_f32 v[66:67], v[128:129], v[2:3] op_sel_hi:[1,0] neg_lo:[0,1] neg_hi:[0,1]
	v_pk_mul_f32 v[16:17], v[62:63], v[62:63]
	v_pk_add_f32 v[58:59], v[126:127], v[2:3] op_sel_hi:[1,0] neg_lo:[0,1] neg_hi:[0,1]
	v_pk_fma_f32 v[16:17], v[66:67], v[66:67], v[16:17]
	v_pk_add_f32 v[56:57], v[124:125], v[2:3] op_sel_hi:[1,0] neg_lo:[0,1] neg_hi:[0,1]
	v_pk_fma_f32 v[16:17], v[58:59], v[58:59], v[16:17]
	v_pk_add_f32 v[28:29], v[46:47], v[2:3] op_sel_hi:[1,0] neg_lo:[0,1] neg_hi:[0,1]
	v_pk_fma_f32 v[16:17], v[56:57], v[56:57], v[16:17]
	v_pk_add_f32 v[22:23], v[48:49], v[2:3] op_sel_hi:[1,0] neg_lo:[0,1] neg_hi:[0,1]
	v_pk_fma_f32 v[16:17], v[28:29], v[28:29], v[16:17]
	v_pk_add_f32 v[18:19], v[50:51], v[2:3] op_sel_hi:[1,0] neg_lo:[0,1] neg_hi:[0,1]
	v_pk_fma_f32 v[16:17], v[22:23], v[22:23], v[16:17]
	s_nop 0
	v_pk_fma_f32 v[20:21], v[18:19], v[18:19], v[16:17]
	v_pk_add_f32 v[16:17], v[52:53], v[2:3] op_sel_hi:[1,0] neg_lo:[0,1] neg_hi:[0,1]
	s_nop 0
	v_pk_fma_f32 v[2:3], v[16:17], v[16:17], v[20:21]
	v_pk_add_f32 v[20:21], v[120:121], 0 op_sel_hi:[1,0]
	s_nop 0
	v_pk_add_f32 v[20:21], v[122:123], v[20:21]
	s_nop 0
	v_pk_add_f32 v[20:21], v[118:119], v[20:21]
	s_nop 0
	v_pk_add_f32 v[20:21], v[116:117], v[20:21]
	s_nop 0
	v_pk_add_f32 v[20:21], v[20:21], v[32:33]
	s_nop 0
	v_pk_add_f32 v[20:21], v[30:31], v[20:21]
	s_nop 0
	v_pk_add_f32 v[20:21], v[24:25], v[20:21]
	s_nop 0
	v_pk_add_f32 v[20:21], v[26:27], v[20:21]
	s_nop 0
	v_add_f32_e32 v20, v20, v21
	s_nop 1
	v_add_f32_dpp v20, v20, v20 quad_perm:[1,0,3,2] row_mask:0xf bank_mask:0xf
	s_nop 1
	v_add_f32_dpp v20, v20, v20 quad_perm:[2,3,0,1] row_mask:0xf bank_mask:0xf
	s_nop 1
	v_add_f32_dpp v20, v20, v20 row_half_mirror row_mask:0xf bank_mask:0xf
	s_nop 1
	v_add_f32_dpp v20, v20, v20 row_mirror row_mask:0xf bank_mask:0xf
	v_mov_b32_e32 v21, v20
	s_nop 1
	v_permlane16_swap_b32_e32 v20, v21
	s_waitcnt lgkmcnt(0)
	v_add_f32_e32 v20, v20, v21
	v_mov_b32_e32 v21, v20
	s_nop 1
	v_permlane32_swap_b32_e32 v20, v21
	s_waitcnt lgkmcnt(0)
	v_add_f32_e32 v20, v20, v21
	v_mul_f32_e32 v20, 0x3a800000, v20
	v_pk_add_f32 v[68:69], v[122:123], v[20:21] op_sel_hi:[1,0] neg_lo:[0,1] neg_hi:[0,1]
	v_pk_add_f32 v[70:71], v[120:121], v[20:21] op_sel_hi:[1,0] neg_lo:[0,1] neg_hi:[0,1]
	v_pk_mul_f32 v[36:37], v[68:69], v[68:69]
	v_pk_add_f32 v[64:65], v[118:119], v[20:21] op_sel_hi:[1,0] neg_lo:[0,1] neg_hi:[0,1]
	v_pk_fma_f32 v[36:37], v[70:71], v[70:71], v[36:37]
	v_pk_add_f32 v[60:61], v[116:117], v[20:21] op_sel_hi:[1,0] neg_lo:[0,1] neg_hi:[0,1]
	v_pk_fma_f32 v[36:37], v[64:65], v[64:65], v[36:37]
	v_pk_add_f32 v[32:33], v[32:33], v[20:21] op_sel_hi:[1,0] neg_lo:[0,1] neg_hi:[0,1]
	v_pk_fma_f32 v[36:37], v[60:61], v[60:61], v[36:37]
	v_pk_add_f32 v[30:31], v[30:31], v[20:21] op_sel_hi:[1,0] neg_lo:[0,1] neg_hi:[0,1]
	v_pk_fma_f32 v[36:37], v[32:33], v[32:33], v[36:37]
	v_pk_add_f32 v[24:25], v[24:25], v[20:21] op_sel_hi:[1,0] neg_lo:[0,1] neg_hi:[0,1]
	v_pk_fma_f32 v[36:37], v[30:31], v[30:31], v[36:37]
	v_pk_add_f32 v[20:21], v[26:27], v[20:21] op_sel_hi:[1,0] neg_lo:[0,1] neg_hi:[0,1]
	v_pk_fma_f32 v[36:37], v[24:25], v[24:25], v[36:37]
	s_nop 0
	v_pk_fma_f32 v[26:27], v[20:21], v[20:21], v[36:37]
	v_mov_b32_e32 v37, v2
	v_mov_b32_e32 v36, v26
	v_mov_b32_e32 v2, v27
	v_pk_add_f32 v[2:3], v[36:37], v[2:3]
	s_nop 1
	v_add_f32_dpp v2, v2, v2 quad_perm:[1,0,3,2] row_mask:0xf bank_mask:0xf
	v_add_f32_dpp v3, v3, v3 quad_perm:[1,0,3,2] row_mask:0xf bank_mask:0xf
	s_nop 1
	v_add_f32_dpp v2, v2, v2 quad_perm:[2,3,0,1] row_mask:0xf bank_mask:0xf
	v_add_f32_dpp v3, v3, v3 quad_perm:[2,3,0,1] row_mask:0xf bank_mask:0xf
	s_nop 1
	v_add_f32_dpp v2, v2, v2 row_half_mirror row_mask:0xf bank_mask:0xf
	v_add_f32_dpp v3, v3, v3 row_half_mirror row_mask:0xf bank_mask:0xf
	s_nop 1
	v_add_f32_dpp v2, v2, v2 row_mirror row_mask:0xf bank_mask:0xf
	v_add_f32_dpp v3, v3, v3 row_mirror row_mask:0xf bank_mask:0xf
	v_mov_b32_e32 v27, v3
	v_mov_b32_e32 v26, v2
	s_nop 1
	v_permlane16_swap_b32_e32 v3, v27
	v_permlane16_swap_b32_e32 v2, v26
	s_waitcnt lgkmcnt(0)
; __device__ __forceinline__ void conv_phase(LAS unsigned char* lds, const bf16_t* U, bf16_t* C, const float* wdw, const float* bdw, const float* lng, const float* lnb,
;                                            int first, int stride, int end, int tid, int wave, int lane) {
;     ...
;         float mean[4], rstd[4];
; #pragma unroll
;         for (int j = 0; j < 4; ++j) { f32x2 s2 = (f32x2){0.f, 0.f};
; #pragma unroll
;             for (int p = 0; p < 2; ++p)
; #pragma unroll
;                 for (int c = 0; c < 4; ++c) s2 += acc[p][j][c];
;             mean[j] = wave_sum(s2.x + s2.y) * (1.f / D); f32x2 q2 = (f32x2){0.f, 0.f};
; #pragma unroll
;             for (int p = 0; p < 2; ++p)
; #pragma unroll
;                 for (int c = 0; c < 4; ++c) { const f32x2 d = acc[p][j][c] - mean[j]; q2 += d * d; }
;             rstd[j] = rsqrtf(wave_sum(q2.x + q2.y) * (1.f / D) + LN_EPS); }
	v_pk_add_f32 v[2:3], v[2:3], v[26:27]
	v_mov_b32_e32 v27, v3
	v_mov_b32_e32 v26, v2
	s_nop 1
	v_permlane32_swap_b32_e32 v3, v27
	v_permlane32_swap_b32_e32 v2, v26
	s_waitcnt lgkmcnt(0)
	v_pk_add_f32 v[26:27], v[2:3], v[26:27]
	v_mov_b64_e32 v[2:3], s[4:5]
	s_mov_b32 s4, 0x3a800000
	v_pk_fma_f32 v[26:27], v[26:27], s[4:5], v[2:3] op_sel_hi:[1,0,0]
	s_nop 0
	v_mul_f32_e32 v36, 0x4b800000, v27
	v_cmp_gt_f32_e64 s[42:43], s7, v27
	v_cmp_gt_f32_e64 s[40:41], s7, v26
	s_nop 0
	v_cndmask_b32_e64 v27, v27, v36, s[42:43]
	v_rsq_f32_e32 v27, v27
	s_nop 0
	v_mul_f32_e32 v36, 0x45800000, v27
	v_cndmask_b32_e64 v40, v27, v36, s[42:43]
	v_pk_add_f32 v[36:37], v[112:113], 0 op_sel_hi:[1,0]
	v_mul_f32_e32 v27, 0x4b800000, v26
	v_pk_add_f32 v[36:37], v[114:115], v[36:37]
	v_cndmask_b32_e64 v26, v26, v27, s[40:41]
	v_pk_add_f32 v[36:37], v[110:111], v[36:37]
	v_rsq_f32_e32 v26, v26
	v_pk_add_f32 v[36:37], v[108:109], v[36:37]
	v_mul_f32_e32 v27, 0x45800000, v26
	v_pk_add_f32 v[36:37], v[36:37], v[34:35]
	v_cndmask_b32_e64 v26, v26, v27, s[40:41]
	v_pk_add_f32 v[36:37], v[14:15], v[36:37]
	s_nop 0
	v_pk_add_f32 v[36:37], v[12:13], v[36:37]
	s_nop 0
	v_pk_add_f32 v[36:37], v[10:11], v[36:37]
	s_nop 0
	v_add_f32_e32 v27, v36, v37
	s_nop 1
	v_add_f32_dpp v27, v27, v27 quad_perm:[1,0,3,2] row_mask:0xf bank_mask:0xf
	s_nop 1
	v_add_f32_dpp v27, v27, v27 quad_perm:[2,3,0,1] row_mask:0xf bank_mask:0xf
	s_nop 1
	v_add_f32_dpp v27, v27, v27 row_half_mirror row_mask:0xf bank_mask:0xf
	s_nop 1
	v_add_f32_dpp v27, v27, v27 row_mirror row_mask:0xf bank_mask:0xf
	v_mov_b32_e32 v36, v27
	s_nop 1
	v_permlane16_swap_b32_e32 v27, v36
	s_waitcnt lgkmcnt(0)
	v_add_f32_e32 v27, v27, v36
	v_mov_b32_e32 v36, v27
	s_nop 1
	v_permlane32_swap_b32_e32 v27, v36
	s_waitcnt lgkmcnt(0)
	v_add_f32_e32 v27, v27, v36
	v_mul_f32_e32 v36, 0x3a800000, v27
	v_pk_add_f32 v[82:83], v[114:115], v[36:37] op_sel_hi:[1,0] neg_lo:[0,1] neg_hi:[0,1]
	v_pk_add_f32 v[112:113], v[112:113], v[36:37] op_sel_hi:[1,0] neg_lo:[0,1] neg_hi:[0,1]
	v_pk_mul_f32 v[38:39], v[82:83], v[82:83]
	v_pk_add_f32 v[78:79], v[110:111], v[36:37] op_sel_hi:[1,0] neg_lo:[0,1] neg_hi:[0,1]
	v_pk_fma_f32 v[38:39], v[112:113], v[112:113], v[38:39]
	v_pk_add_f32 v[72:73], v[108:109], v[36:37] op_sel_hi:[1,0] neg_lo:[0,1] neg_hi:[0,1]
	v_pk_fma_f32 v[38:39], v[78:79], v[78:79], v[38:39]
	v_pk_add_f32 v[50:51], v[34:35], v[36:37] op_sel_hi:[1,0] neg_lo:[0,1] neg_hi:[0,1]
	v_pk_fma_f32 v[38:39], v[72:73], v[72:73], v[38:39]
	v_pk_add_f32 v[46:47], v[14:15], v[36:37] op_sel_hi:[1,0] neg_lo:[0,1] neg_hi:[0,1]
	v_pk_fma_f32 v[34:35], v[50:51], v[50:51], v[38:39]
	v_pk_add_f32 v[38:39], v[12:13], v[36:37] op_sel_hi:[1,0] neg_lo:[0,1] neg_hi:[0,1]
	v_pk_fma_f32 v[14:15], v[46:47], v[46:47], v[34:35]
	v_pk_add_f32 v[34:35], v[10:11], v[36:37] op_sel_hi:[1,0] neg_lo:[0,1] neg_hi:[0,1]
	v_pk_fma_f32 v[12:13], v[38:39], v[38:39], v[14:15]
	s_nop 0
	v_pk_fma_f32 v[10:11], v[34:35], v[34:35], v[12:13]
	v_pk_add_f32 v[12:13], v[104:105], 0 op_sel_hi:[1,0]
	s_nop 0
	v_pk_add_f32 v[12:13], v[106:107], v[12:13]
	s_nop 0
	v_pk_add_f32 v[12:13], v[102:103], v[12:13]
	s_nop 0
	v_pk_add_f32 v[12:13], v[100:101], v[12:13]
	s_nop 0
	v_pk_add_f32 v[12:13], v[12:13], v[8:9]
	s_nop 0
	v_pk_add_f32 v[12:13], v[6:7], v[12:13]
	s_nop 0
	v_pk_add_f32 v[12:13], v[4:5], v[12:13]
	s_nop 0
	v_pk_add_f32 v[12:13], v[0:1], v[12:13]
	s_nop 0
	v_add_f32_e32 v12, v12, v13
	s_nop 1
	v_add_f32_dpp v12, v12, v12 quad_perm:[1,0,3,2] row_mask:0xf bank_mask:0xf
	s_nop 1
	v_add_f32_dpp v12, v12, v12 quad_perm:[2,3,0,1] row_mask:0xf bank_mask:0xf
	s_nop 1
	v_add_f32_dpp v12, v12, v12 row_half_mirror row_mask:0xf bank_mask:0xf
	s_nop 1
	v_add_f32_dpp v12, v12, v12 row_mirror row_mask:0xf bank_mask:0xf
	v_mov_b32_e32 v13, v12
	s_nop 1
	v_permlane16_swap_b32_e32 v12, v13
	s_waitcnt lgkmcnt(0)
	v_add_f32_e32 v12, v12, v13
	v_mov_b32_e32 v13, v12
	s_nop 1
	v_permlane32_swap_b32_e32 v12, v13
	s_waitcnt lgkmcnt(0)
	v_add_f32_e32 v12, v12, v13
	v_mul_f32_e32 v12, 0x3a800000, v12
	v_pk_add_f32 v[108:109], v[104:105], v[12:13] op_sel_hi:[1,0] neg_lo:[0,1] neg_hi:[0,1]
	v_pk_add_f32 v[104:105], v[106:107], v[12:13] op_sel_hi:[1,0] neg_lo:[0,1] neg_hi:[0,1]
	v_pk_add_f32 v[80:81], v[102:103], v[12:13] op_sel_hi:[1,0] neg_lo:[0,1] neg_hi:[0,1]
	v_pk_mul_f32 v[14:15], v[104:105], v[104:105]
	v_pk_add_f32 v[74:75], v[100:101], v[12:13] op_sel_hi:[1,0] neg_lo:[0,1] neg_hi:[0,1]
	v_pk_fma_f32 v[14:15], v[108:109], v[108:109], v[14:15]
	v_pk_add_f32 v[52:53], v[8:9], v[12:13] op_sel_hi:[1,0] neg_lo:[0,1] neg_hi:[0,1]
	v_pk_fma_f32 v[14:15], v[80:81], v[80:81], v[14:15]
	v_pk_add_f32 v[48:49], v[6:7], v[12:13] op_sel_hi:[1,0] neg_lo:[0,1] neg_hi:[0,1]
	v_pk_fma_f32 v[14:15], v[74:75], v[74:75], v[14:15]
	v_pk_add_f32 v[42:43], v[4:5], v[12:13] op_sel_hi:[1,0] neg_lo:[0,1] neg_hi:[0,1]
	v_pk_fma_f32 v[8:9], v[52:53], v[52:53], v[14:15]
	v_pk_add_f32 v[36:37], v[0:1], v[12:13] op_sel_hi:[1,0] neg_lo:[0,1] neg_hi:[0,1]
	v_pk_fma_f32 v[6:7], v[48:49], v[48:49], v[8:9]
	s_nop 0
	v_pk_fma_f32 v[4:5], v[42:43], v[42:43], v[6:7]
	s_nop 0
	v_pk_fma_f32 v[0:1], v[36:37], v[36:37], v[4:5]
	v_mov_b32_e32 v5, v10
	v_mov_b32_e32 v4, v0
	v_mov_b32_e32 v10, v1
	v_pk_add_f32 v[0:1], v[4:5], v[10:11]
	s_nop 1
	v_add_f32_dpp v0, v0, v0 quad_perm:[1,0,3,2] row_mask:0xf bank_mask:0xf
	v_add_f32_dpp v1, v1, v1 quad_perm:[1,0,3,2] row_mask:0xf bank_mask:0xf
	s_nop 1
	v_add_f32_dpp v0, v0, v0 quad_perm:[2,3,0,1] row_mask:0xf bank_mask:0xf
	v_add_f32_dpp v1, v1, v1 quad_perm:[2,3,0,1] row_mask:0xf bank_mask:0xf
	s_nop 1
	v_add_f32_dpp v0, v0, v0 row_half_mirror row_mask:0xf bank_mask:0xf
	v_add_f32_dpp v1, v1, v1 row_half_mirror row_mask:0xf bank_mask:0xf
	s_nop 1
	v_add_f32_dpp v0, v0, v0 row_mirror row_mask:0xf bank_mask:0xf
	v_add_f32_dpp v1, v1, v1 row_mirror row_mask:0xf bank_mask:0xf
	v_mov_b32_e32 v5, v1
	v_mov_b32_e32 v4, v0
	s_nop 1
	v_permlane16_swap_b32_e32 v1, v5
	v_permlane16_swap_b32_e32 v0, v4
	s_waitcnt lgkmcnt(0)
; __device__ __forceinline__ unsigned cvt_pk_bf16(float lo, float hi) { unsigned r; asm volatile("v_cvt_pk_bf16_f32 %0, %1, %2" : "=v"(r) : "v"(lo), "v"(hi)); return r; }
; __device__ __forceinline__ void conv_phase(LAS unsigned char* lds, const bf16_t* U, bf16_t* C, const float* wdw, const float* bdw, const float* lng, const float* lnb,
;                                            int first, int stride, int end, int tid, int wave, int lane) {
;     ...
;         float mean[4], rstd[4];
; #pragma unroll
;         for (int j = 0; j < 4; ++j) { f32x2 s2 = (f32x2){0.f, 0.f};
; #pragma unroll
;             for (int p = 0; p < 2; ++p)
; #pragma unroll
;                 for (int c = 0; c < 4; ++c) s2 += acc[p][j][c];
;             mean[j] = wave_sum(s2.x + s2.y) * (1.f / D); f32x2 q2 = (f32x2){0.f, 0.f};
; #pragma unroll
;             for (int p = 0; p < 2; ++p)
; #pragma unroll
;                 for (int c = 0; c < 4; ++c) { const f32x2 d = acc[p][j][c] - mean[j]; q2 += d * d; }
;             rstd[j] = rsqrtf(wave_sum(q2.x + q2.y) * (1.f / D) + LN_EPS); }
; #pragma unroll
;         for (int p = 0; p < 2; ++p) {
;             const f32x4 g0 = *(const f32x4*)(lng + p * 512 + lane * 8), g1 = *(const f32x4*)(lng + p * 512 + lane * 8 + 4);
;             const f32x4 c0 = *(const f32x4*)(lnb + p * 512 + lane * 8), c1 = *(const f32x4*)(lnb + p * 512 + lane * 8 + 4);
;             const f32x2 gg2[4] = {(f32x2){g0.x, g0.y}, (f32x2){g0.z, g0.w}, (f32x2){g1.x, g1.y}, (f32x2){g1.z, g1.w}}, bb2[4] = {(f32x2){c0.x, c0.y}, (f32x2){c0.z, c0.w}, (f32x2){c1.x, c1.y}, (f32x2){c1.z, c1.w}};
; #pragma unroll
;             for (int j = 0; j < 4; ++j) { unsigned wv[4];
; #pragma unroll
;                 for (int c = 0; c < 4; ++c) {
;                     const f32x2 y = __builtin_elementwise_fma(acc[p][j][c] - mean[j], gg2[c] * rstd[j], bb2[c]);
;                     const f32x2 ne = y * (-LOG2E);
;                     const f32x2 dd = (f32x2){__builtin_amdgcn_exp2f(ne.x), __builtin_amdgcn_exp2f(ne.y)} + 1.0f;
;                     const f32x2 oo = y * (f32x2){__builtin_amdgcn_rcpf(dd.x), __builtin_amdgcn_rcpf(dd.y)};
;                     wv[c] = cvt_pk_bf16(oo.x, oo.y); }
;                 u32x4 w; w.x = wv[0]; w.y = wv[1]; w.z = wv[2]; w.w = wv[3];
;                 *(u32x4*)(C + (size_t)(t0 + 4 * wave + j) * D + p * 512 + lane * 8) = w; }
	v_pk_add_f32 v[0:1], v[0:1], v[4:5]
	v_mov_b32_e32 v5, v1
	v_mov_b32_e32 v4, v0
	s_nop 1
	v_permlane32_swap_b32_e32 v1, v5
	v_permlane32_swap_b32_e32 v0, v4
	v_add_u32_e32 v76, s48, v141
	v_ashrrev_i32_e32 v77, 31, v76
	s_waitcnt lgkmcnt(0)
	v_pk_add_f32 v[0:1], v[0:1], v[4:5]
	s_nop 0
	v_pk_fma_f32 v[0:1], v[0:1], s[4:5], v[2:3] op_sel_hi:[1,0,0]
	s_nop 0
	v_mul_f32_e32 v2, 0x4b800000, v1
	v_cmp_gt_f32_e64 s[42:43], s7, v1
	v_cmp_gt_f32_e64 s[40:41], s7, v0
	s_nop 0
	v_cndmask_b32_e64 v1, v1, v2, s[42:43]
	v_rsq_f32_e32 v1, v1
	s_nop 0
	v_mul_f32_e32 v2, 0x45800000, v1
	v_cndmask_b32_e64 v54, v1, v2, s[42:43]
	v_mul_f32_e32 v1, 0x4b800000, v0
	v_cndmask_b32_e64 v0, v0, v1, s[40:41]
	v_rsq_f32_e32 v0, v0
	s_nop 0
	v_mul_f32_e32 v1, 0x45800000, v0
	v_cndmask_b32_e64 v44, v0, v1, s[40:41]
	v_mov_b64_e32 v[0:1], v[196:197]
	v_mov_b64_e32 v[2:3], v[198:199]
	v_mov_b64_e32 v[8:9], v[200:201]
	v_mov_b64_e32 v[10:11], v[202:203]
	v_mov_b64_e32 v[4:5], v[204:205]
	v_mov_b64_e32 v[6:7], v[206:207]
	v_mov_b64_e32 v[12:13], v[208:209]
	v_mov_b64_e32 v[14:15], v[210:211]
	v_cmp_le_i32_e64 s[40:41], s37, v140
	s_or_b64 s[46:47], s[40:41], s[46:47]
	s_waitcnt vmcnt(2)
	v_pk_mul_f32 v[100:101], v[40:41], v[8:9] op_sel_hi:[0,1]
	s_waitcnt vmcnt(0)
	v_pk_fma_f32 v[66:67], v[66:67], v[100:101], v[12:13]
	s_nop 0
	v_pk_mul_f32 v[100:101], v[66:67], s[8:9] op_sel_hi:[1,0]
	s_nop 0
	v_exp_f32_e32 v100, v100
	v_exp_f32_e32 v101, v101
	s_nop 0
	v_pk_add_f32 v[100:101], v[100:101], 1.0 op_sel_hi:[1,0]
	s_nop 0
	v_rcp_f32_e32 v100, v100
	v_rcp_f32_e32 v101, v101
	s_nop 0
	v_pk_mul_f32 v[66:67], v[66:67], v[100:101]
	s_nop 0
	v_cvt_pk_bf16_f32 v100, v66, v67
	v_pk_mul_f32 v[66:67], v[40:41], v[10:11] op_sel_hi:[0,1]
	v_pk_fma_f32 v[62:63], v[62:63], v[66:67], v[14:15]
	s_nop 0
	v_pk_mul_f32 v[66:67], v[62:63], s[8:9] op_sel_hi:[1,0]
	s_nop 0
	v_exp_f32_e32 v66, v66
	v_exp_f32_e32 v67, v67
	s_nop 0
	v_pk_add_f32 v[66:67], v[66:67], 1.0 op_sel_hi:[1,0]
	s_nop 0
	v_rcp_f32_e32 v66, v66
	v_rcp_f32_e32 v67, v67
	s_nop 0
	v_pk_mul_f32 v[62:63], v[62:63], v[66:67]
	s_nop 0
	v_cvt_pk_bf16_f32 v101, v62, v63
	v_pk_mul_f32 v[62:63], v[40:41], v[0:1] op_sel_hi:[0,1]
	v_pk_fma_f32 v[58:59], v[58:59], v[62:63], v[4:5]
	s_nop 0
	v_pk_mul_f32 v[62:63], v[58:59], s[8:9] op_sel_hi:[1,0]
	s_nop 0
	v_exp_f32_e32 v62, v62
	v_exp_f32_e32 v63, v63
	s_nop 0
	v_pk_add_f32 v[62:63], v[62:63], 1.0 op_sel_hi:[1,0]
	s_nop 0
	v_rcp_f32_e32 v62, v62
	v_rcp_f32_e32 v63, v63
	s_nop 0
	v_pk_mul_f32 v[58:59], v[58:59], v[62:63]
	s_nop 0
	v_cvt_pk_bf16_f32 v102, v58, v59
	v_pk_mul_f32 v[58:59], v[40:41], v[2:3] op_sel_hi:[0,1]
	v_pk_fma_f32 v[56:57], v[56:57], v[58:59], v[6:7]
	s_nop 0
	v_pk_mul_f32 v[58:59], v[56:57], s[8:9] op_sel_hi:[1,0]
	s_nop 0
	v_exp_f32_e32 v58, v58
	v_exp_f32_e32 v59, v59
	s_nop 0
	v_pk_add_f32 v[58:59], v[58:59], 1.0 op_sel_hi:[1,0]
	s_nop 0
	v_rcp_f32_e32 v58, v58
	v_rcp_f32_e32 v59, v59
	s_nop 0
	v_pk_mul_f32 v[56:57], v[56:57], v[58:59]
	v_pk_mul_f32 v[58:59], v[26:27], v[8:9] op_sel_hi:[0,1]
	v_pk_fma_f32 v[58:59], v[70:71], v[58:59], v[12:13]
	v_cvt_pk_bf16_f32 v103, v56, v57
	v_lshlrev_b64 v[56:57], 11, v[76:77]
	v_pk_mul_f32 v[62:63], v[58:59], s[8:9] op_sel_hi:[1,0]
	v_lshl_add_u64 v[56:57], v[92:93], 0, v[56:57]
	v_exp_f32_e32 v62, v62
	v_exp_f32_e32 v63, v63
	global_store_dwordx4 v[56:57], v[100:103], off
	v_pk_add_f32 v[62:63], v[62:63], 1.0 op_sel_hi:[1,0]
	s_nop 0
	v_rcp_f32_e32 v62, v62
	v_rcp_f32_e32 v63, v63
	s_nop 0
	v_pk_mul_f32 v[58:59], v[58:59], v[62:63]
	s_nop 0
	v_cvt_pk_bf16_f32 v62, v58, v59
	v_pk_mul_f32 v[58:59], v[26:27], v[10:11] op_sel_hi:[0,1]
	v_pk_fma_f32 v[58:59], v[68:69], v[58:59], v[14:15]
	s_nop 0
	v_pk_mul_f32 v[66:67], v[58:59], s[8:9] op_sel_hi:[1,0]
	s_nop 0
	v_exp_f32_e32 v66, v66
	v_exp_f32_e32 v67, v67
	s_nop 0
	v_pk_add_f32 v[66:67], v[66:67], 1.0 op_sel_hi:[1,0]
	s_nop 0
	v_rcp_f32_e32 v66, v66
	v_rcp_f32_e32 v67, v67
	s_nop 0
	v_pk_mul_f32 v[58:59], v[58:59], v[66:67]
	s_nop 0
	v_cvt_pk_bf16_f32 v63, v58, v59
	v_pk_mul_f32 v[58:59], v[26:27], v[0:1] op_sel_hi:[0,1]
	v_pk_fma_f32 v[58:59], v[64:65], v[58:59], v[4:5]
	s_nop 0
	v_pk_mul_f32 v[64:65], v[58:59], s[8:9] op_sel_hi:[1,0]
	s_nop 0
	v_exp_f32_e32 v64, v64
	v_exp_f32_e32 v65, v65
	s_nop 0
	v_pk_add_f32 v[64:65], v[64:65], 1.0 op_sel_hi:[1,0]
	s_nop 0
	v_rcp_f32_e32 v64, v64
	v_rcp_f32_e32 v65, v65
	s_nop 0
	v_pk_mul_f32 v[58:59], v[58:59], v[64:65]
	s_nop 0
	v_cvt_pk_bf16_f32 v64, v58, v59
	v_pk_mul_f32 v[58:59], v[26:27], v[2:3] op_sel_hi:[0,1]
	v_pk_fma_f32 v[58:59], v[60:61], v[58:59], v[6:7]
	s_nop 0
	v_pk_mul_f32 v[60:61], v[58:59], s[8:9] op_sel_hi:[1,0]
	s_nop 0
	v_exp_f32_e32 v60, v60
	v_exp_f32_e32 v61, v61
	s_nop 0
	v_pk_add_f32 v[60:61], v[60:61], 1.0 op_sel_hi:[1,0]
	s_nop 0
	v_rcp_f32_e32 v60, v60
	v_rcp_f32_e32 v61, v61
	s_nop 0
	v_pk_mul_f32 v[58:59], v[58:59], v[60:61]
	s_nop 0
	v_cvt_pk_bf16_f32 v65, v58, v59
	v_or_b32_e32 v58, 1, v76
	v_ashrrev_i32_e32 v59, 31, v58
	v_lshlrev_b64 v[58:59], 11, v[58:59]
	v_pk_mul_f32 v[60:61], v[8:9], v[54:55] op_sel_hi:[1,0]
	v_lshl_add_u64 v[58:59], v[92:93], 0, v[58:59]
	v_pk_fma_f32 v[60:61], v[112:113], v[60:61], v[12:13]
	global_store_dwordx4 v[58:59], v[62:65], off
	v_pk_mul_f32 v[8:9], v[8:9], v[44:45] op_sel_hi:[1,0]
	s_nop 0
	v_pk_mul_f32 v[62:63], v[60:61], s[8:9] op_sel_hi:[1,0]
	v_pk_fma_f32 v[8:9], v[108:109], v[8:9], v[12:13]
	v_exp_f32_e32 v62, v62
	v_exp_f32_e32 v63, v63
	v_pk_mul_f32 v[12:13], v[8:9], s[8:9] op_sel_hi:[1,0]
	v_pk_add_f32 v[62:63], v[62:63], 1.0 op_sel_hi:[1,0]
	s_nop 0
	v_rcp_f32_e32 v62, v62
	v_rcp_f32_e32 v63, v63
	v_exp_f32_e32 v12, v12
	v_exp_f32_e32 v13, v13
; __device__ __forceinline__ unsigned cvt_pk_bf16(float lo, float hi) { unsigned r; asm volatile("v_cvt_pk_bf16_f32 %0, %1, %2" : "=v"(r) : "v"(lo), "v"(hi)); return r; }
; __device__ __forceinline__ void conv_phase(LAS unsigned char* lds, const bf16_t* U, bf16_t* C, const float* wdw, const float* bdw, const float* lng, const float* lnb,
;                                            int first, int stride, int end, int tid, int wave, int lane) {
;     ...
; #pragma unroll
;         for (int p = 0; p < 2; ++p) {
;             const f32x4 g0 = *(const f32x4*)(lng + p * 512 + lane * 8), g1 = *(const f32x4*)(lng + p * 512 + lane * 8 + 4);
;             const f32x4 c0 = *(const f32x4*)(lnb + p * 512 + lane * 8), c1 = *(const f32x4*)(lnb + p * 512 + lane * 8 + 4);
;             const f32x2 gg2[4] = {(f32x2){g0.x, g0.y}, (f32x2){g0.z, g0.w}, (f32x2){g1.x, g1.y}, (f32x2){g1.z, g1.w}}, bb2[4] = {(f32x2){c0.x, c0.y}, (f32x2){c0.z, c0.w}, (f32x2){c1.x, c1.y}, (f32x2){c1.z, c1.w}};
; #pragma unroll
;             for (int j = 0; j < 4; ++j) { unsigned wv[4];
; #pragma unroll
;                 for (int c = 0; c < 4; ++c) {
;                     const f32x2 y = __builtin_elementwise_fma(acc[p][j][c] - mean[j], gg2[c] * rstd[j], bb2[c]);
;                     const f32x2 ne = y * (-LOG2E);
;                     const f32x2 dd = (f32x2){__builtin_amdgcn_exp2f(ne.x), __builtin_amdgcn_exp2f(ne.y)} + 1.0f;
;                     const f32x2 oo = y * (f32x2){__builtin_amdgcn_rcpf(dd.x), __builtin_amdgcn_rcpf(dd.y)};
;                     wv[c] = cvt_pk_bf16(oo.x, oo.y); }
;                 u32x4 w; w.x = wv[0]; w.y = wv[1]; w.z = wv[2]; w.w = wv[3];
;                 *(u32x4*)(C + (size_t)(t0 + 4 * wave + j) * D + p * 512 + lane * 8) = w; }
	v_pk_mul_f32 v[60:61], v[60:61], v[62:63]
	s_nop 0
	v_cvt_pk_bf16_f32 v62, v60, v61
	v_pk_mul_f32 v[60:61], v[10:11], v[54:55] op_sel_hi:[1,0]
	v_pk_add_f32 v[12:13], v[12:13], 1.0 op_sel_hi:[1,0]
	v_pk_fma_f32 v[60:61], v[82:83], v[60:61], v[14:15]
	v_rcp_f32_e32 v12, v12
	v_pk_mul_f32 v[64:65], v[60:61], s[8:9] op_sel_hi:[1,0]
	v_rcp_f32_e32 v13, v13
	v_exp_f32_e32 v64, v64
	v_exp_f32_e32 v65, v65
	v_pk_mul_f32 v[10:11], v[10:11], v[44:45] op_sel_hi:[1,0]
	v_pk_mul_f32 v[8:9], v[8:9], v[12:13]
	v_pk_fma_f32 v[10:11], v[104:105], v[10:11], v[14:15]
	v_pk_add_f32 v[64:65], v[64:65], 1.0 op_sel_hi:[1,0]
	v_pk_mul_f32 v[12:13], v[10:11], s[8:9] op_sel_hi:[1,0]
	v_rcp_f32_e32 v64, v64
	v_rcp_f32_e32 v65, v65
	v_exp_f32_e32 v12, v12
	v_exp_f32_e32 v13, v13
	v_pk_mul_f32 v[60:61], v[60:61], v[64:65]
	s_nop 0
	v_cvt_pk_bf16_f32 v63, v60, v61
	v_pk_mul_f32 v[60:61], v[0:1], v[54:55] op_sel_hi:[1,0]
	v_pk_mul_f32 v[0:1], v[0:1], v[44:45] op_sel_hi:[1,0]
	v_pk_fma_f32 v[60:61], v[78:79], v[60:61], v[4:5]
	v_pk_fma_f32 v[0:1], v[80:81], v[0:1], v[4:5]
	v_pk_mul_f32 v[64:65], v[60:61], s[8:9] op_sel_hi:[1,0]
	v_pk_mul_f32 v[4:5], v[0:1], s[8:9] op_sel_hi:[1,0]
	v_exp_f32_e32 v64, v64
	v_exp_f32_e32 v65, v65
	v_exp_f32_e32 v4, v4
	v_exp_f32_e32 v5, v5
	v_pk_add_f32 v[12:13], v[12:13], 1.0 op_sel_hi:[1,0]
	v_pk_add_f32 v[64:65], v[64:65], 1.0 op_sel_hi:[1,0]
	v_rcp_f32_e32 v12, v12
	v_rcp_f32_e32 v64, v64
	v_rcp_f32_e32 v65, v65
	v_pk_add_f32 v[4:5], v[4:5], 1.0 op_sel_hi:[1,0]
	v_rcp_f32_e32 v13, v13
	v_rcp_f32_e32 v4, v4
	v_pk_mul_f32 v[60:61], v[60:61], v[64:65]
	v_rcp_f32_e32 v5, v5
	v_cvt_pk_bf16_f32 v64, v60, v61
	v_pk_mul_f32 v[60:61], v[2:3], v[54:55] op_sel_hi:[1,0]
	v_pk_mul_f32 v[10:11], v[10:11], v[12:13]
	v_pk_fma_f32 v[60:61], v[72:73], v[60:61], v[6:7]
	v_pk_mul_f32 v[0:1], v[0:1], v[4:5]
	v_pk_mul_f32 v[66:67], v[60:61], s[8:9] op_sel_hi:[1,0]
	s_nop 0
	v_exp_f32_e32 v66, v66
	v_exp_f32_e32 v67, v67
	s_nop 0
	v_pk_add_f32 v[66:67], v[66:67], 1.0 op_sel_hi:[1,0]
	s_nop 0
	v_rcp_f32_e32 v66, v66
	v_rcp_f32_e32 v67, v67
	s_nop 0
	v_pk_mul_f32 v[60:61], v[60:61], v[66:67]
	s_nop 0
	v_cvt_pk_bf16_f32 v65, v60, v61
	v_or_b32_e32 v60, 2, v76
	v_ashrrev_i32_e32 v61, 31, v60
	v_lshlrev_b64 v[60:61], 11, v[60:61]
	v_lshl_add_u64 v[60:61], v[92:93], 0, v[60:61]
	global_store_dwordx4 v[60:61], v[62:65], off
	v_cvt_pk_bf16_f32 v8, v8, v9
	v_cvt_pk_bf16_f32 v9, v10, v11
	v_cvt_pk_bf16_f32 v10, v0, v1
	v_pk_mul_f32 v[0:1], v[2:3], v[44:45] op_sel_hi:[1,0]
	s_nop 0
	v_pk_fma_f32 v[0:1], v[74:75], v[0:1], v[6:7]
	s_nop 0
	v_pk_mul_f32 v[2:3], v[0:1], s[8:9] op_sel_hi:[1,0]
	s_nop 0
	v_exp_f32_e32 v2, v2
	v_exp_f32_e32 v3, v3
	s_nop 0
	v_pk_add_f32 v[2:3], v[2:3], 1.0 op_sel_hi:[1,0]
	s_nop 0
	v_rcp_f32_e32 v2, v2
	v_rcp_f32_e32 v3, v3
	s_nop 0
	v_pk_mul_f32 v[0:1], v[0:1], v[2:3]
	s_nop 0
	v_cvt_pk_bf16_f32 v11, v0, v1
	v_or_b32_e32 v0, 3, v76
	v_ashrrev_i32_e32 v1, 31, v0
	v_lshlrev_b64 v[0:1], 11, v[0:1]
	v_lshl_add_u64 v[62:63], v[92:93], 0, v[0:1]
	global_store_dwordx4 v[62:63], v[8:11], off
	v_mov_b64_e32 v[0:1], v[212:213]
	v_mov_b64_e32 v[2:3], v[214:215]
	s_nop 0
	v_mov_b64_e32 v[8:9], v[236:237]
	v_mov_b64_e32 v[10:11], v[238:239]
	v_mov_b64_e32 v[4:5], v[240:241]
	v_mov_b64_e32 v[6:7], v[242:243]
	v_mov_b64_e32 v[12:13], v[244:245]
	v_mov_b64_e32 v[14:15], v[246:247]
	v_pk_mul_f32 v[64:65], v[40:41], v[8:9] op_sel_hi:[0,1]
	v_pk_fma_f32 v[28:29], v[28:29], v[64:65], v[12:13]
	s_nop 0
	v_pk_mul_f32 v[64:65], v[28:29], s[8:9] op_sel_hi:[1,0]
	s_nop 0
	v_exp_f32_e32 v64, v64
	v_exp_f32_e32 v65, v65
	s_nop 0
	v_pk_add_f32 v[64:65], v[64:65], 1.0 op_sel_hi:[1,0]
	s_nop 0
	v_rcp_f32_e32 v64, v64
	v_rcp_f32_e32 v65, v65
	s_nop 0
	v_pk_mul_f32 v[28:29], v[28:29], v[64:65]
	s_nop 0
	v_cvt_pk_bf16_f32 v64, v28, v29
	v_pk_mul_f32 v[28:29], v[40:41], v[10:11] op_sel_hi:[0,1]
	v_pk_fma_f32 v[22:23], v[22:23], v[28:29], v[14:15]
	s_nop 0
	v_pk_mul_f32 v[28:29], v[22:23], s[8:9] op_sel_hi:[1,0]
	s_nop 0
	v_exp_f32_e32 v28, v28
	v_exp_f32_e32 v29, v29
	s_nop 0
	v_pk_add_f32 v[28:29], v[28:29], 1.0 op_sel_hi:[1,0]
	s_nop 0
	v_rcp_f32_e32 v28, v28
	v_rcp_f32_e32 v29, v29
	s_nop 0
	v_pk_mul_f32 v[22:23], v[22:23], v[28:29]
	s_nop 0
	v_cvt_pk_bf16_f32 v65, v22, v23
	v_pk_mul_f32 v[22:23], v[40:41], v[0:1] op_sel_hi:[0,1]
	v_pk_fma_f32 v[18:19], v[18:19], v[22:23], v[4:5]
	s_nop 0
	v_pk_mul_f32 v[22:23], v[18:19], s[8:9] op_sel_hi:[1,0]
	s_nop 0
	v_exp_f32_e32 v22, v22
	v_exp_f32_e32 v23, v23
	s_nop 0
	v_pk_add_f32 v[22:23], v[22:23], 1.0 op_sel_hi:[1,0]
	s_nop 0
	v_rcp_f32_e32 v22, v22
	v_rcp_f32_e32 v23, v23
	s_nop 0
	v_pk_mul_f32 v[18:19], v[18:19], v[22:23]
	s_nop 0
	v_cvt_pk_bf16_f32 v66, v18, v19
	v_pk_mul_f32 v[18:19], v[40:41], v[2:3] op_sel_hi:[0,1]
	v_pk_fma_f32 v[16:17], v[16:17], v[18:19], v[6:7]
	s_nop 0
	v_pk_mul_f32 v[18:19], v[16:17], s[8:9] op_sel_hi:[1,0]
	s_nop 0
	v_exp_f32_e32 v18, v18
	v_exp_f32_e32 v19, v19
	s_nop 0
	v_pk_add_f32 v[18:19], v[18:19], 1.0 op_sel_hi:[1,0]
	s_nop 0
	v_rcp_f32_e32 v18, v18
	v_rcp_f32_e32 v19, v19
	s_nop 0
	v_pk_mul_f32 v[16:17], v[16:17], v[18:19]
	s_nop 0
	v_cvt_pk_bf16_f32 v67, v16, v17
	v_pk_mul_f32 v[16:17], v[26:27], v[8:9] op_sel_hi:[0,1]
; __device__ __forceinline__ unsigned cvt_pk_bf16(float lo, float hi) { unsigned r; asm volatile("v_cvt_pk_bf16_f32 %0, %1, %2" : "=v"(r) : "v"(lo), "v"(hi)); return r; }
; __device__ __forceinline__ void conv_phase(LAS unsigned char* lds, const bf16_t* U, bf16_t* C, const float* wdw, const float* bdw, const float* lng, const float* lnb,
;                                            int first, int stride, int end, int tid, int wave, int lane) {
;     ...
; #pragma unroll
;         for (int p = 0; p < 2; ++p) {
;             const f32x4 g0 = *(const f32x4*)(lng + p * 512 + lane * 8), g1 = *(const f32x4*)(lng + p * 512 + lane * 8 + 4);
;             const f32x4 c0 = *(const f32x4*)(lnb + p * 512 + lane * 8), c1 = *(const f32x4*)(lnb + p * 512 + lane * 8 + 4);
;             const f32x2 gg2[4] = {(f32x2){g0.x, g0.y}, (f32x2){g0.z, g0.w}, (f32x2){g1.x, g1.y}, (f32x2){g1.z, g1.w}}, bb2[4] = {(f32x2){c0.x, c0.y}, (f32x2){c0.z, c0.w}, (f32x2){c1.x, c1.y}, (f32x2){c1.z, c1.w}};
; #pragma unroll
;             for (int j = 0; j < 4; ++j) { unsigned wv[4];
; #pragma unroll
;                 for (int c = 0; c < 4; ++c) {
;                     const f32x2 y = __builtin_elementwise_fma(acc[p][j][c] - mean[j], gg2[c] * rstd[j], bb2[c]);
;                     const f32x2 ne = y * (-LOG2E);
;                     const f32x2 dd = (f32x2){__builtin_amdgcn_exp2f(ne.x), __builtin_amdgcn_exp2f(ne.y)} + 1.0f;
;                     const f32x2 oo = y * (f32x2){__builtin_amdgcn_rcpf(dd.x), __builtin_amdgcn_rcpf(dd.y)};
;                     wv[c] = cvt_pk_bf16(oo.x, oo.y); }
;                 u32x4 w; w.x = wv[0]; w.y = wv[1]; w.z = wv[2]; w.w = wv[3];
;                 *(u32x4*)(C + (size_t)(t0 + 4 * wave + j) * D + p * 512 + lane * 8) = w; }
;         }
;         asm volatile("s_waitcnt lgkmcnt(0)" ::: "memory"); __builtin_amdgcn_s_barrier(); asm volatile("" ::: "memory");
	v_pk_fma_f32 v[16:17], v[32:33], v[16:17], v[12:13]
	global_store_dwordx4 v[56:57], v[64:67], off offset:1024
	v_pk_mul_f32 v[18:19], v[16:17], s[8:9] op_sel_hi:[1,0]
	s_nop 0
	v_exp_f32_e32 v18, v18
	v_exp_f32_e32 v19, v19
	s_nop 0
	v_pk_add_f32 v[18:19], v[18:19], 1.0 op_sel_hi:[1,0]
	s_nop 0
	v_rcp_f32_e32 v18, v18
	v_rcp_f32_e32 v19, v19
	s_nop 0
	v_pk_mul_f32 v[16:17], v[16:17], v[18:19]
	v_pk_mul_f32 v[18:19], v[26:27], v[10:11] op_sel_hi:[0,1]
	v_pk_fma_f32 v[18:19], v[30:31], v[18:19], v[14:15]
	v_cvt_pk_bf16_f32 v16, v16, v17
	s_nop 0
	v_pk_mul_f32 v[22:23], v[18:19], s[8:9] op_sel_hi:[1,0]
	s_nop 0
	v_exp_f32_e32 v22, v22
	v_exp_f32_e32 v23, v23
	s_nop 0
	v_pk_add_f32 v[22:23], v[22:23], 1.0 op_sel_hi:[1,0]
	s_nop 0
	v_rcp_f32_e32 v22, v22
	v_rcp_f32_e32 v23, v23
	s_nop 0
	v_pk_mul_f32 v[18:19], v[18:19], v[22:23]
	s_nop 0
	v_cvt_pk_bf16_f32 v17, v18, v19
	v_pk_mul_f32 v[18:19], v[26:27], v[0:1] op_sel_hi:[0,1]
	v_pk_fma_f32 v[18:19], v[24:25], v[18:19], v[4:5]
	s_nop 0
	v_pk_mul_f32 v[22:23], v[18:19], s[8:9] op_sel_hi:[1,0]
	s_nop 0
	v_exp_f32_e32 v22, v22
	v_exp_f32_e32 v23, v23
	s_nop 0
	v_pk_add_f32 v[22:23], v[22:23], 1.0 op_sel_hi:[1,0]
	s_nop 0
	v_rcp_f32_e32 v22, v22
	v_rcp_f32_e32 v23, v23
	s_nop 0
	v_pk_mul_f32 v[18:19], v[18:19], v[22:23]
	v_pk_mul_f32 v[22:23], v[26:27], v[2:3] op_sel_hi:[0,1]
	v_pk_fma_f32 v[20:21], v[20:21], v[22:23], v[6:7]
	v_cvt_pk_bf16_f32 v18, v18, v19
	s_nop 0
	v_pk_mul_f32 v[22:23], v[20:21], s[8:9] op_sel_hi:[1,0]
	s_nop 0
	v_exp_f32_e32 v22, v22
	v_exp_f32_e32 v23, v23
	s_nop 0
	v_pk_add_f32 v[22:23], v[22:23], 1.0 op_sel_hi:[1,0]
	s_nop 0
	v_rcp_f32_e32 v22, v22
	v_rcp_f32_e32 v23, v23
	s_nop 0
	v_pk_mul_f32 v[20:21], v[20:21], v[22:23]
	s_nop 0
	v_cvt_pk_bf16_f32 v19, v20, v21
	global_store_dwordx4 v[58:59], v[16:19], off offset:1024
	s_nop 1
	v_pk_mul_f32 v[16:17], v[54:55], v[8:9] op_sel_hi:[0,1]
	v_pk_fma_f32 v[16:17], v[50:51], v[16:17], v[12:13]
	v_pk_mul_f32 v[8:9], v[44:45], v[8:9] op_sel_hi:[0,1]
	v_pk_mul_f32 v[18:19], v[16:17], s[8:9] op_sel_hi:[1,0]
	v_pk_fma_f32 v[8:9], v[52:53], v[8:9], v[12:13]
	v_exp_f32_e32 v18, v18
	v_exp_f32_e32 v19, v19
	v_pk_mul_f32 v[12:13], v[8:9], s[8:9] op_sel_hi:[1,0]
	v_pk_add_f32 v[18:19], v[18:19], 1.0 op_sel_hi:[1,0]
	s_nop 0
	v_rcp_f32_e32 v18, v18
	v_rcp_f32_e32 v19, v19
	v_exp_f32_e32 v12, v12
	v_exp_f32_e32 v13, v13
	v_pk_mul_f32 v[16:17], v[16:17], v[18:19]
	v_pk_mul_f32 v[18:19], v[54:55], v[10:11] op_sel_hi:[0,1]
	v_pk_fma_f32 v[18:19], v[46:47], v[18:19], v[14:15]
	v_cvt_pk_bf16_f32 v16, v16, v17
	v_pk_add_f32 v[12:13], v[12:13], 1.0 op_sel_hi:[1,0]
	v_pk_mul_f32 v[20:21], v[18:19], s[8:9] op_sel_hi:[1,0]
	v_rcp_f32_e32 v12, v12
	v_exp_f32_e32 v20, v20
	v_exp_f32_e32 v21, v21
	v_rcp_f32_e32 v13, v13
	v_pk_mul_f32 v[10:11], v[44:45], v[10:11] op_sel_hi:[0,1]
	v_pk_fma_f32 v[10:11], v[48:49], v[10:11], v[14:15]
	v_pk_add_f32 v[20:21], v[20:21], 1.0 op_sel_hi:[1,0]
	v_pk_mul_f32 v[8:9], v[8:9], v[12:13]
	v_rcp_f32_e32 v20, v20
	v_rcp_f32_e32 v21, v21
	v_pk_mul_f32 v[12:13], v[10:11], s[8:9] op_sel_hi:[1,0]
	v_pk_mul_f32 v[18:19], v[18:19], v[20:21]
	s_nop 0
	v_cvt_pk_bf16_f32 v17, v18, v19
	v_pk_mul_f32 v[18:19], v[54:55], v[0:1] op_sel_hi:[0,1]
	v_pk_fma_f32 v[18:19], v[38:39], v[18:19], v[4:5]
	v_pk_mul_f32 v[0:1], v[44:45], v[0:1] op_sel_hi:[0,1]
	v_pk_mul_f32 v[20:21], v[18:19], s[8:9] op_sel_hi:[1,0]
	v_pk_fma_f32 v[0:1], v[42:43], v[0:1], v[4:5]
	v_exp_f32_e32 v20, v20
	v_exp_f32_e32 v21, v21
	v_pk_mul_f32 v[4:5], v[0:1], s[8:9] op_sel_hi:[1,0]
	v_exp_f32_e32 v12, v12
	v_exp_f32_e32 v13, v13
	v_pk_add_f32 v[20:21], v[20:21], 1.0 op_sel_hi:[1,0]
	v_exp_f32_e32 v4, v4
	v_rcp_f32_e32 v20, v20
	v_rcp_f32_e32 v21, v21
	v_exp_f32_e32 v5, v5
	v_pk_add_f32 v[12:13], v[12:13], 1.0 op_sel_hi:[1,0]
	v_pk_mul_f32 v[18:19], v[18:19], v[20:21]
	v_pk_mul_f32 v[20:21], v[54:55], v[2:3] op_sel_hi:[0,1]
	v_pk_fma_f32 v[20:21], v[34:35], v[20:21], v[6:7]
	v_pk_add_f32 v[4:5], v[4:5], 1.0 op_sel_hi:[1,0]
	v_pk_mul_f32 v[22:23], v[20:21], s[8:9] op_sel_hi:[1,0]
	v_rcp_f32_e32 v12, v12
	v_exp_f32_e32 v22, v22
	v_exp_f32_e32 v23, v23
	v_rcp_f32_e32 v13, v13
	v_rcp_f32_e32 v4, v4
	v_rcp_f32_e32 v5, v5
	v_pk_add_f32 v[22:23], v[22:23], 1.0 op_sel_hi:[1,0]
	v_pk_mul_f32 v[10:11], v[10:11], v[12:13]
	v_rcp_f32_e32 v22, v22
	v_rcp_f32_e32 v23, v23
	v_pk_mul_f32 v[0:1], v[0:1], v[4:5]
	v_cvt_pk_bf16_f32 v18, v18, v19
	v_pk_mul_f32 v[20:21], v[20:21], v[22:23]
	s_nop 0
	v_cvt_pk_bf16_f32 v19, v20, v21
	global_store_dwordx4 v[60:61], v[16:19], off offset:1024
	v_cvt_pk_bf16_f32 v8, v8, v9
	v_cvt_pk_bf16_f32 v9, v10, v11
	v_cvt_pk_bf16_f32 v10, v0, v1
	v_pk_mul_f32 v[0:1], v[44:45], v[2:3] op_sel_hi:[0,1]
	v_pk_fma_f32 v[0:1], v[36:37], v[0:1], v[6:7]
	s_nop 0
	v_pk_mul_f32 v[2:3], v[0:1], s[8:9] op_sel_hi:[1,0]
	s_nop 0
	v_exp_f32_e32 v2, v2
	v_exp_f32_e32 v3, v3
	s_nop 0
	v_pk_add_f32 v[2:3], v[2:3], 1.0 op_sel_hi:[1,0]
	s_nop 0
	v_rcp_f32_e32 v2, v2
	v_rcp_f32_e32 v3, v3
	s_nop 0
	v_pk_mul_f32 v[0:1], v[0:1], v[2:3]
	s_nop 0
	v_cvt_pk_bf16_f32 v11, v0, v1
	global_store_dwordx4 v[62:63], v[8:11], off offset:1024
	s_waitcnt lgkmcnt(0)
	s_barrier
	s_andn2_b64 exec, exec, s[46:47]
	s_cbranch_execz .LBB0_95

; __device__ __forceinline__ unsigned cvt_pk_bf16(float lo, float hi) { unsigned r; asm volatile("v_cvt_pk_bf16_f32 %0, %1, %2" : "=v"(r) : "v"(lo), "v"(hi)); return r; }
;     __device__ __forceinline__ void operator()(const f32x4 (&acc)[2][2][4][2], const Unit& u, int wr, int wc, int fr, int fq, LAS unsigned char* lds, int tid, int ui, const Unit& nxt, bool has_next) const {
;     ...
;             for (int m = 0; m < 4; ++m) {
;                 const int row = row0 + ai * 128 + m * 16; const size_t off = (size_t)row * D + col0;
;                 typedef float f32x2 __attribute__((ext_vector_type(2)));
;                 f32x2 sq2 = (f32x2){0.f, 0.f};
; #pragma unroll
;                 for (int bj = 0; bj < 2; ++bj) {
;                     f32x2 v[4];
;                     const u32x4 w0 = xr[m][bj];
; #pragma unroll
;                     for (int i = 0; i < 4; ++i) v[i] = (f32x2){__uint_as_float(w0[i] << 16), __uint_as_float(w0[i] & 0xffff0000u)};
;                     const f32x2 al2 = (f32x2){alpha, alpha};
;                     unsigned wv[4];
; #pragma unroll
;                     for (int i = 0; i < 4; ++i) {
;                         const f32x4 av = acc[ai][bj][m][i >> 1], bb = bv[bj][i >> 1];
;                         const f32x2 a2 = (i & 1) ? (f32x2){av.z, av.w} : (f32x2){av.x, av.y}, b2 = (i & 1) ? (f32x2){bb.z, bb.w} : (f32x2){bb.x, bb.y};
;                         v[i] = __builtin_elementwise_fma(a2, al2, v[i]) + b2;
;                         sq2 = __builtin_elementwise_fma(v[i], v[i], sq2);
;                         wv[i] = cvt_pk_bf16(v[i].x, v[i].y);
;                     }
;                     u32x4 w; w.x = wv[0]; w.y = wv[1]; w.z = wv[2]; w.w = wv[3];
;                     *(u32x4*)(xb + off + bj * 128) = w;
;                 }
;                 float sq = sq2.x + sq2.y;
;                 sq += __shfl_xor(sq, 16); sq += __shfl_xor(sq, 32);
;                 if (fq == 0) ssp[(size_t)row * 16 + u.pn * 4 + wc] = sq;
;             }
.Lmy_epibar_resid:
	v_lshlrev_b32_e32 v216, 16, v172
	v_and_b32_e32 v217, 0xffff0000, v172
	v_lshlrev_b32_e32 v172, 16, v173
	v_and_b32_e32 v173, 0xffff0000, v173
	v_lshlrev_b32_e32 v242, 16, v170
	v_and_b32_e32 v243, 0xffff0000, v170
	v_lshlrev_b32_e32 v170, 16, v171
	v_and_b32_e32 v171, 0xffff0000, v171
	v_pk_fma_f32 v[140:141], v[140:141], s[26:27], v[216:217]
	v_lshlrev_b32_e32 v238, 16, v174
	v_and_b32_e32 v239, 0xffff0000, v174
	v_pk_fma_f32 v[142:143], v[142:143], s[26:27], v[172:173]
	v_pk_fma_f32 v[130:131], v[130:131], s[26:27], v[170:171]
	v_pk_add_f32 v[140:141], v[76:77], v[140:141]
	v_lshlrev_b32_e32 v174, 16, v175
	v_and_b32_e32 v175, 0xffff0000, v175
	v_pk_fma_f32 v[136:137], v[136:137], s[26:27], v[238:239]
	v_pk_add_f32 v[142:143], v[78:79], v[142:143]
	v_pk_add_f32 v[170:171], v[66:67], v[130:131]
	v_pk_fma_f32 v[130:131], v[140:141], v[140:141], 0 op_sel_hi:[1,1,0]
	v_lshlrev_b32_e32 v240, 16, v168
	v_and_b32_e32 v241, 0xffff0000, v168
	v_pk_fma_f32 v[138:139], v[138:139], s[26:27], v[174:175]
	v_pk_add_f32 v[136:137], v[68:69], v[136:137]
	v_pk_fma_f32 v[130:131], v[142:143], v[142:143], v[130:131]
	v_lshlrev_b32_e32 v168, 16, v169
	v_and_b32_e32 v169, 0xffff0000, v169
	v_pk_fma_f32 v[132:133], v[132:133], s[26:27], v[240:241]
	v_pk_add_f32 v[138:139], v[70:71], v[138:139]
	v_pk_fma_f32 v[130:131], v[136:137], v[136:137], v[130:131]
	v_pk_fma_f32 v[134:135], v[134:135], s[26:27], v[168:169]
	v_pk_add_f32 v[132:133], v[72:73], v[132:133]
	v_pk_fma_f32 v[130:131], v[138:139], v[138:139], v[130:131]
	v_pk_fma_f32 v[128:129], v[128:129], s[26:27], v[242:243]
	v_pk_add_f32 v[134:135], v[74:75], v[134:135]
	v_pk_fma_f32 v[130:131], v[132:133], v[132:133], v[130:131]
	v_pk_add_f32 v[168:169], v[64:65], v[128:129]
	v_pk_fma_f32 v[130:131], v[134:135], v[134:135], v[130:131]
	v_cvt_pk_bf16_f32 v128, v140, v141
	v_cndmask_b32_e32 v221, v224, v231, vcc
	v_pk_fma_f32 v[130:131], v[168:169], v[168:169], v[130:131]
	v_cvt_pk_bf16_f32 v129, v142, v143
	s_nop 0
	v_pk_fma_f32 v[130:131], v[170:171], v[170:171], v[130:131]
	s_nop 0
	v_add_f32_e32 v140, v130, v131
	v_mov_b32_e32 v141, v140
	s_nop 1
	v_permlane16_swap_b32_e32 v140, v141
	v_cvt_pk_bf16_f32 v130, v136, v137
	v_cvt_pk_bf16_f32 v131, v138, v139
	global_store_dwordx4 v[214:215], v[128:131], off
	v_cvt_pk_bf16_f32 v132, v132, v133
	v_cvt_pk_bf16_f32 v133, v134, v135
	v_cvt_pk_bf16_f32 v134, v168, v169
	v_cvt_pk_bf16_f32 v135, v170, v171
	global_store_dwordx4 v[214:215], v[132:135], off offset:256
	s_waitcnt lgkmcnt(0)
	v_add_f32_e32 v129, v140, v141
	v_lshlrev_b32_e32 v128, 2, v221
	v_mov_b32_e32 v130, v129
	s_nop 1
	v_permlane32_swap_b32_e32 v129, v130
	s_and_saveexec_b64 s[4:5], s[38:39]
	s_cbranch_execz .LBB0_206
	v_lshlrev_b64 v[132:133], 6, v[200:201]
	v_lshl_add_u64 v[132:133], s[48:49], 0, v[132:133]
	v_lshl_add_u64 v[132:133], s[42:43], 2, v[132:133]
	s_lshl_b32 s2, s62, 2
	v_lshl_add_u64 v[132:133], v[132:133], 0, s[2:3]
	s_waitcnt lgkmcnt(0)
	v_add_f32_e32 v129, v129, v130
	global_store_dword v[132:133], v129, off
.LBB0_206:
	s_or_b64 exec, exec, s[4:5]
	s_waitcnt lgkmcnt(0)
	v_lshlrev_b32_e32 v130, 16, v164
	v_and_b32_e32 v131, 0xffff0000, v164
	v_lshlrev_b32_e32 v132, 16, v165
	v_and_b32_e32 v133, 0xffff0000, v165
	v_pk_fma_f32 v[124:125], v[124:125], s[26:27], v[130:131]
	v_lshlrev_b32_e32 v134, 16, v166
	v_and_b32_e32 v135, 0xffff0000, v166
	v_pk_add_f32 v[124:125], v[76:77], v[124:125]
	v_pk_fma_f32 v[126:127], v[126:127], s[26:27], v[132:133]
	v_pk_fma_f32 v[130:131], v[124:125], v[124:125], 0 op_sel_hi:[1,1,0]
	v_pk_add_f32 v[126:127], v[78:79], v[126:127]
	v_pk_fma_f32 v[120:121], v[120:121], s[26:27], v[134:135]
	v_lshlrev_b32_e32 v136, 16, v167
	v_and_b32_e32 v137, 0xffff0000, v167
	v_pk_fma_f32 v[130:131], v[126:127], v[126:127], v[130:131]
	v_pk_add_f32 v[120:121], v[68:69], v[120:121]
	v_cvt_pk_bf16_f32 v124, v124, v125
	v_cvt_pk_bf16_f32 v125, v126, v127
	v_lshlrev_b32_e32 v132, 16, v162
	v_pk_fma_f32 v[130:131], v[120:121], v[120:121], v[130:131]
	v_cvt_pk_bf16_f32 v126, v120, v121
	v_pk_fma_f32 v[120:121], v[122:123], s[26:27], v[136:137]
	v_and_b32_e32 v133, 0xffff0000, v162
	v_pk_add_f32 v[120:121], v[70:71], v[120:121]
	v_lshlrev_b32_e32 v134, 16, v163
	v_pk_fma_f32 v[122:123], v[120:121], v[120:121], v[130:131]
	v_cvt_pk_bf16_f32 v127, v120, v121
	v_lshlrev_b32_e32 v120, 16, v160
	v_and_b32_e32 v121, 0xffff0000, v160
	v_lshlrev_b32_e32 v130, 16, v161
	v_and_b32_e32 v131, 0xffff0000, v161
	v_pk_fma_f32 v[116:117], v[116:117], s[26:27], v[120:121]
	v_pk_fma_f32 v[118:119], v[118:119], s[26:27], v[130:131]
	v_pk_add_f32 v[116:117], v[72:73], v[116:117]
	v_and_b32_e32 v135, 0xffff0000, v163
	v_pk_fma_f32 v[120:121], v[116:117], v[116:117], v[122:123]
	v_pk_add_f32 v[118:119], v[74:75], v[118:119]
	v_pk_fma_f32 v[112:113], v[112:113], s[26:27], v[132:133]
	v_pk_fma_f32 v[120:121], v[118:119], v[118:119], v[120:121]
	v_pk_add_f32 v[122:123], v[64:65], v[112:113]
	v_pk_fma_f32 v[114:115], v[114:115], s[26:27], v[134:135]
	v_pk_fma_f32 v[112:113], v[122:123], v[122:123], v[120:121]
	v_pk_add_f32 v[120:121], v[66:67], v[114:115]
	s_nop 0
	v_pk_fma_f32 v[112:113], v[120:121], v[120:121], v[112:113]
	s_nop 0
	v_add_f32_e32 v115, v112, v113
	v_mov_b32_e32 v129, v115
	s_nop 1
	v_permlane16_swap_b32_e32 v115, v129
	v_lshl_add_u64 v[112:113], s[82:83], 0, v[212:213]
	v_lshl_add_u64 v[130:131], v[196:197], 1, v[112:113]
	global_store_dwordx4 v[130:131], v[124:127], off
	v_cvt_pk_bf16_f32 v114, v116, v117
	s_waitcnt lgkmcnt(0)
	v_add_f32_e32 v112, v115, v129
	v_mov_b32_e32 v113, v112
	s_nop 1
	v_permlane32_swap_b32_e32 v112, v113
	v_cvt_pk_bf16_f32 v115, v118, v119
	v_cvt_pk_bf16_f32 v116, v122, v123
	v_cvt_pk_bf16_f32 v117, v120, v121
	global_store_dwordx4 v[130:131], v[114:117], off offset:256
	s_and_saveexec_b64 s[4:5], s[38:39]
	s_cbranch_execz .LBB0_208
	v_lshlrev_b64 v[114:115], 6, v[210:211]
	v_lshl_add_u64 v[114:115], s[48:49], 0, v[114:115]
	v_lshl_add_u64 v[114:115], s[42:43], 2, v[114:115]
	s_lshl_b32 s2, s62, 2
	v_lshl_add_u64 v[114:115], v[114:115], 0, s[2:3]
	s_waitcnt lgkmcnt(0)
	v_add_f32_e32 v112, v112, v113
	global_store_dword v[114:115], v112, off
; __device__ __forceinline__ unsigned cvt_pk_bf16(float lo, float hi) { unsigned r; asm volatile("v_cvt_pk_bf16_f32 %0, %1, %2" : "=v"(r) : "v"(lo), "v"(hi)); return r; }
;     __device__ __forceinline__ void operator()(const f32x4 (&acc)[2][2][4][2], const Unit& u, int wr, int wc, int fr, int fq, LAS unsigned char* lds, int tid, int ui, const Unit& nxt, bool has_next) const {
;     ...
;             for (int m = 0; m < 4; ++m) {
;                 const int row = row0 + ai * 128 + m * 16; const size_t off = (size_t)row * D + col0;
;                 typedef float f32x2 __attribute__((ext_vector_type(2)));
;                 f32x2 sq2 = (f32x2){0.f, 0.f};
; #pragma unroll
;                 for (int bj = 0; bj < 2; ++bj) {
;                     f32x2 v[4];
;                     const u32x4 w0 = xr[m][bj];
; #pragma unroll
;                     for (int i = 0; i < 4; ++i) v[i] = (f32x2){__uint_as_float(w0[i] << 16), __uint_as_float(w0[i] & 0xffff0000u)};
;                     const f32x2 al2 = (f32x2){alpha, alpha};
;                     unsigned wv[4];
; #pragma unroll
;                     for (int i = 0; i < 4; ++i) {
;                         const f32x4 av = acc[ai][bj][m][i >> 1], bb = bv[bj][i >> 1];
;                         const f32x2 a2 = (i & 1) ? (f32x2){av.z, av.w} : (f32x2){av.x, av.y}, b2 = (i & 1) ? (f32x2){bb.z, bb.w} : (f32x2){bb.x, bb.y};
;                         v[i] = __builtin_elementwise_fma(a2, al2, v[i]) + b2;
;                         sq2 = __builtin_elementwise_fma(v[i], v[i], sq2);
;                         wv[i] = cvt_pk_bf16(v[i].x, v[i].y);
;                     }
;                     u32x4 w; w.x = wv[0]; w.y = wv[1]; w.z = wv[2]; w.w = wv[3];
;                     *(u32x4*)(xb + off + bj * 128) = w;
;                 }
;                 float sq = sq2.x + sq2.y;
;                 sq += __shfl_xor(sq, 16); sq += __shfl_xor(sq, 32);
;                 if (fq == 0) ssp[(size_t)row * 16 + u.pn * 4 + wc] = sq;
;             }
.LBB0_208:
	s_or_b64 exec, exec, s[4:5]
	v_lshlrev_b32_e32 v112, 16, v156
	s_waitcnt lgkmcnt(0)
	v_and_b32_e32 v113, 0xffff0000, v156
	v_lshlrev_b32_e32 v114, 16, v157
	v_and_b32_e32 v115, 0xffff0000, v157
	v_pk_fma_f32 v[108:109], v[108:109], s[26:27], v[112:113]
	v_lshlrev_b32_e32 v116, 16, v158
	v_and_b32_e32 v117, 0xffff0000, v158
	v_pk_add_f32 v[108:109], v[76:77], v[108:109]
	v_pk_fma_f32 v[110:111], v[110:111], s[26:27], v[114:115]
	v_pk_fma_f32 v[112:113], v[108:109], v[108:109], 0 op_sel_hi:[1,1,0]
	v_pk_add_f32 v[110:111], v[78:79], v[110:111]
	v_pk_fma_f32 v[104:105], v[104:105], s[26:27], v[116:117]
	v_lshlrev_b32_e32 v118, 16, v159
	v_and_b32_e32 v119, 0xffff0000, v159
	v_pk_fma_f32 v[112:113], v[110:111], v[110:111], v[112:113]
	v_pk_add_f32 v[104:105], v[68:69], v[104:105]
	v_cvt_pk_bf16_f32 v108, v108, v109
	v_cvt_pk_bf16_f32 v109, v110, v111
	v_lshlrev_b32_e32 v114, 16, v154
	v_pk_fma_f32 v[112:113], v[104:105], v[104:105], v[112:113]
	v_cvt_pk_bf16_f32 v110, v104, v105
	v_pk_fma_f32 v[104:105], v[106:107], s[26:27], v[118:119]
	v_and_b32_e32 v115, 0xffff0000, v154
	v_pk_add_f32 v[104:105], v[70:71], v[104:105]
	v_lshlrev_b32_e32 v116, 16, v155
	v_pk_fma_f32 v[106:107], v[104:105], v[104:105], v[112:113]
	v_cvt_pk_bf16_f32 v111, v104, v105
	v_lshlrev_b32_e32 v104, 16, v152
	v_and_b32_e32 v105, 0xffff0000, v152
	v_lshlrev_b32_e32 v112, 16, v153
	v_and_b32_e32 v113, 0xffff0000, v153
	v_pk_fma_f32 v[100:101], v[100:101], s[26:27], v[104:105]
	v_pk_fma_f32 v[102:103], v[102:103], s[26:27], v[112:113]
	v_pk_add_f32 v[100:101], v[72:73], v[100:101]
	v_and_b32_e32 v117, 0xffff0000, v155
	v_pk_fma_f32 v[104:105], v[100:101], v[100:101], v[106:107]
	v_pk_add_f32 v[102:103], v[74:75], v[102:103]
	v_pk_fma_f32 v[96:97], v[96:97], s[26:27], v[114:115]
	v_pk_fma_f32 v[104:105], v[102:103], v[102:103], v[104:105]
	v_pk_add_f32 v[106:107], v[64:65], v[96:97]
	v_pk_fma_f32 v[98:99], v[98:99], s[26:27], v[116:117]
	v_pk_fma_f32 v[96:97], v[106:107], v[106:107], v[104:105]
	v_pk_add_f32 v[104:105], v[66:67], v[98:99]
	s_nop 0
	v_pk_fma_f32 v[96:97], v[104:105], v[104:105], v[96:97]
	s_nop 0
	v_add_f32_e32 v99, v96, v97
	v_mov_b32_e32 v114, v99
	s_nop 1
	v_permlane16_swap_b32_e32 v99, v114
	v_lshl_add_u64 v[96:97], s[82:83], 0, v[208:209]
	v_lshl_add_u64 v[112:113], v[196:197], 1, v[96:97]
	global_store_dwordx4 v[112:113], v[108:111], off
	v_cvt_pk_bf16_f32 v98, v100, v101
	s_waitcnt lgkmcnt(0)
	v_add_f32_e32 v96, v99, v114
	v_mov_b32_e32 v97, v96
	s_nop 1
	v_permlane32_swap_b32_e32 v96, v97
	v_cvt_pk_bf16_f32 v99, v102, v103
	v_cvt_pk_bf16_f32 v100, v106, v107
	v_cvt_pk_bf16_f32 v101, v104, v105
	global_store_dwordx4 v[112:113], v[98:101], off offset:256
	s_and_saveexec_b64 s[4:5], s[38:39]
	s_cbranch_execz .LBB0_210
	v_lshlrev_b64 v[98:99], 6, v[206:207]
	v_lshl_add_u64 v[98:99], s[48:49], 0, v[98:99]
	v_lshl_add_u64 v[98:99], s[42:43], 2, v[98:99]
	s_lshl_b32 s2, s62, 2
	v_lshl_add_u64 v[98:99], v[98:99], 0, s[2:3]
	s_waitcnt lgkmcnt(0)
	v_add_f32_e32 v96, v96, v97
	global_store_dword v[98:99], v96, off
.LBB0_210:
	s_or_b64 exec, exec, s[4:5]
	v_lshlrev_b32_e32 v96, 16, v148
	s_waitcnt lgkmcnt(0)
	v_and_b32_e32 v97, 0xffff0000, v148
	v_lshlrev_b32_e32 v98, 16, v149
	v_and_b32_e32 v99, 0xffff0000, v149
	v_pk_fma_f32 v[92:93], v[92:93], s[26:27], v[96:97]
	v_lshlrev_b32_e32 v100, 16, v150
	v_and_b32_e32 v101, 0xffff0000, v150
	v_pk_add_f32 v[92:93], v[76:77], v[92:93]
	v_pk_fma_f32 v[94:95], v[94:95], s[26:27], v[98:99]
	v_pk_fma_f32 v[96:97], v[92:93], v[92:93], 0 op_sel_hi:[1,1,0]
	v_pk_add_f32 v[94:95], v[78:79], v[94:95]
	v_pk_fma_f32 v[88:89], v[88:89], s[26:27], v[100:101]
	v_lshlrev_b32_e32 v102, 16, v151
	v_and_b32_e32 v103, 0xffff0000, v151
	v_pk_fma_f32 v[96:97], v[94:95], v[94:95], v[96:97]
	v_pk_add_f32 v[88:89], v[68:69], v[88:89]
	v_cvt_pk_bf16_f32 v92, v92, v93
	v_cvt_pk_bf16_f32 v93, v94, v95
	v_lshlrev_b32_e32 v98, 16, v146
	v_pk_fma_f32 v[96:97], v[88:89], v[88:89], v[96:97]
	v_cvt_pk_bf16_f32 v94, v88, v89
	v_pk_fma_f32 v[88:89], v[90:91], s[26:27], v[102:103]
	v_and_b32_e32 v99, 0xffff0000, v146
	v_pk_add_f32 v[88:89], v[70:71], v[88:89]
	v_lshlrev_b32_e32 v100, 16, v147
	v_pk_fma_f32 v[90:91], v[88:89], v[88:89], v[96:97]
	v_cvt_pk_bf16_f32 v95, v88, v89
	v_lshlrev_b32_e32 v88, 16, v144
	v_and_b32_e32 v89, 0xffff0000, v144
	v_lshlrev_b32_e32 v96, 16, v145
	v_and_b32_e32 v97, 0xffff0000, v145
	v_pk_fma_f32 v[84:85], v[84:85], s[26:27], v[88:89]
	v_pk_fma_f32 v[86:87], v[86:87], s[26:27], v[96:97]
	v_pk_add_f32 v[84:85], v[72:73], v[84:85]
	v_and_b32_e32 v101, 0xffff0000, v147
	v_pk_fma_f32 v[88:89], v[84:85], v[84:85], v[90:91]
	v_pk_add_f32 v[86:87], v[74:75], v[86:87]
	v_pk_fma_f32 v[80:81], v[80:81], s[26:27], v[98:99]
	v_pk_fma_f32 v[88:89], v[86:87], v[86:87], v[88:89]
	v_pk_add_f32 v[90:91], v[64:65], v[80:81]
	v_pk_fma_f32 v[82:83], v[82:83], s[26:27], v[100:101]
	v_pk_fma_f32 v[80:81], v[90:91], v[90:91], v[88:89]
	v_pk_add_f32 v[88:89], v[66:67], v[82:83]
	s_nop 0
	v_pk_fma_f32 v[80:81], v[88:89], v[88:89], v[80:81]
	s_nop 0
	v_add_f32_e32 v83, v80, v81
	v_mov_b32_e32 v98, v83
	s_nop 1
	v_permlane16_swap_b32_e32 v83, v98
	v_lshl_add_u64 v[80:81], s[82:83], 0, v[204:205]
	v_lshl_add_u64 v[96:97], v[196:197], 1, v[80:81]
	global_store_dwordx4 v[96:97], v[92:95], off
	v_cvt_pk_bf16_f32 v82, v84, v85
	s_waitcnt lgkmcnt(0)
	v_add_f32_e32 v80, v83, v98
	v_mov_b32_e32 v81, v80
	s_nop 1
	v_permlane32_swap_b32_e32 v80, v81
	v_cvt_pk_bf16_f32 v83, v86, v87
	v_cvt_pk_bf16_f32 v84, v90, v91
	v_cvt_pk_bf16_f32 v85, v88, v89
	global_store_dwordx4 v[96:97], v[82:85], off offset:256
	s_and_saveexec_b64 s[4:5], s[38:39]
	s_cbranch_execz .LBB0_212
	v_lshlrev_b64 v[82:83], 6, v[202:203]
	v_lshl_add_u64 v[82:83], s[48:49], 0, v[82:83]
	v_lshl_add_u64 v[82:83], s[42:43], 2, v[82:83]
	s_lshl_b32 s2, s62, 2
	v_lshl_add_u64 v[82:83], v[82:83], 0, s[2:3]
	s_waitcnt lgkmcnt(0)
	v_add_f32_e32 v80, v80, v81
	global_store_dword v[82:83], v80, off
; __device__ __forceinline__ unsigned cvt_pk_bf16(float lo, float hi) { unsigned r; asm volatile("v_cvt_pk_bf16_f32 %0, %1, %2" : "=v"(r) : "v"(lo), "v"(hi)); return r; }
;     __device__ __forceinline__ void operator()(const f32x4 (&acc)[2][2][4][2], const Unit& u, int wr, int wc, int fr, int fq, LAS unsigned char* lds, int tid, int ui, const Unit& nxt, bool has_next) const {
;     ...
;         for (int ai = 0; ai < 2; ++ai) {
;             u32x4 xr[4][2];
; #pragma unroll
;             for (int m = 0; m < 4; ++m)
; #pragma unroll
;                 for (int bj = 0; bj < 2; ++bj) xr[m][bj] = *(const u32x4*)(xb + (size_t)(row0 + ai * 128 + m * 16) * D + col0 + bj * 128);
; #pragma unroll
;             for (int m = 0; m < 4; ++m) {
;                 const int row = row0 + ai * 128 + m * 16; const size_t off = (size_t)row * D + col0;
;                 typedef float f32x2 __attribute__((ext_vector_type(2)));
;                 f32x2 sq2 = (f32x2){0.f, 0.f};
; #pragma unroll
;                 for (int bj = 0; bj < 2; ++bj) {
;                     f32x2 v[4];
;                     const u32x4 w0 = xr[m][bj];
; #pragma unroll
;                     for (int i = 0; i < 4; ++i) v[i] = (f32x2){__uint_as_float(w0[i] << 16), __uint_as_float(w0[i] & 0xffff0000u)};
;                     const f32x2 al2 = (f32x2){alpha, alpha};
;                     unsigned wv[4];
; #pragma unroll
;                     for (int i = 0; i < 4; ++i) {
;                         const f32x4 av = acc[ai][bj][m][i >> 1], bb = bv[bj][i >> 1];
;                         const f32x2 a2 = (i & 1) ? (f32x2){av.z, av.w} : (f32x2){av.x, av.y}, b2 = (i & 1) ? (f32x2){bb.z, bb.w} : (f32x2){bb.x, bb.y};
;                         v[i] = __builtin_elementwise_fma(a2, al2, v[i]) + b2;
;                         sq2 = __builtin_elementwise_fma(v[i], v[i], sq2);
;                         wv[i] = cvt_pk_bf16(v[i].x, v[i].y);
;                     }
;                     u32x4 w; w.x = wv[0]; w.y = wv[1]; w.z = wv[2]; w.w = wv[3];
;                     *(u32x4*)(xb + off + bj * 128) = w;
;                 }
;                 float sq = sq2.x + sq2.y;
;                 sq += __shfl_xor(sq, 16); sq += __shfl_xor(sq, 32);
;                 if (fq == 0) ssp[(size_t)row * 16 + u.pn * 4 + wc] = sq;
;             }
.LBB0_212:
	s_or_b64 exec, exec, s[4:5]
	v_add_u32_e32 v116, 0x80, v200
	v_ashrrev_i32_e32 v117, 31, v116
	v_lshlrev_b64 v[126:127], 11, v[116:117]
	s_waitcnt lgkmcnt(0)
	v_lshl_add_u64 v[80:81], v[198:199], 0, v[126:127]
	global_load_dwordx4 v[118:121], v[80:81], off
	global_load_dwordx4 v[122:125], v[80:81], off offset:256
	v_add_u32_e32 v112, 0x90, v200
	v_ashrrev_i32_e32 v113, 31, v112
	v_add_u32_e32 v108, 0xa0, v200
	v_lshlrev_b64 v[114:115], 11, v[112:113]
	v_ashrrev_i32_e32 v109, 31, v108
	v_add_u32_e32 v104, 0xb0, v200
	v_lshl_add_u64 v[80:81], v[198:199], 0, v[114:115]
	v_lshlrev_b64 v[110:111], 11, v[108:109]
	v_ashrrev_i32_e32 v105, 31, v104
	global_load_dwordx4 v[100:103], v[80:81], off
	global_load_dwordx4 v[96:99], v[80:81], off offset:256
	v_lshl_add_u64 v[80:81], v[198:199], 0, v[110:111]
	v_lshlrev_b64 v[106:107], 11, v[104:105]
	global_load_dwordx4 v[92:95], v[80:81], off
	global_load_dwordx4 v[88:91], v[80:81], off offset:256
	v_lshl_add_u64 v[80:81], v[198:199], 0, v[106:107]
	global_load_dwordx4 v[84:87], v[80:81], off
	s_nop 0
	global_load_dwordx4 v[80:83], v[80:81], off offset:256
	s_waitcnt vmcnt(7)
	v_lshlrev_b32_e32 v130, 16, v118
	v_and_b32_e32 v131, 0xffff0000, v118
	v_lshlrev_b32_e32 v118, 16, v119
	v_and_b32_e32 v119, 0xffff0000, v119
	v_pk_fma_f32 v[60:61], v[60:61], s[26:27], v[130:131]
	v_lshlrev_b32_e32 v132, 16, v120
	v_and_b32_e32 v133, 0xffff0000, v120
	v_pk_add_f32 v[60:61], v[76:77], v[60:61]
	v_pk_fma_f32 v[62:63], v[62:63], s[26:27], v[118:119]
	v_pk_fma_f32 v[130:131], v[60:61], v[60:61], 0 op_sel_hi:[1,1,0]
	v_pk_add_f32 v[62:63], v[78:79], v[62:63]
	v_pk_fma_f32 v[56:57], v[56:57], s[26:27], v[132:133]
	v_lshlrev_b32_e32 v120, 16, v121
	v_and_b32_e32 v121, 0xffff0000, v121
	v_pk_fma_f32 v[118:119], v[62:63], v[62:63], v[130:131]
	v_pk_add_f32 v[56:57], v[68:69], v[56:57]
	v_cvt_pk_bf16_f32 v60, v60, v61
	v_cvt_pk_bf16_f32 v61, v62, v63
	s_nop 0
	v_pk_fma_f32 v[118:119], v[56:57], v[56:57], v[118:119]
	v_cvt_pk_bf16_f32 v62, v56, v57
	v_pk_fma_f32 v[56:57], v[58:59], s[26:27], v[120:121]
	s_waitcnt vmcnt(6)
	v_lshlrev_b32_e32 v120, 16, v125
	v_pk_add_f32 v[56:57], v[70:71], v[56:57]
	v_and_b32_e32 v121, 0xffff0000, v125
	v_pk_fma_f32 v[58:59], v[56:57], v[56:57], v[118:119]
	v_cvt_pk_bf16_f32 v63, v56, v57
	v_lshl_add_u64 v[56:57], s[82:83], 0, v[126:127]
	v_lshl_add_u64 v[56:57], v[196:197], 1, v[56:57]
	global_store_dwordx4 v[56:57], v[60:63], off
	v_lshlrev_b32_e32 v118, 16, v124
	v_and_b32_e32 v119, 0xffff0000, v124
	v_lshlrev_b32_e32 v60, 16, v122
	v_and_b32_e32 v61, 0xffff0000, v122
	v_lshlrev_b32_e32 v62, 16, v123
	v_and_b32_e32 v63, 0xffff0000, v123
	v_pk_fma_f32 v[52:53], v[52:53], s[26:27], v[60:61]
	v_pk_fma_f32 v[54:55], v[54:55], s[26:27], v[62:63]
	v_pk_add_f32 v[52:53], v[72:73], v[52:53]
	v_pk_add_f32 v[54:55], v[74:75], v[54:55]
	v_pk_fma_f32 v[58:59], v[52:53], v[52:53], v[58:59]
	v_pk_fma_f32 v[48:49], v[48:49], s[26:27], v[118:119]
	v_pk_fma_f32 v[58:59], v[54:55], v[54:55], v[58:59]
	v_pk_add_f32 v[48:49], v[64:65], v[48:49]
	v_cvt_pk_bf16_f32 v52, v52, v53
	v_cvt_pk_bf16_f32 v53, v54, v55
	s_nop 0
	v_pk_fma_f32 v[58:59], v[48:49], v[48:49], v[58:59]
	v_cvt_pk_bf16_f32 v54, v48, v49
	v_pk_fma_f32 v[48:49], v[50:51], s[26:27], v[120:121]
	s_nop 0
	v_pk_add_f32 v[48:49], v[66:67], v[48:49]
	s_nop 0
	v_pk_fma_f32 v[50:51], v[48:49], v[48:49], v[58:59]
	v_cvt_pk_bf16_f32 v55, v48, v49
	global_store_dwordx4 v[56:57], v[52:55], off offset:256
	v_add_f32_e32 v48, v50, v51
	v_mov_b32_e32 v49, v48
	s_nop 1
	v_permlane16_swap_b32_e32 v48, v49
	s_waitcnt lgkmcnt(0)
	v_add_f32_e32 v48, v48, v49
	v_mov_b32_e32 v49, v48
	s_nop 1
	v_permlane32_swap_b32_e32 v48, v49
	s_and_saveexec_b64 s[4:5], s[38:39]
	s_cbranch_execz .LBB0_214
	v_lshlrev_b64 v[50:51], 6, v[116:117]
	v_lshl_add_u64 v[50:51], s[48:49], 0, v[50:51]
	v_lshl_add_u64 v[50:51], s[42:43], 2, v[50:51]
	s_lshl_b32 s2, s62, 2
	v_lshl_add_u64 v[50:51], v[50:51], 0, s[2:3]
	s_waitcnt lgkmcnt(0)
	v_add_f32_e32 v48, v48, v49
	global_store_dword v[50:51], v48, off
.LBB0_214:
	s_or_b64 exec, exec, s[4:5]
	s_waitcnt vmcnt(7)
	v_lshlrev_b32_e32 v48, 16, v100
	s_waitcnt lgkmcnt(0)
	v_and_b32_e32 v49, 0xffff0000, v100
	v_lshlrev_b32_e32 v50, 16, v101
	v_and_b32_e32 v51, 0xffff0000, v101
	v_pk_fma_f32 v[44:45], v[44:45], s[26:27], v[48:49]
	v_lshlrev_b32_e32 v52, 16, v102
	v_and_b32_e32 v53, 0xffff0000, v102
	v_pk_add_f32 v[44:45], v[76:77], v[44:45]
	v_pk_fma_f32 v[46:47], v[46:47], s[26:27], v[50:51]
	v_pk_fma_f32 v[48:49], v[44:45], v[44:45], 0 op_sel_hi:[1,1,0]
	v_pk_add_f32 v[46:47], v[78:79], v[46:47]
	v_pk_fma_f32 v[40:41], v[40:41], s[26:27], v[52:53]
	v_lshlrev_b32_e32 v54, 16, v103
	v_and_b32_e32 v55, 0xffff0000, v103
	v_pk_fma_f32 v[48:49], v[46:47], v[46:47], v[48:49]
	v_pk_add_f32 v[40:41], v[68:69], v[40:41]
	v_cvt_pk_bf16_f32 v44, v44, v45
	v_cvt_pk_bf16_f32 v45, v46, v47
	s_waitcnt vmcnt(6)
	v_lshlrev_b32_e32 v50, 16, v98
	v_pk_fma_f32 v[48:49], v[40:41], v[40:41], v[48:49]
	v_cvt_pk_bf16_f32 v46, v40, v41
	v_pk_fma_f32 v[40:41], v[42:43], s[26:27], v[54:55]
	v_and_b32_e32 v51, 0xffff0000, v98
	v_pk_add_f32 v[40:41], v[70:71], v[40:41]
	v_lshlrev_b32_e32 v52, 16, v99
	v_pk_fma_f32 v[42:43], v[40:41], v[40:41], v[48:49]
	v_cvt_pk_bf16_f32 v47, v40, v41
	v_lshlrev_b32_e32 v40, 16, v96
	v_and_b32_e32 v41, 0xffff0000, v96
	v_lshlrev_b32_e32 v48, 16, v97
	v_and_b32_e32 v49, 0xffff0000, v97
	v_pk_fma_f32 v[36:37], v[36:37], s[26:27], v[40:41]
	v_pk_fma_f32 v[38:39], v[38:39], s[26:27], v[48:49]
	v_pk_add_f32 v[36:37], v[72:73], v[36:37]
	v_and_b32_e32 v53, 0xffff0000, v99
	v_pk_fma_f32 v[40:41], v[36:37], v[36:37], v[42:43]
	v_pk_add_f32 v[38:39], v[74:75], v[38:39]
	v_pk_fma_f32 v[32:33], v[32:33], s[26:27], v[50:51]
	v_pk_fma_f32 v[40:41], v[38:39], v[38:39], v[40:41]
	v_pk_add_f32 v[42:43], v[64:65], v[32:33]
	v_pk_fma_f32 v[34:35], v[34:35], s[26:27], v[52:53]
	v_pk_fma_f32 v[32:33], v[42:43], v[42:43], v[40:41]
	v_pk_add_f32 v[40:41], v[66:67], v[34:35]
	s_nop 0
	v_pk_fma_f32 v[32:33], v[40:41], v[40:41], v[32:33]
	s_nop 0
	v_add_f32_e32 v35, v32, v33
	v_mov_b32_e32 v50, v35
	s_nop 1
	v_permlane16_swap_b32_e32 v35, v50
	v_lshl_add_u64 v[32:33], s[82:83], 0, v[114:115]
	v_lshl_add_u64 v[48:49], v[196:197], 1, v[32:33]
	global_store_dwordx4 v[48:49], v[44:47], off
	v_cvt_pk_bf16_f32 v34, v36, v37
	s_waitcnt lgkmcnt(0)
	v_add_f32_e32 v32, v35, v50
	v_mov_b32_e32 v33, v32
	s_nop 1
	v_permlane32_swap_b32_e32 v32, v33
	v_cvt_pk_bf16_f32 v35, v38, v39
	v_cvt_pk_bf16_f32 v36, v42, v43
	v_cvt_pk_bf16_f32 v37, v40, v41
	global_store_dwordx4 v[48:49], v[34:37], off offset:256
	s_and_saveexec_b64 s[4:5], s[38:39]
	s_cbranch_execz .LBB0_216
	v_lshlrev_b64 v[34:35], 6, v[112:113]
	v_lshl_add_u64 v[34:35], s[48:49], 0, v[34:35]
	v_lshl_add_u64 v[34:35], s[42:43], 2, v[34:35]
	s_lshl_b32 s2, s62, 2
	v_lshl_add_u64 v[34:35], v[34:35], 0, s[2:3]
	s_waitcnt lgkmcnt(0)
	v_add_f32_e32 v32, v32, v33
	global_store_dword v[34:35], v32, off
; __device__ __forceinline__ unsigned cvt_pk_bf16(float lo, float hi) { unsigned r; asm volatile("v_cvt_pk_bf16_f32 %0, %1, %2" : "=v"(r) : "v"(lo), "v"(hi)); return r; }
;     __device__ __forceinline__ void operator()(const f32x4 (&acc)[2][2][4][2], const Unit& u, int wr, int wc, int fr, int fq, LAS unsigned char* lds, int tid, int ui, const Unit& nxt, bool has_next) const {
;     ...
;             for (int m = 0; m < 4; ++m) {
;                 const int row = row0 + ai * 128 + m * 16; const size_t off = (size_t)row * D + col0;
;                 typedef float f32x2 __attribute__((ext_vector_type(2)));
;                 f32x2 sq2 = (f32x2){0.f, 0.f};
; #pragma unroll
;                 for (int bj = 0; bj < 2; ++bj) {
;                     f32x2 v[4];
;                     const u32x4 w0 = xr[m][bj];
; #pragma unroll
;                     for (int i = 0; i < 4; ++i) v[i] = (f32x2){__uint_as_float(w0[i] << 16), __uint_as_float(w0[i] & 0xffff0000u)};
;                     const f32x2 al2 = (f32x2){alpha, alpha};
;                     unsigned wv[4];
; #pragma unroll
;                     for (int i = 0; i < 4; ++i) {
;                         const f32x4 av = acc[ai][bj][m][i >> 1], bb = bv[bj][i >> 1];
;                         const f32x2 a2 = (i & 1) ? (f32x2){av.z, av.w} : (f32x2){av.x, av.y}, b2 = (i & 1) ? (f32x2){bb.z, bb.w} : (f32x2){bb.x, bb.y};
;                         v[i] = __builtin_elementwise_fma(a2, al2, v[i]) + b2;
;                         sq2 = __builtin_elementwise_fma(v[i], v[i], sq2);
;                         wv[i] = cvt_pk_bf16(v[i].x, v[i].y);
;                     }
;                     u32x4 w; w.x = wv[0]; w.y = wv[1]; w.z = wv[2]; w.w = wv[3];
;                     *(u32x4*)(xb + off + bj * 128) = w;
;                 }
;                 float sq = sq2.x + sq2.y;
;                 sq += __shfl_xor(sq, 16); sq += __shfl_xor(sq, 32);
;                 if (fq == 0) ssp[(size_t)row * 16 + u.pn * 4 + wc] = sq;
;             }
.LBB0_216:
	s_or_b64 exec, exec, s[4:5]
	s_waitcnt vmcnt(7)
	v_lshlrev_b32_e32 v32, 16, v92
	s_waitcnt lgkmcnt(0)
	v_and_b32_e32 v33, 0xffff0000, v92
	v_lshlrev_b32_e32 v34, 16, v93
	v_and_b32_e32 v35, 0xffff0000, v93
	v_pk_fma_f32 v[28:29], v[28:29], s[26:27], v[32:33]
	v_lshlrev_b32_e32 v36, 16, v94
	v_and_b32_e32 v37, 0xffff0000, v94
	v_pk_add_f32 v[28:29], v[76:77], v[28:29]
	v_pk_fma_f32 v[30:31], v[30:31], s[26:27], v[34:35]
	v_pk_fma_f32 v[32:33], v[28:29], v[28:29], 0 op_sel_hi:[1,1,0]
	v_pk_add_f32 v[30:31], v[78:79], v[30:31]
	v_pk_fma_f32 v[24:25], v[24:25], s[26:27], v[36:37]
	v_lshlrev_b32_e32 v38, 16, v95
	v_and_b32_e32 v39, 0xffff0000, v95
	v_pk_fma_f32 v[32:33], v[30:31], v[30:31], v[32:33]
	v_pk_add_f32 v[24:25], v[68:69], v[24:25]
	v_cvt_pk_bf16_f32 v28, v28, v29
	v_cvt_pk_bf16_f32 v29, v30, v31
	s_waitcnt vmcnt(6)
	v_lshlrev_b32_e32 v34, 16, v90
	v_pk_fma_f32 v[32:33], v[24:25], v[24:25], v[32:33]
	v_cvt_pk_bf16_f32 v30, v24, v25
	v_pk_fma_f32 v[24:25], v[26:27], s[26:27], v[38:39]
	v_and_b32_e32 v35, 0xffff0000, v90
	v_pk_add_f32 v[24:25], v[70:71], v[24:25]
	v_lshlrev_b32_e32 v36, 16, v91
	v_pk_fma_f32 v[26:27], v[24:25], v[24:25], v[32:33]
	v_cvt_pk_bf16_f32 v31, v24, v25
	v_lshlrev_b32_e32 v24, 16, v88
	v_and_b32_e32 v25, 0xffff0000, v88
	v_lshlrev_b32_e32 v32, 16, v89
	v_and_b32_e32 v33, 0xffff0000, v89
	v_pk_fma_f32 v[20:21], v[20:21], s[26:27], v[24:25]
	v_pk_fma_f32 v[22:23], v[22:23], s[26:27], v[32:33]
	v_pk_add_f32 v[20:21], v[72:73], v[20:21]
	v_and_b32_e32 v37, 0xffff0000, v91
	v_pk_fma_f32 v[24:25], v[20:21], v[20:21], v[26:27]
	v_pk_add_f32 v[22:23], v[74:75], v[22:23]
	v_pk_fma_f32 v[16:17], v[16:17], s[26:27], v[34:35]
	v_pk_fma_f32 v[24:25], v[22:23], v[22:23], v[24:25]
	v_pk_add_f32 v[26:27], v[64:65], v[16:17]
	v_pk_fma_f32 v[18:19], v[18:19], s[26:27], v[36:37]
	v_pk_fma_f32 v[16:17], v[26:27], v[26:27], v[24:25]
	v_pk_add_f32 v[24:25], v[66:67], v[18:19]
	s_nop 0
	v_pk_fma_f32 v[16:17], v[24:25], v[24:25], v[16:17]
	s_nop 0
	v_add_f32_e32 v19, v16, v17
	v_mov_b32_e32 v34, v19
	s_nop 1
	v_permlane16_swap_b32_e32 v19, v34
	v_lshl_add_u64 v[16:17], s[82:83], 0, v[110:111]
	v_lshl_add_u64 v[32:33], v[196:197], 1, v[16:17]
	global_store_dwordx4 v[32:33], v[28:31], off
	v_cvt_pk_bf16_f32 v18, v20, v21
	s_waitcnt lgkmcnt(0)
	v_add_f32_e32 v16, v19, v34
	v_mov_b32_e32 v17, v16
	s_nop 1
	v_permlane32_swap_b32_e32 v16, v17
	v_cvt_pk_bf16_f32 v19, v22, v23
	v_cvt_pk_bf16_f32 v20, v26, v27
	v_cvt_pk_bf16_f32 v21, v24, v25
	global_store_dwordx4 v[32:33], v[18:21], off offset:256
	s_and_saveexec_b64 s[4:5], s[38:39]
	s_cbranch_execz .LBB0_218
	v_lshlrev_b64 v[18:19], 6, v[108:109]
	v_lshl_add_u64 v[18:19], s[48:49], 0, v[18:19]
	v_lshl_add_u64 v[18:19], s[42:43], 2, v[18:19]
	s_lshl_b32 s2, s62, 2
	v_lshl_add_u64 v[18:19], v[18:19], 0, s[2:3]
	s_waitcnt lgkmcnt(0)
	v_add_f32_e32 v16, v16, v17
	global_store_dword v[18:19], v16, off
.LBB0_218:
	s_or_b64 exec, exec, s[4:5]
	s_waitcnt vmcnt(7)
	v_lshlrev_b32_e32 v16, 16, v84
	s_waitcnt lgkmcnt(0)
	v_and_b32_e32 v17, 0xffff0000, v84
	v_lshlrev_b32_e32 v18, 16, v85
	v_and_b32_e32 v19, 0xffff0000, v85
	v_pk_fma_f32 v[12:13], v[12:13], s[26:27], v[16:17]
	v_lshlrev_b32_e32 v20, 16, v86
	v_and_b32_e32 v21, 0xffff0000, v86
	v_pk_add_f32 v[12:13], v[76:77], v[12:13]
	v_pk_fma_f32 v[14:15], v[14:15], s[26:27], v[18:19]
	v_pk_fma_f32 v[16:17], v[12:13], v[12:13], 0 op_sel_hi:[1,1,0]
	v_pk_add_f32 v[14:15], v[78:79], v[14:15]
	v_pk_fma_f32 v[8:9], v[8:9], s[26:27], v[20:21]
	v_lshlrev_b32_e32 v22, 16, v87
	v_and_b32_e32 v23, 0xffff0000, v87
	v_pk_fma_f32 v[16:17], v[14:15], v[14:15], v[16:17]
	v_pk_add_f32 v[8:9], v[68:69], v[8:9]
	v_cvt_pk_bf16_f32 v12, v12, v13
	v_cvt_pk_bf16_f32 v13, v14, v15
	s_waitcnt vmcnt(6)
	v_lshlrev_b32_e32 v18, 16, v82
	v_pk_fma_f32 v[16:17], v[8:9], v[8:9], v[16:17]
	v_cvt_pk_bf16_f32 v14, v8, v9
	v_pk_fma_f32 v[8:9], v[10:11], s[26:27], v[22:23]
	v_and_b32_e32 v19, 0xffff0000, v82
	v_pk_add_f32 v[8:9], v[70:71], v[8:9]
	v_lshlrev_b32_e32 v20, 16, v83
	v_pk_fma_f32 v[10:11], v[8:9], v[8:9], v[16:17]
	v_cvt_pk_bf16_f32 v15, v8, v9
	v_lshlrev_b32_e32 v8, 16, v80
	v_and_b32_e32 v9, 0xffff0000, v80
	v_lshlrev_b32_e32 v16, 16, v81
	v_and_b32_e32 v17, 0xffff0000, v81
	v_pk_fma_f32 v[4:5], v[4:5], s[26:27], v[8:9]
	v_pk_fma_f32 v[6:7], v[6:7], s[26:27], v[16:17]
	v_pk_add_f32 v[4:5], v[72:73], v[4:5]
	v_and_b32_e32 v21, 0xffff0000, v83
	v_pk_fma_f32 v[8:9], v[4:5], v[4:5], v[10:11]
	v_pk_add_f32 v[6:7], v[74:75], v[6:7]
	v_pk_fma_f32 v[0:1], v[0:1], s[26:27], v[18:19]
	v_pk_fma_f32 v[8:9], v[6:7], v[6:7], v[8:9]
	v_pk_add_f32 v[10:11], v[64:65], v[0:1]
	v_pk_fma_f32 v[2:3], v[2:3], s[26:27], v[20:21]
	v_pk_fma_f32 v[0:1], v[10:11], v[10:11], v[8:9]
	v_pk_add_f32 v[8:9], v[66:67], v[2:3]
	s_nop 0
	v_pk_fma_f32 v[0:1], v[8:9], v[8:9], v[0:1]
	s_nop 0
	v_add_f32_e32 v3, v0, v1
	v_mov_b32_e32 v18, v3
	s_nop 1
	v_permlane16_swap_b32_e32 v3, v18
	v_lshl_add_u64 v[0:1], s[82:83], 0, v[106:107]
	v_lshl_add_u64 v[16:17], v[196:197], 1, v[0:1]
	global_store_dwordx4 v[16:17], v[12:15], off
	v_cvt_pk_bf16_f32 v2, v4, v5
	s_waitcnt lgkmcnt(0)
	v_add_f32_e32 v0, v3, v18
	v_mov_b32_e32 v1, v0
	s_nop 1
	v_permlane32_swap_b32_e32 v0, v1
	v_cvt_pk_bf16_f32 v3, v6, v7
	v_cvt_pk_bf16_f32 v4, v10, v11
	v_cvt_pk_bf16_f32 v5, v8, v9
	global_store_dwordx4 v[16:17], v[2:5], off offset:256
	s_and_saveexec_b64 s[4:5], s[38:39]
	s_cbranch_execz .LBB0_220
	v_lshlrev_b64 v[2:3], 6, v[104:105]
	v_lshl_add_u64 v[2:3], s[48:49], 0, v[2:3]
	v_lshl_add_u64 v[2:3], s[42:43], 2, v[2:3]
	s_lshl_b32 s2, s62, 2
	v_lshl_add_u64 v[2:3], v[2:3], 0, s[2:3]
	s_waitcnt lgkmcnt(0)
	v_add_f32_e32 v0, v0, v1
	global_store_dword v[2:3], v0, off
